# s_setprio 1 around the GEMM K loops so the co-resident block's epilogue VALU yields to MFMA issue
# speedup vs baseline: 1.0095x; 1.0095x over previous
; #define LAS __attribute__((address_space(3)))
;   int tid = tid_in; asm volatile("" : "+v"(tid));
;   const int lane = tid & 63, wid = __builtin_amdgcn_readfirstlane(tid >> 6), wr = wid >> 1, wc = wid & 1;
;   const int m0 = mt * 128, n0 = nt * 256;
;   const int r = lane & 31, h = lane >> 5, key = (r >> 2) & 3;
;   constexpr int STG = 24576;
;   const int rowl = lane >> 2, cch = (lane & 3) ^ ((lane >> 4) & 3);
;   const unsigned voffA = (unsigned)(rowl * lda * 2 + cch * 16), voffB = (unsigned)(rowl * K * 2 + cch * 16);
;   const char* Abase = (const char*)(A + (size_t)m0 * lda) + (size_t)(wid * 2) * 32 * lda;
;   const char* Bbase = (const char*)(Bt + (size_t)n0 * K) + (size_t)(wid * 4) * 32 * K;
;   const size_t ablk = (size_t)32 * lda, bblk = (size_t)32 * K;
;   LAS char* lds = (LAS char*)smem;
;   LAS char* ldsA = lds + (wid * 2) * 1024;
;   LAS char* ldsB = lds + 8192 + (wid * 4) * 1024;
;     ...
;   const int x0 = ((0 + h) ^ key) * 16, x1 = ((2 + h) ^ key) * 16;
;   const int a_rd = (wr * 64 + r) * 64, b_rd = 8192 + (wc * 128 + r) * 64;
;   f32x16 acc[2][4];
; #pragma unroll
;   for (int i = 0; i < 2; ++i)
; #pragma unroll
;     for (int j = 0; j < 4; ++j)
; #pragma unroll
;       for (int e = 0; e < 16; ++e) acc[i][j][e] = 0.f;
;   const int nk = K >> 5;
;   DMA_STEP_(0, 0);
;   DMA_STEP_(1, STG);
;   asm volatile("s_waitcnt vmcnt(6)" ::: "memory");
;   __builtin_amdgcn_s_barrier();
;   asm volatile("" ::: "memory");
;   int s0 = 0, s2 = 2 * STG;
;   for (int kt = 0; kt < nk; ++kt) {
;     const int kn = (kt + 2 < nk) ? (kt + 2) : (nk - 1);
;     const LAS char* cur = lds + s0;
;     bf16x8 af[2][2], bfr[2][4];
; #pragma unroll
;     for (int kk = 0; kk < 2; ++kk) {
;       const int xo = kk ? x1 : x0;
;       af[kk][0] = *(const LAS bf16x8*)(cur + a_rd + xo);
;       bfr[kk][0] = *(const LAS bf16x8*)(cur + b_rd + xo);
;       bfr[kk][1] = *(const LAS bf16x8*)(cur + b_rd + 2048 + xo);
;       af[kk][1] = *(const LAS bf16x8*)(cur + a_rd + 2048 + xo);
;       bfr[kk][2] = *(const LAS bf16x8*)(cur + b_rd + 4096 + xo);
;       bfr[kk][3] = *(const LAS bf16x8*)(cur + b_rd + 6144 + xo);
;     }
.LBB0_20:
	s_ashr_i32 s10, s23, 31
	s_lshr_b32 s10, s10, 27
	s_add_i32 s10, s23, s10
	s_ashr_i32 s10, s10, 5
	v_readlane_b32 s11, v252, 18
	v_mov_b32_e32 v189, v188
	s_lshl_b32 s11, s10, s11
	v_readlane_b32 s12, v252, 41
	s_add_i32 s11, s11, s12
	v_readfirstlane_b32 s44, v189
	s_ashr_i32 s46, s44, 6
	s_lshl_b32 s12, s23, 7
	s_lshl_b32 s11, s11, 10
	s_and_b32 s12, s12, 0x380
	s_lshl_b32 s28, s46, 1
	s_or_b32 s12, s11, s12
	s_lshl_b32 s10, s10, 10
	s_lshl_b32 s11, s23, 5
	s_ashr_i32 s29, s28, 31
	s_sub_i32 s10, s11, s10
	s_lshl_b64 s[40:41], s[28:29], 15
	s_lshl_b32 s28, s46, 2
	s_ashr_i32 s11, s44, 1
	s_and_b32 s14, s10, 0xffffff00
	v_and_b32_e32 v0, 31, v189
	s_ashr_i32 s29, s28, 31
	s_lshl_b32 s10, s46, 12
	s_andn2_b32 s11, s11, 63
	v_lshlrev_b32_e32 v2, 4, v189
	s_ashr_i32 s13, s12, 31
	s_lshl_b64 s[42:43], s[28:29], 10
	s_add_i32 s29, s10, 16
	v_or_b32_e32 v197, s11, v0
	s_lshl_b32 s11, s46, 7
	v_bitop3_b32 v2, v2, 48, v189 bitop3:0x48
	v_lshlrev_b32_e32 v3, 9, v189
	s_ashr_i32 s15, s14, 31
	s_add_i32 s10, s29, 0x2000
	s_and_b32 s28, s11, 0x80
	s_movk_i32 s11, 0x7800
	s_lshl_b64 s[44:45], s[12:13], 11
	v_or_b32_e32 v4, s28, v0
	v_and_or_b32 v0, v3, s11, v2
	v_lshlrev_b32_e32 v10, 4, v189
	v_and_b32_e32 v10, 0x3c0, v10
	v_or_b32_e32 v10, v10, v2
	v_mov_b32_e32 v11, 0
	s_add_u32 s11, s21, s44
	s_addc_u32 s13, s22, s45
	s_add_u32 s40, s11, s40
	s_addc_u32 s41, s13, s41
	s_lshl_b64 s[44:45], s[14:15], 6
	s_add_u32 s11, s17, s44
	s_addc_u32 s13, s18, s45
	s_add_u32 s42, s11, s42
	s_addc_u32 s43, s13, s43
	s_lshl_b32 s11, s46, 11
	s_sub_i32 s13, s29, s11
	v_lshl_add_u64 v[192:193], s[40:41], 0, v[0:1]
	s_mov_b32 m0, s13
	v_lshl_add_u64 v[2:3], v[192:193], 0, s[72:73]
	global_load_lds_dwordx4 v0, s[40:41]
	s_add_i32 m0, s13, 0x400
	v_lshl_add_u64 v[194:195], s[42:43], 0, v[10:11]
	global_load_lds_dwordx4 v[2:3], off
	s_mov_b32 m0, s10
	s_nop 0
	global_load_lds_dwordx4 v[194:195], off
	global_load_lds_dwordx4 v[194:195], off offset:1024
	global_load_lds_dwordx4 v[194:195], off offset:2048
	global_load_lds_dwordx4 v[194:195], off offset:3072
	s_mov_b64 s[10:11], 0x10000
	s_mov_b64 s[10:11], 0x18000
	s_mov_b64 s[10:11], 0x8040
	s_add_i32 m0, s13, 0x6000
	v_lshl_add_u64 v[2:3], v[192:193], 0, 64
	global_load_lds_dwordx4 v[2:3], off
	v_lshl_add_u64 v[2:3], v[192:193], 0, s[10:11]
	s_add_i32 m0, s13, 0x6400
	v_bfe_u32 v196, v189, 5, 1
	global_load_lds_dwordx4 v[2:3], off
	s_add_i32 m0, s29, 0x8000
	s_mov_b32 s100, 0x10000
	v_lshl_add_u64 v[2:3], v[194:195], 0, s[100:101]
	global_load_lds_dwordx4 v[2:3], off
	global_load_lds_dwordx4 v[2:3], off offset:1024
	global_load_lds_dwordx4 v[2:3], off offset:2048
	global_load_lds_dwordx4 v[2:3], off offset:3072
	s_mov_b64 s[10:11], 0x10040
	s_mov_b64 s[10:11], 0x18040
	v_lshlrev_b32_e32 v218, 6, v4
	v_bfe_u32 v4, v189, 2, 2
	v_lshrrev_b32_e32 v5, 5, v189
	s_lshl_b32 s100, s100, 1
	v_lshl_add_u64 v[194:195], v[194:195], 0, s[100:101]
	s_waitcnt vmcnt(6)
	s_barrier
	v_bitop3_b32 v2, v196, v4, 2 bitop3:0x36
	v_bitop3_b32 v0, v5, v4, 1 bitop3:0x6c
	v_lshlrev_b32_e32 v220, 4, v2
	v_mov_b32_e32 v2, 0
	v_lshlrev_b32_e32 v219, 6, v197
	v_lshlrev_b32_e32 v0, 4, v0
	s_mov_b32 s41, 0xc000
	s_mov_b32 s40, 0
	s_mov_b32 s42, 0
	v_mov_b32_e32 v3, v2
	v_mov_b32_e32 v4, v2
	v_mov_b32_e32 v5, v2
	v_mov_b32_e32 v6, v2
	v_mov_b32_e32 v7, v2
	v_mov_b32_e32 v8, v2
	v_mov_b32_e32 v9, v2
	v_mov_b32_e32 v10, v2
	v_mov_b32_e32 v11, v2
	v_mov_b32_e32 v12, v2
	v_mov_b32_e32 v13, v2
	v_mov_b32_e32 v14, v2
	v_mov_b32_e32 v15, v2
	v_mov_b32_e32 v16, v2
	v_mov_b32_e32 v17, v2
	v_mov_b32_e32 v18, v2
	v_mov_b32_e32 v19, v2
	v_mov_b32_e32 v20, v2
	v_mov_b32_e32 v21, v2
	v_mov_b32_e32 v22, v2
	v_mov_b32_e32 v23, v2
	v_mov_b32_e32 v24, v2
	v_mov_b32_e32 v25, v2
	v_mov_b32_e32 v26, v2
	v_mov_b32_e32 v27, v2
	v_mov_b32_e32 v28, v2
	v_mov_b32_e32 v29, v2
	v_mov_b32_e32 v30, v2
	v_mov_b32_e32 v31, v2
	v_mov_b32_e32 v32, v2
	v_mov_b32_e32 v33, v2
	v_mov_b32_e32 v50, v2
	v_mov_b32_e32 v51, v2
	v_mov_b32_e32 v52, v2
	v_mov_b32_e32 v53, v2
	v_mov_b32_e32 v54, v2
	v_mov_b32_e32 v55, v2
	v_mov_b32_e32 v56, v2
	v_mov_b32_e32 v57, v2
	v_mov_b32_e32 v58, v2
	v_mov_b32_e32 v59, v2
	v_mov_b32_e32 v60, v2
	v_mov_b32_e32 v61, v2
	v_mov_b32_e32 v62, v2
	v_mov_b32_e32 v63, v2
	v_mov_b32_e32 v64, v2
	v_mov_b32_e32 v65, v2
	v_mov_b32_e32 v82, v2
	v_mov_b32_e32 v83, v2
	v_mov_b32_e32 v84, v2
	v_mov_b32_e32 v85, v2
	v_mov_b32_e32 v86, v2
	v_mov_b32_e32 v87, v2
	v_mov_b32_e32 v88, v2
	v_mov_b32_e32 v89, v2
	s_waitcnt vmcnt(0)
	v_mov_b32_e32 v90, v2
	v_mov_b32_e32 v91, v2
	v_mov_b32_e32 v92, v2
	v_mov_b32_e32 v93, v2
	v_mov_b32_e32 v94, v2
	v_mov_b32_e32 v95, v2
	v_mov_b32_e32 v96, v2
	v_mov_b32_e32 v97, v2
	v_mov_b32_e32 v34, v2
	v_mov_b32_e32 v35, v2
	v_mov_b32_e32 v36, v2
	v_mov_b32_e32 v37, v2
	v_mov_b32_e32 v38, v2
	v_mov_b32_e32 v39, v2
	v_mov_b32_e32 v40, v2
	v_mov_b32_e32 v41, v2
	v_mov_b32_e32 v42, v2
	v_mov_b32_e32 v43, v2
	v_mov_b32_e32 v44, v2
	v_mov_b32_e32 v45, v2
	v_mov_b32_e32 v46, v2
	v_mov_b32_e32 v47, v2
	v_mov_b32_e32 v48, v2
	v_mov_b32_e32 v49, v2
	v_mov_b32_e32 v66, v2
	v_mov_b32_e32 v67, v2
	v_mov_b32_e32 v68, v2
	v_mov_b32_e32 v69, v2
	v_mov_b32_e32 v70, v2
	v_mov_b32_e32 v71, v2
	v_mov_b32_e32 v72, v2
	v_mov_b32_e32 v73, v2
	v_mov_b32_e32 v74, v2
	v_mov_b32_e32 v75, v2
	v_mov_b32_e32 v76, v2
	v_mov_b32_e32 v77, v2
	v_mov_b32_e32 v78, v2
	v_mov_b32_e32 v79, v2
	v_mov_b32_e32 v80, v2
	v_mov_b32_e32 v81, v2
	v_mov_b32_e32 v98, v2
	v_mov_b32_e32 v99, v2
	v_mov_b32_e32 v100, v2
	v_mov_b32_e32 v101, v2
	v_mov_b32_e32 v102, v2
	v_mov_b32_e32 v103, v2
	v_mov_b32_e32 v104, v2
	v_mov_b32_e32 v105, v2
	v_mov_b32_e32 v106, v2
	v_mov_b32_e32 v107, v2
	v_mov_b32_e32 v108, v2
	v_mov_b32_e32 v109, v2
	v_mov_b32_e32 v110, v2
	v_mov_b32_e32 v111, v2
	v_mov_b32_e32 v112, v2
	v_mov_b32_e32 v113, v2
	v_mov_b32_e32 v114, v2
	v_mov_b32_e32 v115, v2
	v_mov_b32_e32 v116, v2
	v_mov_b32_e32 v117, v2
	v_mov_b32_e32 v118, v2
	v_mov_b32_e32 v119, v2
	v_mov_b32_e32 v120, v2
	v_mov_b32_e32 v121, v2
	v_mov_b32_e32 v122, v2
	v_mov_b32_e32 v123, v2
	v_mov_b32_e32 v124, v2
	v_mov_b32_e32 v125, v2
	v_mov_b32_e32 v126, v2
	v_mov_b32_e32 v127, v2
	v_mov_b32_e32 v128, v2
	v_mov_b32_e32 v129, v2
	v_add_u32_e32 v158, 16, v219
	v_add_u32_e32 v170, 16, v218
	v_add_u32_e32 v158, v158, v0
	v_add_u32_e32 v170, v170, v0
	ds_read_b128 v[154:157], v158
	ds_read_b128 v[182:185], v170 offset:8192
	ds_read_b128 v[178:181], v170 offset:10240
	ds_read_b128 v[158:161], v158 offset:2048
	ds_read_b128 v[174:177], v170 offset:12288
	ds_read_b128 v[170:173], v170 offset:14336
	s_setprio 1
; #define LAS __attribute__((address_space(3)))
; DI f32x16 mfma32(bf16x8 a, bf16x8 b, f32x16 c) { return __builtin_amdgcn_mfma_f32_32x32x16_bf16(a, b, c, 0, 0, 0); }
;     ...
;   for (int kt = 0; kt < nk; ++kt) {
;     const int kn = (kt + 2 < nk) ? (kt + 2) : (nk - 1);
;     const LAS char* cur = lds + s0;
;     bf16x8 af[2][2], bfr[2][4];
; #pragma unroll
;     for (int kk = 0; kk < 2; ++kk) {
;       const int xo = kk ? x1 : x0;
;       af[kk][0] = *(const LAS bf16x8*)(cur + a_rd + xo);
;       bfr[kk][0] = *(const LAS bf16x8*)(cur + b_rd + xo);
;       bfr[kk][1] = *(const LAS bf16x8*)(cur + b_rd + 2048 + xo);
;       af[kk][1] = *(const LAS bf16x8*)(cur + a_rd + 2048 + xo);
;       bfr[kk][2] = *(const LAS bf16x8*)(cur + b_rd + 4096 + xo);
;       bfr[kk][3] = *(const LAS bf16x8*)(cur + b_rd + 6144 + xo);
;     }
;     DMA_STEP_(kn, s2);
; #pragma unroll
;     for (int kk = 0; kk < 2; ++kk) {
;       acc[0][0] = mfma32(bfr[kk][0], af[kk][0], acc[0][0]); acc[0][1] = mfma32(bfr[kk][1], af[kk][0], acc[0][1]);
;       acc[1][0] = mfma32(bfr[kk][0], af[kk][1], acc[1][0]); acc[1][1] = mfma32(bfr[kk][1], af[kk][1], acc[1][1]);
;       acc[0][2] = mfma32(bfr[kk][2], af[kk][0], acc[0][2]); acc[0][3] = mfma32(bfr[kk][3], af[kk][0], acc[0][3]);
;       acc[1][2] = mfma32(bfr[kk][2], af[kk][1], acc[1][2]); acc[1][3] = mfma32(bfr[kk][3], af[kk][1], acc[1][3]);
;     }
;     __builtin_amdgcn_sched_group_barrier(0x100, 12, 0);
;     __builtin_amdgcn_sched_group_barrier(0x010, 6, 0);
;     __builtin_amdgcn_sched_group_barrier(0x008, 16, 0);
;     asm volatile("s_waitcnt vmcnt(6) lgkmcnt(0)" ::: "memory");
;     __builtin_amdgcn_s_barrier();
;     asm volatile("" ::: "memory");
;     s0 = (s0 == 2 * STG) ? 0 : s0 + STG;
;     s2 = (s2 == 2 * STG) ? 0 : s2 + STG;
;   }
.LBB0_21:
	s_add_i32 s11, s42, 16
	s_mov_b32 s10, s40
	v_add_u32_e32 v142, s11, v219
	v_add_u32_e32 v150, s11, v218
	s_min_u32 s10, s10, 29
	v_add_u32_e32 v142, v142, v220
	v_add_u32_e32 v150, v150, v220
	s_lshl_b32 s70, s10, 6
	ds_read_b128 v[138:141], v142
	ds_read_b128 v[162:165], v150 offset:8192
	ds_read_b128 v[166:169], v150 offset:10240
	ds_read_b128 v[142:145], v142 offset:2048
	ds_read_b128 v[146:149], v150 offset:12288
	ds_read_b128 v[150:153], v150 offset:14336
	v_lshl_add_u64 v[222:223], v[192:193], 0, s[70:71]
	s_add_i32 s10, s13, s41
	v_lshl_add_u64 v[224:225], v[222:223], 0, s[24:25]
	s_mov_b32 m0, s10
	v_lshl_add_u64 v[222:223], v[222:223], 0, s[38:39]
	s_mul_i32 s100, s70, 0x400
	s_waitcnt lgkmcnt(6)
	v_mfma_f32_32x32x16_bf16 v[114:129], v[182:185], v[154:157], v[114:129]
	global_load_lds_dwordx4 v[224:225], off
	s_add_i32 m0, s10, 0x400
	v_mfma_f32_32x32x16_bf16 v[98:113], v[178:181], v[154:157], v[98:113]
	global_load_lds_dwordx4 v[222:223], off
	v_lshl_add_u64 v[224:225], v[194:195], 0, s[100:101]
	s_add_i32 s10, s29, s41
	s_add_i32 m0, s10, 0x2000
	v_mfma_f32_32x32x16_bf16 v[66:81], v[182:185], v[158:161], v[66:81]
	global_load_lds_dwordx4 v[224:225], off
	v_mfma_f32_32x32x16_bf16 v[34:49], v[178:181], v[158:161], v[34:49]
	global_load_lds_dwordx4 v[224:225], off offset:1024
	v_mfma_f32_32x32x16_bf16 v[82:97], v[174:177], v[154:157], v[82:97]
	global_load_lds_dwordx4 v[224:225], off offset:2048
	v_mfma_f32_32x32x16_bf16 v[50:65], v[170:173], v[154:157], v[50:65]
	global_load_lds_dwordx4 v[224:225], off offset:3072
	v_mfma_f32_32x32x16_bf16 v[18:33], v[174:177], v[158:161], v[18:33]
	s_add_i32 s10, s42, 0x6000
	s_cmpk_lg_u32 s42, 0xc000
	s_cselect_b32 s42, s10, 0
	s_add_i32 s10, s41, 0x6000
	s_cmpk_lg_u32 s41, 0xc000
	s_cselect_b32 s41, s10, 0
	v_mfma_f32_32x32x16_bf16 v[2:17], v[170:173], v[158:161], v[2:17]
	s_add_i32 s11, s42, 16
	s_waitcnt vmcnt(6) lgkmcnt(0)
	s_barrier
	v_add_u32_e32 v158, s11, v219
	v_add_u32_e32 v170, s11, v218
	v_add_u32_e32 v158, v158, v0
	v_add_u32_e32 v170, v170, v0
	ds_read_b128 v[154:157], v158
	ds_read_b128 v[182:185], v170 offset:8192
	ds_read_b128 v[178:181], v170 offset:10240
	ds_read_b128 v[158:161], v158 offset:2048
	ds_read_b128 v[174:177], v170 offset:12288
	ds_read_b128 v[170:173], v170 offset:14336
	v_mfma_f32_32x32x16_bf16 v[114:129], v[162:165], v[138:141], v[114:129]
	v_mfma_f32_32x32x16_bf16 v[98:113], v[166:169], v[138:141], v[98:113]
	v_mfma_f32_32x32x16_bf16 v[66:81], v[162:165], v[142:145], v[66:81]
	v_mfma_f32_32x32x16_bf16 v[34:49], v[166:169], v[142:145], v[34:49]
	v_mfma_f32_32x32x16_bf16 v[82:97], v[146:149], v[138:141], v[82:97]
	v_mfma_f32_32x32x16_bf16 v[50:65], v[150:153], v[138:141], v[50:65]
	v_mfma_f32_32x32x16_bf16 v[18:33], v[146:149], v[142:145], v[18:33]
	v_mfma_f32_32x32x16_bf16 v[2:17], v[150:153], v[142:145], v[2:17]
	s_add_i32 s11, s42, 16
	s_add_i32 s10, s40, 1
	v_add_u32_e32 v142, s11, v219
	v_add_u32_e32 v150, s11, v218
	s_min_u32 s10, s10, 29
	v_add_u32_e32 v142, v142, v220
	v_add_u32_e32 v150, v150, v220
	s_lshl_b32 s70, s10, 6
	ds_read_b128 v[138:141], v142
	ds_read_b128 v[162:165], v150 offset:8192
	ds_read_b128 v[166:169], v150 offset:10240
	ds_read_b128 v[142:145], v142 offset:2048
	ds_read_b128 v[146:149], v150 offset:12288
	ds_read_b128 v[150:153], v150 offset:14336
	v_lshl_add_u64 v[222:223], v[192:193], 0, s[70:71]
	s_add_i32 s10, s13, s41
	v_lshl_add_u64 v[224:225], v[222:223], 0, s[24:25]
	s_mov_b32 m0, s10
	v_lshl_add_u64 v[222:223], v[222:223], 0, s[38:39]
	s_mul_i32 s100, s70, 0x400
	s_waitcnt lgkmcnt(6)
	v_mfma_f32_32x32x16_bf16 v[114:129], v[182:185], v[154:157], v[114:129]
	global_load_lds_dwordx4 v[224:225], off
	s_add_i32 m0, s10, 0x400
	v_mfma_f32_32x32x16_bf16 v[98:113], v[178:181], v[154:157], v[98:113]
	global_load_lds_dwordx4 v[222:223], off
	v_lshl_add_u64 v[224:225], v[194:195], 0, s[100:101]
	s_add_i32 s10, s29, s41
	s_add_i32 m0, s10, 0x2000
	v_mfma_f32_32x32x16_bf16 v[66:81], v[182:185], v[158:161], v[66:81]
	global_load_lds_dwordx4 v[224:225], off
	v_mfma_f32_32x32x16_bf16 v[34:49], v[178:181], v[158:161], v[34:49]
	global_load_lds_dwordx4 v[224:225], off offset:1024
	v_mfma_f32_32x32x16_bf16 v[82:97], v[174:177], v[154:157], v[82:97]
	global_load_lds_dwordx4 v[224:225], off offset:2048
	v_mfma_f32_32x32x16_bf16 v[50:65], v[170:173], v[154:157], v[50:65]
	global_load_lds_dwordx4 v[224:225], off offset:3072
	v_mfma_f32_32x32x16_bf16 v[18:33], v[174:177], v[158:161], v[18:33]
	s_add_i32 s10, s42, 0x6000
	s_cmpk_lg_u32 s42, 0xc000
	s_cselect_b32 s42, s10, 0
	s_add_i32 s10, s41, 0x6000
	s_cmpk_lg_u32 s41, 0xc000
	s_cselect_b32 s41, s10, 0
	v_mfma_f32_32x32x16_bf16 v[2:17], v[170:173], v[158:161], v[2:17]
	s_add_i32 s11, s42, 16
	s_waitcnt vmcnt(6) lgkmcnt(0)
	s_barrier
	v_add_u32_e32 v158, s11, v219
	v_add_u32_e32 v170, s11, v218
	v_add_u32_e32 v158, v158, v0
	v_add_u32_e32 v170, v170, v0
	ds_read_b128 v[154:157], v158
	ds_read_b128 v[182:185], v170 offset:8192
	ds_read_b128 v[178:181], v170 offset:10240
	ds_read_b128 v[158:161], v158 offset:2048
	ds_read_b128 v[174:177], v170 offset:12288
	ds_read_b128 v[170:173], v170 offset:14336
	v_mfma_f32_32x32x16_bf16 v[114:129], v[162:165], v[138:141], v[114:129]
	v_mfma_f32_32x32x16_bf16 v[98:113], v[166:169], v[138:141], v[98:113]
	v_mfma_f32_32x32x16_bf16 v[66:81], v[162:165], v[142:145], v[66:81]
	v_mfma_f32_32x32x16_bf16 v[34:49], v[166:169], v[142:145], v[34:49]
	v_mfma_f32_32x32x16_bf16 v[82:97], v[146:149], v[138:141], v[82:97]
	v_mfma_f32_32x32x16_bf16 v[50:65], v[150:153], v[138:141], v[50:65]
	v_mfma_f32_32x32x16_bf16 v[18:33], v[146:149], v[142:145], v[18:33]
	v_mfma_f32_32x32x16_bf16 v[2:17], v[150:153], v[142:145], v[2:17]
	s_add_i32 s40, s40, 2
	s_cmp_lg_u32 s40, 32
	s_cbranch_scc1 .LBB0_21
; DI unsigned pk2(float a, float b) { f32x2 v = {a, b}; bf2_t r = __builtin_convertvector(v, bf2_t); return __builtin_bit_cast(unsigned, r); }
;     ...
;   asm volatile("s_waitcnt vmcnt(0)" ::: "memory");
;   __builtin_amdgcn_s_barrier();
;   asm volatile("" ::: "memory");
;     ...
;   {
;     const int h = lane >> 5, cl = lane & 31;
; #pragma unroll
;     for (int i = 0; i < 2; ++i)
; #pragma unroll
;       for (int j = 0; j < 4; ++j)
; #pragma unroll
;         for (int g = 0; g < 4; ++g) {
;           u32x2 w; w.x = pk2(acc[i][j][4 * g], acc[i][j][4 * g + 1]); w.y = pk2(acc[i][j][4 * g + 2], acc[i][j][4 * g + 3]);
;           *(u32x2*)(smem + (wr * 64 + i * 32 + cl) * 528 + (wc * 128 + j * 32 + 8 * g + 4 * h) * 2) = w;
;         }
;   }
;   __syncthreads();
	s_waitcnt lgkmcnt(0)
	s_setprio 0
	v_mul_lo_u32 v0, v197, s55
	v_add_u32_e32 v0, 16, v0
	s_nop 1
	v_cvt_pk_bf16_f32 v114, v114, v115
	v_cvt_pk_bf16_f32 v115, v116, v117
	v_lshlrev_b32_e32 v116, 3, v196
	s_lshl_b32 s10, s28, 1
	v_add3_u32 v0, v0, v116, s10
	v_cvt_pk_bf16_f32 v116, v118, v119
	v_cvt_pk_bf16_f32 v117, v120, v121
	v_cvt_pk_bf16_f32 v98, v98, v99
	v_cvt_pk_bf16_f32 v99, v100, v101
	v_cvt_pk_bf16_f32 v100, v102, v103
	v_cvt_pk_bf16_f32 v101, v104, v105
	v_cvt_pk_bf16_f32 v82, v82, v83
	v_cvt_pk_bf16_f32 v83, v84, v85
	v_cvt_pk_bf16_f32 v84, v86, v87
	v_cvt_pk_bf16_f32 v85, v88, v89
	v_cvt_pk_bf16_f32 v50, v50, v51
	v_cvt_pk_bf16_f32 v51, v52, v53
	v_cvt_pk_bf16_f32 v52, v54, v55
	v_cvt_pk_bf16_f32 v53, v56, v57
	s_waitcnt vmcnt(0)
	s_barrier
	ds_write2_b64 v0, v[114:115], v[116:117] offset1:2
	v_cvt_pk_bf16_f32 v114, v122, v123
	v_cvt_pk_bf16_f32 v115, v124, v125
	v_cvt_pk_bf16_f32 v116, v126, v127
	v_cvt_pk_bf16_f32 v117, v128, v129
	ds_write2_b64 v0, v[98:99], v[100:101] offset0:8 offset1:10
	v_cvt_pk_bf16_f32 v98, v106, v107
	v_cvt_pk_bf16_f32 v99, v108, v109
	v_cvt_pk_bf16_f32 v100, v110, v111
	v_cvt_pk_bf16_f32 v101, v112, v113
	ds_write2_b64 v0, v[82:83], v[84:85] offset0:16 offset1:18
	v_cvt_pk_bf16_f32 v82, v90, v91
	v_cvt_pk_bf16_f32 v83, v92, v93
	v_cvt_pk_bf16_f32 v84, v94, v95
	v_cvt_pk_bf16_f32 v85, v96, v97
	ds_write2_b64 v0, v[50:51], v[52:53] offset0:24 offset1:26
	v_cvt_pk_bf16_f32 v50, v58, v59
	v_cvt_pk_bf16_f32 v51, v60, v61
	v_cvt_pk_bf16_f32 v52, v62, v63
	v_cvt_pk_bf16_f32 v53, v64, v65
	ds_write2_b64 v0, v[114:115], v[116:117] offset0:4 offset1:6
	ds_write2_b64 v0, v[98:99], v[100:101] offset0:12 offset1:14
	ds_write2_b64 v0, v[82:83], v[84:85] offset0:20 offset1:22
	ds_write2_b64 v0, v[50:51], v[52:53] offset0:28 offset1:30
	v_cvt_pk_bf16_f32 v50, v66, v67
	v_cvt_pk_bf16_f32 v51, v68, v69
	v_cvt_pk_bf16_f32 v52, v70, v71
	v_cvt_pk_bf16_f32 v53, v72, v73
	v_add_u32_e32 v0, 0x4000, v0
	v_cvt_pk_bf16_f32 v34, v34, v35
	v_cvt_pk_bf16_f32 v35, v36, v37
	v_cvt_pk_bf16_f32 v36, v38, v39
	v_cvt_pk_bf16_f32 v37, v40, v41
	v_cvt_pk_bf16_f32 v18, v18, v19
	v_cvt_pk_bf16_f32 v19, v20, v21
	v_cvt_pk_bf16_f32 v20, v22, v23
	v_cvt_pk_bf16_f32 v21, v24, v25
	v_cvt_pk_bf16_f32 v2, v2, v3
	v_cvt_pk_bf16_f32 v3, v4, v5
	v_cvt_pk_bf16_f32 v4, v6, v7
	v_cvt_pk_bf16_f32 v5, v8, v9
	ds_write2_b64 v0, v[50:51], v[52:53] offset0:64 offset1:66
	v_cvt_pk_bf16_f32 v50, v74, v75
	v_cvt_pk_bf16_f32 v51, v76, v77
	v_cvt_pk_bf16_f32 v52, v78, v79
	v_cvt_pk_bf16_f32 v53, v80, v81
	ds_write2_b64 v0, v[34:35], v[36:37] offset0:72 offset1:74
	v_cvt_pk_bf16_f32 v34, v42, v43
	v_cvt_pk_bf16_f32 v35, v44, v45
	v_cvt_pk_bf16_f32 v36, v46, v47
	v_cvt_pk_bf16_f32 v37, v48, v49
	ds_write2_b64 v0, v[18:19], v[20:21] offset0:80 offset1:82
	v_cvt_pk_bf16_f32 v18, v26, v27
	v_cvt_pk_bf16_f32 v19, v28, v29
	v_cvt_pk_bf16_f32 v20, v30, v31
	v_cvt_pk_bf16_f32 v21, v32, v33
	ds_write2_b64 v0, v[2:3], v[4:5] offset0:88 offset1:90
	v_cvt_pk_bf16_f32 v2, v10, v11
	v_cvt_pk_bf16_f32 v3, v12, v13
	v_cvt_pk_bf16_f32 v4, v14, v15
	v_cvt_pk_bf16_f32 v5, v16, v17
	s_lshl_b64 s[14:15], s[14:15], 1
	ds_write2_b64 v0, v[50:51], v[52:53] offset0:68 offset1:70
	ds_write2_b64 v0, v[34:35], v[36:37] offset0:76 offset1:78
	ds_write2_b64 v0, v[18:19], v[20:21] offset0:84 offset1:86
	ds_write2_b64 v0, v[2:3], v[4:5] offset0:92 offset1:94
	s_waitcnt vmcnt(0) lgkmcnt(0)
	s_barrier
; #define GAS __attribute__((address_space(1)))
;     ...
;   int tid2 = tid; asm volatile("" : "+v"(tid2));
;   if (EPI == 0) {
; #pragma unroll
;     for (int i = 0; i < 16; ++i) {
;       const int id = tid2 + 256 * i, r = id >> 5, c8 = (id & 31) * 8;
;       const u32x4 v = *(const u32x4*)(smem + r * 528 + c8 * 2);
;       *(GAS u32x4*)(ea.out + (size_t)(m0 + r) * ea.ldo + n0 + c8) = v;
;     }
	s_add_u32 s14, s19, s14
	v_lshlrev_b32_e32 v0, 4, v189
	v_and_b32_e32 v0, 0x1f0, v0
	s_addc_u32 s15, s20, s15
	v_add_u32_e32 v10, 16, v0
	v_lshl_add_u64 v[12:13], s[14:15], 0, v[0:1]
	v_ashrrev_i32_e32 v0, 5, v189
	v_mad_u64_u32 v[2:3], s[14:15], v0, s55, v[10:11]
	ds_read_b128 v[2:5], v2
	v_add_u32_e32 v6, s12, v0
	v_ashrrev_i32_e32 v7, 31, v6
	v_add_u32_e32 v0, 0x100, v189
	v_lshlrev_b64 v[6:7], 11, v[6:7]
	v_ashrrev_i32_e32 v0, 5, v0
	v_lshl_add_u64 v[14:15], v[12:13], 0, v[6:7]
	v_mad_u64_u32 v[6:7], s[14:15], v0, s55, v[10:11]
	ds_read_b128 v[6:9], v6
	s_waitcnt lgkmcnt(1)
	global_store_dwordx4 v[14:15], v[2:5], off
	v_readlane_b32 s10, v252, 12
	s_add_i32 s23, s23, s10
	v_add_u32_e32 v2, s12, v0
	v_ashrrev_i32_e32 v3, 31, v2
	v_lshlrev_b64 v[2:3], 11, v[2:3]
	v_add_u32_e32 v0, 0x200, v189
	v_lshl_add_u64 v[2:3], v[12:13], 0, v[2:3]
	v_ashrrev_i32_e32 v0, 5, v0
	s_waitcnt lgkmcnt(0)
	global_store_dwordx4 v[2:3], v[6:9], off
	v_mad_u64_u32 v[2:3], s[14:15], v0, s55, v[10:11]
	ds_read_b128 v[2:5], v2
	v_add_u32_e32 v6, s12, v0
	v_ashrrev_i32_e32 v7, 31, v6
	v_add_u32_e32 v0, 0x300, v189
	v_lshlrev_b64 v[6:7], 11, v[6:7]
	v_ashrrev_i32_e32 v0, 5, v0
	v_lshl_add_u64 v[14:15], v[12:13], 0, v[6:7]
	v_mad_u64_u32 v[6:7], s[14:15], v0, s55, v[10:11]
	ds_read_b128 v[6:9], v6
	s_waitcnt lgkmcnt(1)
	global_store_dwordx4 v[14:15], v[2:5], off
	s_cmp_ge_i32 s23, s16
	s_nop 0
	v_add_u32_e32 v2, s12, v0
	v_ashrrev_i32_e32 v3, 31, v2
	v_lshlrev_b64 v[2:3], 11, v[2:3]
	v_add_u32_e32 v0, 0x400, v189
	v_lshl_add_u64 v[2:3], v[12:13], 0, v[2:3]
	v_ashrrev_i32_e32 v0, 5, v0
	s_waitcnt lgkmcnt(0)
	global_store_dwordx4 v[2:3], v[6:9], off
	v_mad_u64_u32 v[2:3], s[14:15], v0, s55, v[10:11]
	ds_read_b128 v[2:5], v2
	v_add_u32_e32 v6, s12, v0
	v_ashrrev_i32_e32 v7, 31, v6
	v_add_u32_e32 v0, 0x500, v189
	v_lshlrev_b64 v[6:7], 11, v[6:7]
	v_ashrrev_i32_e32 v0, 5, v0
	v_lshl_add_u64 v[14:15], v[12:13], 0, v[6:7]
	v_mad_u64_u32 v[6:7], s[14:15], v0, s55, v[10:11]
	ds_read_b128 v[6:9], v6
	s_waitcnt lgkmcnt(1)
	global_store_dwordx4 v[14:15], v[2:5], off
	s_nop 1
	v_add_u32_e32 v2, s12, v0
	v_ashrrev_i32_e32 v3, 31, v2
	v_lshlrev_b64 v[2:3], 11, v[2:3]
	v_add_u32_e32 v0, 0x600, v189
	v_lshl_add_u64 v[2:3], v[12:13], 0, v[2:3]
	v_ashrrev_i32_e32 v0, 5, v0
	s_waitcnt lgkmcnt(0)
	global_store_dwordx4 v[2:3], v[6:9], off
	v_mad_u64_u32 v[2:3], s[14:15], v0, s55, v[10:11]
	ds_read_b128 v[2:5], v2
	v_add_u32_e32 v6, s12, v0
	v_ashrrev_i32_e32 v7, 31, v6
	v_add_u32_e32 v0, 0x700, v189
	v_lshlrev_b64 v[6:7], 11, v[6:7]
	v_ashrrev_i32_e32 v0, 5, v0
	v_lshl_add_u64 v[14:15], v[12:13], 0, v[6:7]
	v_mad_u64_u32 v[6:7], s[14:15], v0, s55, v[10:11]
	ds_read_b128 v[6:9], v6
	s_waitcnt lgkmcnt(1)
	global_store_dwordx4 v[14:15], v[2:5], off
	s_nop 1
	v_add_u32_e32 v2, s12, v0
	v_ashrrev_i32_e32 v3, 31, v2
	v_lshlrev_b64 v[2:3], 11, v[2:3]
	v_add_u32_e32 v0, 0x800, v189
	v_lshl_add_u64 v[2:3], v[12:13], 0, v[2:3]
	v_ashrrev_i32_e32 v0, 5, v0
	s_waitcnt lgkmcnt(0)
	global_store_dwordx4 v[2:3], v[6:9], off
	v_mad_u64_u32 v[2:3], s[14:15], v0, s55, v[10:11]
	ds_read_b128 v[2:5], v2
	v_add_u32_e32 v6, s12, v0
	v_ashrrev_i32_e32 v7, 31, v6
	v_add_u32_e32 v0, 0x900, v189
	v_lshlrev_b64 v[6:7], 11, v[6:7]
	v_ashrrev_i32_e32 v0, 5, v0
	v_lshl_add_u64 v[14:15], v[12:13], 0, v[6:7]
	v_mad_u64_u32 v[6:7], s[14:15], v0, s55, v[10:11]
	ds_read_b128 v[6:9], v6
	s_waitcnt lgkmcnt(1)
	global_store_dwordx4 v[14:15], v[2:5], off
	s_nop 1
	v_add_u32_e32 v2, s12, v0
	v_ashrrev_i32_e32 v3, 31, v2
	v_lshlrev_b64 v[2:3], 11, v[2:3]
	v_add_u32_e32 v0, 0xa00, v189
	v_lshl_add_u64 v[2:3], v[12:13], 0, v[2:3]
	v_ashrrev_i32_e32 v0, 5, v0
	s_waitcnt lgkmcnt(0)
	global_store_dwordx4 v[2:3], v[6:9], off
	v_mad_u64_u32 v[2:3], s[14:15], v0, s55, v[10:11]
	ds_read_b128 v[2:5], v2
	v_add_u32_e32 v6, s12, v0
	v_ashrrev_i32_e32 v7, 31, v6
	v_add_u32_e32 v0, 0xb00, v189
	v_lshlrev_b64 v[6:7], 11, v[6:7]
	v_ashrrev_i32_e32 v0, 5, v0
	v_lshl_add_u64 v[14:15], v[12:13], 0, v[6:7]
	v_mad_u64_u32 v[6:7], s[14:15], v0, s55, v[10:11]
	ds_read_b128 v[6:9], v6
	s_waitcnt lgkmcnt(1)
	global_store_dwordx4 v[14:15], v[2:5], off
	s_nop 1
	v_add_u32_e32 v2, s12, v0
	v_ashrrev_i32_e32 v3, 31, v2
	v_lshlrev_b64 v[2:3], 11, v[2:3]
	v_add_u32_e32 v0, 0xc00, v189
	v_lshl_add_u64 v[2:3], v[12:13], 0, v[2:3]
	v_ashrrev_i32_e32 v0, 5, v0
	s_waitcnt lgkmcnt(0)
	global_store_dwordx4 v[2:3], v[6:9], off
	v_mad_u64_u32 v[2:3], s[14:15], v0, s55, v[10:11]
	ds_read_b128 v[2:5], v2
	v_add_u32_e32 v6, s12, v0
	v_ashrrev_i32_e32 v7, 31, v6
	v_add_u32_e32 v0, 0xd00, v189
	v_lshlrev_b64 v[6:7], 11, v[6:7]
	v_ashrrev_i32_e32 v0, 5, v0
	v_lshl_add_u64 v[14:15], v[12:13], 0, v[6:7]
	v_mad_u64_u32 v[6:7], s[14:15], v0, s55, v[10:11]
	ds_read_b128 v[6:9], v6
	s_waitcnt lgkmcnt(1)
	global_store_dwordx4 v[14:15], v[2:5], off
	s_nop 1
	v_add_u32_e32 v2, s12, v0
	v_ashrrev_i32_e32 v3, 31, v2
	v_lshlrev_b64 v[2:3], 11, v[2:3]
	v_add_u32_e32 v0, 0xe00, v189
	v_lshl_add_u64 v[2:3], v[12:13], 0, v[2:3]
	v_ashrrev_i32_e32 v0, 5, v0
	s_waitcnt lgkmcnt(0)
	global_store_dwordx4 v[2:3], v[6:9], off
	v_mad_u64_u32 v[2:3], s[14:15], v0, s55, v[10:11]
	ds_read_b128 v[2:5], v2
	v_add_u32_e32 v6, s12, v0
	v_ashrrev_i32_e32 v7, 31, v6
	v_add_u32_e32 v0, 0xf00, v189
	v_lshlrev_b64 v[6:7], 11, v[6:7]
	v_ashrrev_i32_e32 v0, 5, v0
	v_lshl_add_u64 v[14:15], v[12:13], 0, v[6:7]
	v_mad_u64_u32 v[6:7], s[14:15], v0, s55, v[10:11]
	ds_read_b128 v[6:9], v6
	s_waitcnt lgkmcnt(1)
	global_store_dwordx4 v[14:15], v[2:5], off
	s_nop 1
	v_add_u32_e32 v2, s12, v0
	v_ashrrev_i32_e32 v3, 31, v2
	v_lshlrev_b64 v[2:3], 11, v[2:3]
	v_lshl_add_u64 v[2:3], v[12:13], 0, v[2:3]
	s_waitcnt lgkmcnt(0)
	global_store_dwordx4 v[2:3], v[6:9], off
	s_barrier
	s_cbranch_scc0 .LBB0_20

; #define LAS __attribute__((address_space(3)))
;   int tid = tid_in; asm volatile("" : "+v"(tid));
;   const int lane = tid & 63, wid = __builtin_amdgcn_readfirstlane(tid >> 6), wr = wid >> 1, wc = wid & 1;
;   const int m0 = mt * 128, n0 = nt * 256;
;   const int r = lane & 31, h = lane >> 5, key = (r >> 2) & 3;
;   constexpr int STG = 24576;
;   const int rowl = lane >> 2, cch = (lane & 3) ^ ((lane >> 4) & 3);
;   const unsigned voffA = (unsigned)(rowl * lda * 2 + cch * 16), voffB = (unsigned)(rowl * K * 2 + cch * 16);
;   const char* Abase = (const char*)(A + (size_t)m0 * lda) + (size_t)(wid * 2) * 32 * lda;
;   const char* Bbase = (const char*)(Bt + (size_t)n0 * K) + (size_t)(wid * 4) * 32 * K;
;   const size_t ablk = (size_t)32 * lda, bblk = (size_t)32 * K;
;   LAS char* lds = (LAS char*)smem;
;   LAS char* ldsA = lds + (wid * 2) * 1024;
;   LAS char* ldsB = lds + 8192 + (wid * 4) * 1024;
;     ...
;   const int x0 = ((0 + h) ^ key) * 16, x1 = ((2 + h) ^ key) * 16;
;   const int a_rd = (wr * 64 + r) * 64, b_rd = 8192 + (wc * 128 + r) * 64;
;   f32x16 acc[2][4];
; #pragma unroll
;   for (int i = 0; i < 2; ++i)
; #pragma unroll
;     for (int j = 0; j < 4; ++j)
; #pragma unroll
;       for (int e = 0; e < 16; ++e) acc[i][j][e] = 0.f;
;   const int nk = K >> 5;
;   DMA_STEP_(0, 0);
;   DMA_STEP_(1, STG);
;   asm volatile("s_waitcnt vmcnt(6)" ::: "memory");
;   __builtin_amdgcn_s_barrier();
;   asm volatile("" ::: "memory");
;   int s0 = 0, s2 = 2 * STG;
;   for (int kt = 0; kt < nk; ++kt) {
;     const int kn = (kt + 2 < nk) ? (kt + 2) : (nk - 1);
;     const LAS char* cur = lds + s0;
;     bf16x8 af[2][2], bfr[2][4];
; #pragma unroll
;     for (int kk = 0; kk < 2; ++kk) {
;       const int xo = kk ? x1 : x0;
;       af[kk][0] = *(const LAS bf16x8*)(cur + a_rd + xo);
;       bfr[kk][0] = *(const LAS bf16x8*)(cur + b_rd + xo);
;       bfr[kk][1] = *(const LAS bf16x8*)(cur + b_rd + 2048 + xo);
;       af[kk][1] = *(const LAS bf16x8*)(cur + a_rd + 2048 + xo);
;       bfr[kk][2] = *(const LAS bf16x8*)(cur + b_rd + 4096 + xo);
;       bfr[kk][3] = *(const LAS bf16x8*)(cur + b_rd + 6144 + xo);
;     }
.LBB0_183:
	s_mul_hi_i32 s10, s20, 0x38e38e39
	s_lshr_b32 s11, s10, 31
	s_ashr_i32 s10, s10, 4
	v_mov_b32_e32 v189, v188
	s_add_i32 s10, s10, s11
	v_readlane_b32 s12, v252, 18
	s_mul_i32 s11, s10, 0xffffffb8
	v_readfirstlane_b32 s21, v189
	s_lshl_b32 s10, s10, s12
	v_readlane_b32 s12, v252, 41
	s_ashr_i32 s44, s21, 6
	s_add_i32 s10, s10, s12
	s_lshl_b32 s12, s20, 7
	s_lshl_b32 s22, s44, 1
	s_add_i32 s11, s11, s20
	s_lshl_b32 s10, s10, 10
	s_and_b32 s12, s12, 0x380
	s_ashr_i32 s23, s22, 31
	s_or_b32 s12, s10, s12
	s_lshl_b32 s10, s11, 5
	s_lshl_b64 s[28:29], s[22:23], 10
	s_lshl_b32 s22, s44, 2
	s_ashr_i32 s11, s21, 1
	s_and_b32 s14, s10, 0xffffff00
	v_and_b32_e32 v0, 31, v189
	s_ashr_i32 s23, s22, 31
	s_lshl_b32 s10, s44, 12
	s_andn2_b32 s11, s11, 63
	v_lshlrev_b32_e32 v2, 4, v189
	s_ashr_i32 s13, s12, 31
	s_lshl_b64 s[40:41], s[22:23], 10
	s_add_i32 s22, s10, 16
	v_or_b32_e32 v197, s11, v0
	s_lshl_b32 s11, s44, 7
	v_bitop3_b32 v2, v2, 48, v189 bitop3:0x48
	v_lshlrev_b32_e32 v3, 9, v189
	s_ashr_i32 s15, s14, 31
	s_add_i32 s10, s22, 0x2000
	s_and_b32 s21, s11, 0x80
	s_movk_i32 s11, 0x7800
	s_lshl_b64 s[42:43], s[12:13], 6
	v_or_b32_e32 v4, s21, v0
	v_and_or_b32 v0, v3, s11, v2
	v_lshlrev_b32_e32 v10, 4, v189
	v_and_b32_e32 v10, 0x3c0, v10
	v_or_b32_e32 v10, v10, v2
	v_mov_b32_e32 v11, 0
	s_add_u32 s11, s18, s42
	s_addc_u32 s13, s19, s43
	s_add_u32 s28, s11, s28
	s_addc_u32 s29, s13, s29
	s_lshl_b64 s[42:43], s[14:15], 6
	v_readlane_b32 s46, v250, 18
	v_readlane_b32 s47, v250, 19
	s_add_u32 s11, s46, s42
	s_addc_u32 s13, s47, s43
	s_add_u32 s40, s11, s40
	s_addc_u32 s41, s13, s41
	s_lshl_b32 s11, s44, 11
	s_sub_i32 s13, s22, s11
	v_lshl_add_u64 v[192:193], s[28:29], 0, v[10:11]
	s_mov_b32 m0, s13
	s_nop 0
	global_load_lds_dwordx4 v[192:193], off
	global_load_lds_dwordx4 v[192:193], off offset:1024
	v_lshl_add_u64 v[194:195], s[40:41], 0, v[10:11]
	s_mov_b32 m0, s10
	s_nop 0
	global_load_lds_dwordx4 v[194:195], off
	global_load_lds_dwordx4 v[194:195], off offset:1024
	global_load_lds_dwordx4 v[194:195], off offset:2048
	global_load_lds_dwordx4 v[194:195], off offset:3072
	s_mov_b64 s[10:11], 0x10000
	s_mov_b64 s[10:11], 0x18000
	s_mov_b64 s[10:11], 0x8040
	s_add_i32 m0, s13, 0x6000
	s_mov_b32 vcc_lo, 0x480000
	s_mov_b32 vcc_hi, 0
	v_lshl_add_u64 v[2:3], v[192:193], 0, vcc
	global_load_lds_dwordx4 v[2:3], off
	global_load_lds_dwordx4 v[2:3], off offset:1024
	v_bfe_u32 v196, v189, 5, 1
	s_add_i32 m0, s22, 0x8000
	s_mov_b32 s100, 0x24000
	v_lshl_add_u64 v[2:3], v[194:195], 0, s[100:101]
	global_load_lds_dwordx4 v[2:3], off
	global_load_lds_dwordx4 v[2:3], off offset:1024
	global_load_lds_dwordx4 v[2:3], off offset:2048
	global_load_lds_dwordx4 v[2:3], off offset:3072
	s_mov_b64 s[10:11], 0x10040
	s_mov_b64 s[10:11], 0x18040
	v_lshlrev_b32_e32 v218, 6, v4
	v_bfe_u32 v4, v189, 2, 2
	v_lshrrev_b32_e32 v5, 5, v189
	s_lshl_b32 s100, s100, 1
	v_lshl_add_u64 v[194:195], v[194:195], 0, s[100:101]
	s_lshl_b32 vcc_lo, vcc_lo, 1
	v_lshl_add_u64 v[192:193], v[192:193], 0, vcc
	s_waitcnt vmcnt(6)
	s_barrier
	v_bitop3_b32 v2, v196, v4, 2 bitop3:0x36
	v_bitop3_b32 v0, v5, v4, 1 bitop3:0x6c
	v_lshlrev_b32_e32 v220, 4, v2
	v_mov_b32_e32 v2, 0
	v_lshlrev_b32_e32 v219, 6, v197
	v_lshlrev_b32_e32 v0, 4, v0
	s_mov_b32 s28, 0xc000
	s_mov_b32 s23, 0
	s_mov_b32 s29, 0
	v_mov_b32_e32 v3, v2
	v_mov_b32_e32 v4, v2
	v_mov_b32_e32 v5, v2
	v_mov_b32_e32 v6, v2
	v_mov_b32_e32 v7, v2
	v_mov_b32_e32 v8, v2
	v_mov_b32_e32 v9, v2
	v_mov_b32_e32 v10, v2
	v_mov_b32_e32 v11, v2
	v_mov_b32_e32 v12, v2
	v_mov_b32_e32 v13, v2
	v_mov_b32_e32 v14, v2
	v_mov_b32_e32 v15, v2
	v_mov_b32_e32 v16, v2
	v_mov_b32_e32 v17, v2
	v_mov_b32_e32 v18, v2
	v_mov_b32_e32 v19, v2
	v_mov_b32_e32 v20, v2
	v_mov_b32_e32 v21, v2
	v_mov_b32_e32 v22, v2
	v_mov_b32_e32 v23, v2
	v_mov_b32_e32 v24, v2
	v_mov_b32_e32 v25, v2
	v_mov_b32_e32 v26, v2
	v_mov_b32_e32 v27, v2
	v_mov_b32_e32 v28, v2
	v_mov_b32_e32 v29, v2
	v_mov_b32_e32 v30, v2
	v_mov_b32_e32 v31, v2
	v_mov_b32_e32 v32, v2
	v_mov_b32_e32 v33, v2
	v_mov_b32_e32 v50, v2
	v_mov_b32_e32 v51, v2
	v_mov_b32_e32 v52, v2
	v_mov_b32_e32 v53, v2
	v_mov_b32_e32 v54, v2
	v_mov_b32_e32 v55, v2
	v_mov_b32_e32 v56, v2
	v_mov_b32_e32 v57, v2
	v_mov_b32_e32 v58, v2
	v_mov_b32_e32 v59, v2
	v_mov_b32_e32 v60, v2
	v_mov_b32_e32 v61, v2
	v_mov_b32_e32 v62, v2
	v_mov_b32_e32 v63, v2
	v_mov_b32_e32 v64, v2
	v_mov_b32_e32 v65, v2
	v_mov_b32_e32 v82, v2
	v_mov_b32_e32 v83, v2
	v_mov_b32_e32 v84, v2
	v_mov_b32_e32 v85, v2
	v_mov_b32_e32 v86, v2
	v_mov_b32_e32 v87, v2
	v_mov_b32_e32 v88, v2
	v_mov_b32_e32 v89, v2
	v_mov_b32_e32 v90, v2
	v_mov_b32_e32 v91, v2
	v_mov_b32_e32 v92, v2
	v_mov_b32_e32 v93, v2
	v_mov_b32_e32 v94, v2
	v_mov_b32_e32 v95, v2
	v_mov_b32_e32 v96, v2
	v_mov_b32_e32 v97, v2
	v_mov_b32_e32 v34, v2
	v_mov_b32_e32 v35, v2
	v_mov_b32_e32 v36, v2
	v_mov_b32_e32 v37, v2
	v_mov_b32_e32 v38, v2
	v_mov_b32_e32 v39, v2
	v_mov_b32_e32 v40, v2
	v_mov_b32_e32 v41, v2
	v_mov_b32_e32 v42, v2
	v_mov_b32_e32 v43, v2
	v_mov_b32_e32 v44, v2
	v_mov_b32_e32 v45, v2
	v_mov_b32_e32 v46, v2
	v_mov_b32_e32 v47, v2
	v_mov_b32_e32 v48, v2
	v_mov_b32_e32 v49, v2
	v_mov_b32_e32 v66, v2
	v_mov_b32_e32 v67, v2
	v_mov_b32_e32 v68, v2
	v_mov_b32_e32 v69, v2
	v_mov_b32_e32 v70, v2
	v_mov_b32_e32 v71, v2
	v_mov_b32_e32 v72, v2
	v_mov_b32_e32 v73, v2
	v_mov_b32_e32 v74, v2
	v_mov_b32_e32 v75, v2
	v_mov_b32_e32 v76, v2
	v_mov_b32_e32 v77, v2
	v_mov_b32_e32 v78, v2
	v_mov_b32_e32 v79, v2
	v_mov_b32_e32 v80, v2
	v_mov_b32_e32 v81, v2
	v_mov_b32_e32 v98, v2
	v_mov_b32_e32 v99, v2
	v_mov_b32_e32 v100, v2
	v_mov_b32_e32 v101, v2
	v_mov_b32_e32 v102, v2
	v_mov_b32_e32 v103, v2
	v_mov_b32_e32 v104, v2
	v_mov_b32_e32 v105, v2
	v_mov_b32_e32 v106, v2
	v_mov_b32_e32 v107, v2
	v_mov_b32_e32 v108, v2
	v_mov_b32_e32 v109, v2
	v_mov_b32_e32 v110, v2
	v_mov_b32_e32 v111, v2
	v_mov_b32_e32 v112, v2
	v_mov_b32_e32 v113, v2
	v_mov_b32_e32 v114, v2
	v_mov_b32_e32 v115, v2
	v_mov_b32_e32 v116, v2
	v_mov_b32_e32 v117, v2
	v_mov_b32_e32 v118, v2
	v_mov_b32_e32 v119, v2
	v_mov_b32_e32 v120, v2
	v_mov_b32_e32 v121, v2
	v_mov_b32_e32 v122, v2
	v_mov_b32_e32 v123, v2
	v_mov_b32_e32 v124, v2
	v_mov_b32_e32 v125, v2
	v_mov_b32_e32 v126, v2
	v_mov_b32_e32 v127, v2
	v_mov_b32_e32 v128, v2
	v_mov_b32_e32 v129, v2
	s_mov_b32 vcc_hi, 0
	v_add_u32_e32 v158, 16, v219
	v_add_u32_e32 v170, 16, v218
	v_add_u32_e32 v158, v158, v0
	v_add_u32_e32 v170, v170, v0
	ds_read_b128 v[154:157], v158
	ds_read_b128 v[182:185], v170 offset:8192
	ds_read_b128 v[178:181], v170 offset:10240
	ds_read_b128 v[158:161], v158 offset:2048
	ds_read_b128 v[174:177], v170 offset:12288
	ds_read_b128 v[170:173], v170 offset:14336
	s_setprio 1
; #define LAS __attribute__((address_space(3)))
; DI f32x16 mfma32(bf16x8 a, bf16x8 b, f32x16 c) { return __builtin_amdgcn_mfma_f32_32x32x16_bf16(a, b, c, 0, 0, 0); }
;     ...
;   for (int kt = 0; kt < nk; ++kt) {
;     const int kn = (kt + 2 < nk) ? (kt + 2) : (nk - 1);
;     const LAS char* cur = lds + s0;
;     bf16x8 af[2][2], bfr[2][4];
; #pragma unroll
;     for (int kk = 0; kk < 2; ++kk) {
;       const int xo = kk ? x1 : x0;
;       af[kk][0] = *(const LAS bf16x8*)(cur + a_rd + xo);
;       bfr[kk][0] = *(const LAS bf16x8*)(cur + b_rd + xo);
;       bfr[kk][1] = *(const LAS bf16x8*)(cur + b_rd + 2048 + xo);
;       af[kk][1] = *(const LAS bf16x8*)(cur + a_rd + 2048 + xo);
;       bfr[kk][2] = *(const LAS bf16x8*)(cur + b_rd + 4096 + xo);
;       bfr[kk][3] = *(const LAS bf16x8*)(cur + b_rd + 6144 + xo);
;     }
;     DMA_STEP_(kn, s2);
; #pragma unroll
;     for (int kk = 0; kk < 2; ++kk) {
;       acc[0][0] = mfma32(bfr[kk][0], af[kk][0], acc[0][0]); acc[0][1] = mfma32(bfr[kk][1], af[kk][0], acc[0][1]);
;       acc[1][0] = mfma32(bfr[kk][0], af[kk][1], acc[1][0]); acc[1][1] = mfma32(bfr[kk][1], af[kk][1], acc[1][1]);
;       acc[0][2] = mfma32(bfr[kk][2], af[kk][0], acc[0][2]); acc[0][3] = mfma32(bfr[kk][3], af[kk][0], acc[0][3]);
;       acc[1][2] = mfma32(bfr[kk][2], af[kk][1], acc[1][2]); acc[1][3] = mfma32(bfr[kk][3], af[kk][1], acc[1][3]);
;     }
;     __builtin_amdgcn_sched_group_barrier(0x100, 12, 0);
;     __builtin_amdgcn_sched_group_barrier(0x010, 6, 0);
;     __builtin_amdgcn_sched_group_barrier(0x008, 16, 0);
;     asm volatile("s_waitcnt vmcnt(6) lgkmcnt(0)" ::: "memory");
;     __builtin_amdgcn_s_barrier();
;     asm volatile("" ::: "memory");
;     s0 = (s0 == 2 * STG) ? 0 : s0 + STG;
;     s2 = (s2 == 2 * STG) ? 0 : s2 + STG;
;   }
.LBB0_184:
	s_add_i32 s11, s29, 16
	s_mov_b32 s10, s23
	v_add_u32_e32 v142, s11, v219
	v_add_u32_e32 v150, s11, v218
	s_min_u32 s10, s10, 29
	v_add_u32_e32 v142, v142, v220
	v_add_u32_e32 v150, v150, v220
	s_lshl_b32 s70, s10, 6
	ds_read_b128 v[138:141], v142
	ds_read_b128 v[162:165], v150 offset:8192
	ds_read_b128 v[166:169], v150 offset:10240
	ds_read_b128 v[142:145], v142 offset:2048
	ds_read_b128 v[146:149], v150 offset:12288
	ds_read_b128 v[150:153], v150 offset:14336
	s_mul_i32 vcc_lo, s70, 0x12000
	s_add_i32 s10, s13, s28
	v_lshl_add_u64 v[222:223], v[192:193], 0, vcc
	s_mov_b32 m0, s10
	s_mul_i32 s100, s70, 0x900
	v_lshl_add_u64 v[224:225], v[194:195], 0, s[100:101]
	s_add_i32 s10, s22, s28
	s_waitcnt lgkmcnt(6)
	v_mfma_f32_32x32x16_bf16 v[114:129], v[182:185], v[154:157], v[114:129]
	global_load_lds_dwordx4 v[222:223], off
	v_mfma_f32_32x32x16_bf16 v[98:113], v[178:181], v[154:157], v[98:113]
	global_load_lds_dwordx4 v[222:223], off offset:1024
	s_add_i32 m0, s10, 0x2000
	v_mfma_f32_32x32x16_bf16 v[66:81], v[182:185], v[158:161], v[66:81]
	global_load_lds_dwordx4 v[224:225], off
	v_mfma_f32_32x32x16_bf16 v[34:49], v[178:181], v[158:161], v[34:49]
	global_load_lds_dwordx4 v[224:225], off offset:1024
	v_mfma_f32_32x32x16_bf16 v[82:97], v[174:177], v[154:157], v[82:97]
	global_load_lds_dwordx4 v[224:225], off offset:2048
	v_mfma_f32_32x32x16_bf16 v[50:65], v[170:173], v[154:157], v[50:65]
	global_load_lds_dwordx4 v[224:225], off offset:3072
	v_mfma_f32_32x32x16_bf16 v[18:33], v[174:177], v[158:161], v[18:33]
	s_add_i32 s10, s29, 0x6000
	s_cmpk_lg_u32 s29, 0xc000
	s_cselect_b32 s29, s10, 0
	s_add_i32 s10, s28, 0x6000
	s_cmpk_lg_u32 s28, 0xc000
	s_cselect_b32 s28, s10, 0
	v_mfma_f32_32x32x16_bf16 v[2:17], v[170:173], v[158:161], v[2:17]
	s_add_i32 s11, s29, 16
	s_waitcnt vmcnt(6) lgkmcnt(0)
	s_barrier
	v_add_u32_e32 v158, s11, v219
	v_add_u32_e32 v170, s11, v218
	v_add_u32_e32 v158, v158, v0
	v_add_u32_e32 v170, v170, v0
	ds_read_b128 v[154:157], v158
	ds_read_b128 v[182:185], v170 offset:8192
	ds_read_b128 v[178:181], v170 offset:10240
	ds_read_b128 v[158:161], v158 offset:2048
	ds_read_b128 v[174:177], v170 offset:12288
	ds_read_b128 v[170:173], v170 offset:14336
	v_mfma_f32_32x32x16_bf16 v[114:129], v[162:165], v[138:141], v[114:129]
	v_mfma_f32_32x32x16_bf16 v[98:113], v[166:169], v[138:141], v[98:113]
	v_mfma_f32_32x32x16_bf16 v[66:81], v[162:165], v[142:145], v[66:81]
	v_mfma_f32_32x32x16_bf16 v[34:49], v[166:169], v[142:145], v[34:49]
	v_mfma_f32_32x32x16_bf16 v[82:97], v[146:149], v[138:141], v[82:97]
	v_mfma_f32_32x32x16_bf16 v[50:65], v[150:153], v[138:141], v[50:65]
	v_mfma_f32_32x32x16_bf16 v[18:33], v[146:149], v[142:145], v[18:33]
	v_mfma_f32_32x32x16_bf16 v[2:17], v[150:153], v[142:145], v[2:17]
	s_add_i32 s11, s29, 16
	s_add_i32 s10, s23, 1
	v_add_u32_e32 v142, s11, v219
	v_add_u32_e32 v150, s11, v218
	s_min_u32 s10, s10, 29
	v_add_u32_e32 v142, v142, v220
	v_add_u32_e32 v150, v150, v220
	s_lshl_b32 s70, s10, 6
	ds_read_b128 v[138:141], v142
	ds_read_b128 v[162:165], v150 offset:8192
	ds_read_b128 v[166:169], v150 offset:10240
	ds_read_b128 v[142:145], v142 offset:2048
	ds_read_b128 v[146:149], v150 offset:12288
	ds_read_b128 v[150:153], v150 offset:14336
	s_mul_i32 vcc_lo, s70, 0x12000
	s_add_i32 s10, s13, s28
	v_lshl_add_u64 v[222:223], v[192:193], 0, vcc
	s_mov_b32 m0, s10
	s_mul_i32 s100, s70, 0x900
	v_lshl_add_u64 v[224:225], v[194:195], 0, s[100:101]
	s_add_i32 s10, s22, s28
	s_waitcnt lgkmcnt(6)
	v_mfma_f32_32x32x16_bf16 v[114:129], v[182:185], v[154:157], v[114:129]
	global_load_lds_dwordx4 v[222:223], off
	v_mfma_f32_32x32x16_bf16 v[98:113], v[178:181], v[154:157], v[98:113]
	global_load_lds_dwordx4 v[222:223], off offset:1024
	s_add_i32 m0, s10, 0x2000
	v_mfma_f32_32x32x16_bf16 v[66:81], v[182:185], v[158:161], v[66:81]
	global_load_lds_dwordx4 v[224:225], off
	v_mfma_f32_32x32x16_bf16 v[34:49], v[178:181], v[158:161], v[34:49]
	global_load_lds_dwordx4 v[224:225], off offset:1024
	v_mfma_f32_32x32x16_bf16 v[82:97], v[174:177], v[154:157], v[82:97]
	global_load_lds_dwordx4 v[224:225], off offset:2048
	v_mfma_f32_32x32x16_bf16 v[50:65], v[170:173], v[154:157], v[50:65]
	global_load_lds_dwordx4 v[224:225], off offset:3072
	v_mfma_f32_32x32x16_bf16 v[18:33], v[174:177], v[158:161], v[18:33]
	s_add_i32 s10, s29, 0x6000
	s_cmpk_lg_u32 s29, 0xc000
	s_cselect_b32 s29, s10, 0
	s_add_i32 s10, s28, 0x6000
	s_cmpk_lg_u32 s28, 0xc000
	s_cselect_b32 s28, s10, 0
	v_mfma_f32_32x32x16_bf16 v[2:17], v[170:173], v[158:161], v[2:17]
	s_add_i32 s11, s29, 16
	s_waitcnt vmcnt(6) lgkmcnt(0)
	s_barrier
	v_add_u32_e32 v158, s11, v219
	v_add_u32_e32 v170, s11, v218
	v_add_u32_e32 v158, v158, v0
	v_add_u32_e32 v170, v170, v0
	ds_read_b128 v[154:157], v158
	ds_read_b128 v[182:185], v170 offset:8192
	ds_read_b128 v[178:181], v170 offset:10240
	ds_read_b128 v[158:161], v158 offset:2048
	ds_read_b128 v[174:177], v170 offset:12288
	ds_read_b128 v[170:173], v170 offset:14336
	v_mfma_f32_32x32x16_bf16 v[114:129], v[162:165], v[138:141], v[114:129]
	v_mfma_f32_32x32x16_bf16 v[98:113], v[166:169], v[138:141], v[98:113]
	v_mfma_f32_32x32x16_bf16 v[66:81], v[162:165], v[142:145], v[66:81]
	v_mfma_f32_32x32x16_bf16 v[34:49], v[166:169], v[142:145], v[34:49]
	v_mfma_f32_32x32x16_bf16 v[82:97], v[146:149], v[138:141], v[82:97]
	v_mfma_f32_32x32x16_bf16 v[50:65], v[150:153], v[138:141], v[50:65]
	v_mfma_f32_32x32x16_bf16 v[18:33], v[146:149], v[142:145], v[18:33]
	v_mfma_f32_32x32x16_bf16 v[2:17], v[150:153], v[142:145], v[2:17]
	s_add_i32 s23, s23, 2
	s_cmp_lg_u32 s23, 32
	s_cbranch_scc1 .LBB0_184
; DI unsigned pk2(float a, float b) { f32x2 v = {a, b}; bf2_t r = __builtin_convertvector(v, bf2_t); return __builtin_bit_cast(unsigned, r); }
;     ...
;   asm volatile("s_waitcnt vmcnt(0)" ::: "memory");
;   __builtin_amdgcn_s_barrier();
;   asm volatile("" ::: "memory");
;     ...
;   {
;     const int h = lane >> 5, cl = lane & 31;
; #pragma unroll
;     for (int i = 0; i < 2; ++i)
; #pragma unroll
;       for (int j = 0; j < 4; ++j)
; #pragma unroll
;         for (int g = 0; g < 4; ++g) {
;           u32x2 w; w.x = pk2(acc[i][j][4 * g], acc[i][j][4 * g + 1]); w.y = pk2(acc[i][j][4 * g + 2], acc[i][j][4 * g + 3]);
;           *(u32x2*)(smem + (wr * 64 + i * 32 + cl) * 528 + (wc * 128 + j * 32 + 8 * g + 4 * h) * 2) = w;
;         }
;   }
;   __syncthreads();
	s_waitcnt lgkmcnt(0)
	s_setprio 0
	v_mul_lo_u32 v0, v197, s55
	v_add_u32_e32 v0, 16, v0
	s_nop 1
	v_cvt_pk_bf16_f32 v114, v114, v115
	v_cvt_pk_bf16_f32 v115, v116, v117
	v_lshlrev_b32_e32 v116, 3, v196
	s_lshl_b32 s10, s21, 1
	v_add3_u32 v0, v0, v116, s10
	v_cvt_pk_bf16_f32 v116, v118, v119
	v_cvt_pk_bf16_f32 v117, v120, v121
	v_cvt_pk_bf16_f32 v98, v98, v99
	v_cvt_pk_bf16_f32 v99, v100, v101
	v_cvt_pk_bf16_f32 v100, v102, v103
	v_cvt_pk_bf16_f32 v101, v104, v105
	v_cvt_pk_bf16_f32 v82, v82, v83
	v_cvt_pk_bf16_f32 v83, v84, v85
	v_cvt_pk_bf16_f32 v84, v86, v87
	v_cvt_pk_bf16_f32 v85, v88, v89
	v_cvt_pk_bf16_f32 v50, v50, v51
	v_cvt_pk_bf16_f32 v51, v52, v53
	v_cvt_pk_bf16_f32 v52, v54, v55
	v_cvt_pk_bf16_f32 v53, v56, v57
	s_waitcnt vmcnt(0)
	s_barrier
	ds_write2_b64 v0, v[114:115], v[116:117] offset1:2
	v_cvt_pk_bf16_f32 v114, v122, v123
	v_cvt_pk_bf16_f32 v115, v124, v125
	v_cvt_pk_bf16_f32 v116, v126, v127
	v_cvt_pk_bf16_f32 v117, v128, v129
	ds_write2_b64 v0, v[98:99], v[100:101] offset0:8 offset1:10
	v_cvt_pk_bf16_f32 v98, v106, v107
	v_cvt_pk_bf16_f32 v99, v108, v109
	v_cvt_pk_bf16_f32 v100, v110, v111
	v_cvt_pk_bf16_f32 v101, v112, v113
	ds_write2_b64 v0, v[82:83], v[84:85] offset0:16 offset1:18
	v_cvt_pk_bf16_f32 v82, v90, v91
	v_cvt_pk_bf16_f32 v83, v92, v93
	v_cvt_pk_bf16_f32 v84, v94, v95
	v_cvt_pk_bf16_f32 v85, v96, v97
	ds_write2_b64 v0, v[50:51], v[52:53] offset0:24 offset1:26
	v_cvt_pk_bf16_f32 v50, v58, v59
	v_cvt_pk_bf16_f32 v51, v60, v61
	v_cvt_pk_bf16_f32 v52, v62, v63
	v_cvt_pk_bf16_f32 v53, v64, v65
	ds_write2_b64 v0, v[114:115], v[116:117] offset0:4 offset1:6
	ds_write2_b64 v0, v[98:99], v[100:101] offset0:12 offset1:14
	ds_write2_b64 v0, v[82:83], v[84:85] offset0:20 offset1:22
	ds_write2_b64 v0, v[50:51], v[52:53] offset0:28 offset1:30
	v_cvt_pk_bf16_f32 v50, v66, v67
	v_cvt_pk_bf16_f32 v51, v68, v69
	v_cvt_pk_bf16_f32 v52, v70, v71
	v_cvt_pk_bf16_f32 v53, v72, v73
	v_add_u32_e32 v0, 0x4000, v0
	v_cvt_pk_bf16_f32 v34, v34, v35
	v_cvt_pk_bf16_f32 v35, v36, v37
	v_cvt_pk_bf16_f32 v36, v38, v39
	v_cvt_pk_bf16_f32 v37, v40, v41
	v_cvt_pk_bf16_f32 v18, v18, v19
	v_cvt_pk_bf16_f32 v19, v20, v21
	v_cvt_pk_bf16_f32 v20, v22, v23
	v_cvt_pk_bf16_f32 v21, v24, v25
	v_cvt_pk_bf16_f32 v2, v2, v3
	v_cvt_pk_bf16_f32 v3, v4, v5
	v_cvt_pk_bf16_f32 v4, v6, v7
	v_cvt_pk_bf16_f32 v5, v8, v9
	ds_write2_b64 v0, v[50:51], v[52:53] offset0:64 offset1:66
	v_cvt_pk_bf16_f32 v50, v74, v75
	v_cvt_pk_bf16_f32 v51, v76, v77
	v_cvt_pk_bf16_f32 v52, v78, v79
	v_cvt_pk_bf16_f32 v53, v80, v81
	ds_write2_b64 v0, v[34:35], v[36:37] offset0:72 offset1:74
	v_cvt_pk_bf16_f32 v34, v42, v43
	v_cvt_pk_bf16_f32 v35, v44, v45
	v_cvt_pk_bf16_f32 v36, v46, v47
	v_cvt_pk_bf16_f32 v37, v48, v49
	ds_write2_b64 v0, v[18:19], v[20:21] offset0:80 offset1:82
	v_cvt_pk_bf16_f32 v18, v26, v27
	v_cvt_pk_bf16_f32 v19, v28, v29
	v_cvt_pk_bf16_f32 v20, v30, v31
	v_cvt_pk_bf16_f32 v21, v32, v33
	ds_write2_b64 v0, v[2:3], v[4:5] offset0:88 offset1:90
	v_cvt_pk_bf16_f32 v2, v10, v11
	v_cvt_pk_bf16_f32 v3, v12, v13
	v_cvt_pk_bf16_f32 v4, v14, v15
	v_cvt_pk_bf16_f32 v5, v16, v17
	s_lshl_b64 s[14:15], s[14:15], 1
	ds_write2_b64 v0, v[50:51], v[52:53] offset0:68 offset1:70
	ds_write2_b64 v0, v[34:35], v[36:37] offset0:76 offset1:78
	ds_write2_b64 v0, v[18:19], v[20:21] offset0:84 offset1:86
	ds_write2_b64 v0, v[2:3], v[4:5] offset0:92 offset1:94
	s_waitcnt vmcnt(0) lgkmcnt(0)
	s_barrier
; #define GAS __attribute__((address_space(1)))
;     ...
;   int tid2 = tid; asm volatile("" : "+v"(tid2));
;   if (EPI == 0) {
; #pragma unroll
;     for (int i = 0; i < 16; ++i) {
;       const int id = tid2 + 256 * i, r = id >> 5, c8 = (id & 31) * 8;
;       const u32x4 v = *(const u32x4*)(smem + r * 528 + c8 * 2);
;       *(GAS u32x4*)(ea.out + (size_t)(m0 + r) * ea.ldo + n0 + c8) = v;
;     }
	s_add_u32 s14, s16, s14
	v_lshlrev_b32_e32 v0, 4, v189
	v_and_b32_e32 v0, 0x1f0, v0
	s_addc_u32 s15, s17, s15
	v_add_u32_e32 v10, 16, v0
	v_lshl_add_u64 v[12:13], s[14:15], 0, v[0:1]
	v_ashrrev_i32_e32 v0, 5, v189
	v_mad_u64_u32 v[2:3], s[14:15], v0, s55, v[10:11]
	v_add_u32_e32 v0, s12, v0
	v_mad_i64_i32 v[14:15], s[14:15], v0, s35, v[12:13]
	v_add_u32_e32 v0, 0x100, v189
	ds_read_b128 v[2:5], v2
	v_ashrrev_i32_e32 v0, 5, v0
	v_mad_u64_u32 v[6:7], s[14:15], v0, s55, v[10:11]
	ds_read_b128 v[6:9], v6
	v_add_u32_e32 v0, s12, v0
	s_waitcnt lgkmcnt(1)
	global_store_dwordx4 v[14:15], v[2:5], off
	v_readlane_b32 s10, v252, 12
	s_add_i32 s20, s20, s10
	v_mad_i64_i32 v[2:3], s[14:15], v0, s35, v[12:13]
	v_add_u32_e32 v0, 0x200, v189
	v_ashrrev_i32_e32 v0, 5, v0
	s_waitcnt lgkmcnt(0)
	global_store_dwordx4 v[2:3], v[6:9], off
	v_mad_u64_u32 v[2:3], s[14:15], v0, s55, v[10:11]
	v_add_u32_e32 v0, s12, v0
	v_mad_i64_i32 v[14:15], s[14:15], v0, s35, v[12:13]
	v_add_u32_e32 v0, 0x300, v189
	ds_read_b128 v[2:5], v2
	v_ashrrev_i32_e32 v0, 5, v0
	v_mad_u64_u32 v[6:7], s[14:15], v0, s55, v[10:11]
	ds_read_b128 v[6:9], v6
	v_add_u32_e32 v0, s12, v0
	s_waitcnt lgkmcnt(1)
	global_store_dwordx4 v[14:15], v[2:5], off
	s_cmp_ge_i32 s20, s45
	s_nop 0
	v_mad_i64_i32 v[2:3], s[14:15], v0, s35, v[12:13]
	v_add_u32_e32 v0, 0x400, v189
	v_ashrrev_i32_e32 v0, 5, v0
	s_waitcnt lgkmcnt(0)
	global_store_dwordx4 v[2:3], v[6:9], off
	v_mad_u64_u32 v[2:3], s[14:15], v0, s55, v[10:11]
	v_add_u32_e32 v0, s12, v0
	v_mad_i64_i32 v[14:15], s[14:15], v0, s35, v[12:13]
	v_add_u32_e32 v0, 0x500, v189
	ds_read_b128 v[2:5], v2
	v_ashrrev_i32_e32 v0, 5, v0
	v_mad_u64_u32 v[6:7], s[14:15], v0, s55, v[10:11]
	ds_read_b128 v[6:9], v6
	v_add_u32_e32 v0, s12, v0
	s_waitcnt lgkmcnt(1)
	global_store_dwordx4 v[14:15], v[2:5], off
	s_nop 1
	v_mad_i64_i32 v[2:3], s[14:15], v0, s35, v[12:13]
	v_add_u32_e32 v0, 0x600, v189
	v_ashrrev_i32_e32 v0, 5, v0
	s_waitcnt lgkmcnt(0)
	global_store_dwordx4 v[2:3], v[6:9], off
	v_mad_u64_u32 v[2:3], s[14:15], v0, s55, v[10:11]
	v_add_u32_e32 v0, s12, v0
	v_mad_i64_i32 v[14:15], s[14:15], v0, s35, v[12:13]
	v_add_u32_e32 v0, 0x700, v189
	ds_read_b128 v[2:5], v2
	v_ashrrev_i32_e32 v0, 5, v0
	v_mad_u64_u32 v[6:7], s[14:15], v0, s55, v[10:11]
	ds_read_b128 v[6:9], v6
	v_add_u32_e32 v0, s12, v0
	s_waitcnt lgkmcnt(1)
	global_store_dwordx4 v[14:15], v[2:5], off
	s_nop 1
	v_mad_i64_i32 v[2:3], s[14:15], v0, s35, v[12:13]
	v_add_u32_e32 v0, 0x800, v189
	v_ashrrev_i32_e32 v0, 5, v0
	s_waitcnt lgkmcnt(0)
	global_store_dwordx4 v[2:3], v[6:9], off
	v_mad_u64_u32 v[2:3], s[14:15], v0, s55, v[10:11]
	v_add_u32_e32 v0, s12, v0
	v_mad_i64_i32 v[14:15], s[14:15], v0, s35, v[12:13]
	v_add_u32_e32 v0, 0x900, v189
	ds_read_b128 v[2:5], v2
	v_ashrrev_i32_e32 v0, 5, v0
	v_mad_u64_u32 v[6:7], s[14:15], v0, s55, v[10:11]
	ds_read_b128 v[6:9], v6
	v_add_u32_e32 v0, s12, v0
	s_waitcnt lgkmcnt(1)
	global_store_dwordx4 v[14:15], v[2:5], off
	s_nop 1
	v_mad_i64_i32 v[2:3], s[14:15], v0, s35, v[12:13]
	v_add_u32_e32 v0, 0xa00, v189
	v_ashrrev_i32_e32 v0, 5, v0
	s_waitcnt lgkmcnt(0)
	global_store_dwordx4 v[2:3], v[6:9], off
	v_mad_u64_u32 v[2:3], s[14:15], v0, s55, v[10:11]
	v_add_u32_e32 v0, s12, v0
	v_mad_i64_i32 v[14:15], s[14:15], v0, s35, v[12:13]
	v_add_u32_e32 v0, 0xb00, v189
	ds_read_b128 v[2:5], v2
	v_ashrrev_i32_e32 v0, 5, v0
	v_mad_u64_u32 v[6:7], s[14:15], v0, s55, v[10:11]
	ds_read_b128 v[6:9], v6
	v_add_u32_e32 v0, s12, v0
	s_waitcnt lgkmcnt(1)
	global_store_dwordx4 v[14:15], v[2:5], off
	s_nop 1
	v_mad_i64_i32 v[2:3], s[14:15], v0, s35, v[12:13]
	v_add_u32_e32 v0, 0xc00, v189
	v_ashrrev_i32_e32 v0, 5, v0
	s_waitcnt lgkmcnt(0)
	global_store_dwordx4 v[2:3], v[6:9], off
	v_mad_u64_u32 v[2:3], s[14:15], v0, s55, v[10:11]
	v_add_u32_e32 v0, s12, v0
	v_mad_i64_i32 v[14:15], s[14:15], v0, s35, v[12:13]
	v_add_u32_e32 v0, 0xd00, v189
	ds_read_b128 v[2:5], v2
	v_ashrrev_i32_e32 v0, 5, v0
	v_mad_u64_u32 v[6:7], s[14:15], v0, s55, v[10:11]
	ds_read_b128 v[6:9], v6
	v_add_u32_e32 v0, s12, v0
	s_waitcnt lgkmcnt(1)
	global_store_dwordx4 v[14:15], v[2:5], off
	s_nop 1
	v_mad_i64_i32 v[2:3], s[14:15], v0, s35, v[12:13]
	v_add_u32_e32 v0, 0xe00, v189
	v_ashrrev_i32_e32 v0, 5, v0
	s_waitcnt lgkmcnt(0)
	global_store_dwordx4 v[2:3], v[6:9], off
	v_mad_u64_u32 v[2:3], s[14:15], v0, s55, v[10:11]
	v_add_u32_e32 v0, s12, v0
	v_mad_i64_i32 v[14:15], s[14:15], v0, s35, v[12:13]
	v_add_u32_e32 v0, 0xf00, v189
	v_ashrrev_i32_e32 v0, 5, v0
	ds_read_b128 v[2:5], v2
	v_mad_u64_u32 v[6:7], s[14:15], v0, s55, v[10:11]
	ds_read_b128 v[6:9], v6
	v_add_u32_e32 v0, s12, v0
	s_waitcnt lgkmcnt(1)
	global_store_dwordx4 v[14:15], v[2:5], off
	s_nop 1
	v_mad_i64_i32 v[2:3], s[12:13], v0, s35, v[12:13]
	s_waitcnt lgkmcnt(0)
	global_store_dwordx4 v[2:3], v[6:9], off
	s_barrier
	s_cbranch_scc0 .LBB0_183
	v_mov_b64_e32 v[6:7], v[130:131]
	v_mov_b64_e32 v[2:3], v[134:135]
	v_mov_b32_e32 v31, v214
	v_mov_b32_e32 v30, v215
	v_mov_b32_e32 v29, v216
	v_mov_b32_e32 v28, v217
	v_mov_b64_e32 v[8:9], v[132:133]
	v_mov_b64_e32 v[4:5], v[136:137]
	v_readlane_b32 s44, v250, 17

; #define LAS __attribute__((address_space(3)))
;   int tid = tid_in; asm volatile("" : "+v"(tid));
;   const int lane = tid & 63, wid = __builtin_amdgcn_readfirstlane(tid >> 6), wr = wid >> 1, wc = wid & 1;
;   const int m0 = mt * 128, n0 = nt * 256;
;   const int r = lane & 31, h = lane >> 5, key = (r >> 2) & 3;
;   constexpr int STG = 24576;
;   const int rowl = lane >> 2, cch = (lane & 3) ^ ((lane >> 4) & 3);
;   const unsigned voffA = (unsigned)(rowl * lda * 2 + cch * 16), voffB = (unsigned)(rowl * K * 2 + cch * 16);
;   const char* Abase = (const char*)(A + (size_t)m0 * lda) + (size_t)(wid * 2) * 32 * lda;
;   const char* Bbase = (const char*)(Bt + (size_t)n0 * K) + (size_t)(wid * 4) * 32 * K;
;   const size_t ablk = (size_t)32 * lda, bblk = (size_t)32 * K;
;   LAS char* lds = (LAS char*)smem;
;   LAS char* ldsA = lds + (wid * 2) * 1024;
;   LAS char* ldsB = lds + 8192 + (wid * 4) * 1024;
;     ...
;   const int x0 = ((0 + h) ^ key) * 16, x1 = ((2 + h) ^ key) * 16;
;   const int a_rd = (wr * 64 + r) * 64, b_rd = 8192 + (wc * 128 + r) * 64;
;   f32x16 acc[2][4];
; #pragma unroll
;   for (int i = 0; i < 2; ++i)
; #pragma unroll
;     for (int j = 0; j < 4; ++j)
; #pragma unroll
;       for (int e = 0; e < 16; ++e) acc[i][j][e] = 0.f;
;   const int nk = K >> 5;
;   DMA_STEP_(0, 0);
;   DMA_STEP_(1, STG);
;   asm volatile("s_waitcnt vmcnt(6)" ::: "memory");
;   __builtin_amdgcn_s_barrier();
;   asm volatile("" ::: "memory");
;   int s0 = 0, s2 = 2 * STG;
;   for (int kt = 0; kt < nk; ++kt) {
;     const int kn = (kt + 2 < nk) ? (kt + 2) : (nk - 1);
;     const LAS char* cur = lds + s0;
;     bf16x8 af[2][2], bfr[2][4];
; #pragma unroll
;     for (int kk = 0; kk < 2; ++kk) {
;       const int xo = kk ? x1 : x0;
;       af[kk][0] = *(const LAS bf16x8*)(cur + a_rd + xo);
;       bfr[kk][0] = *(const LAS bf16x8*)(cur + b_rd + xo);
;       bfr[kk][1] = *(const LAS bf16x8*)(cur + b_rd + 2048 + xo);
;       af[kk][1] = *(const LAS bf16x8*)(cur + a_rd + 2048 + xo);
;       bfr[kk][2] = *(const LAS bf16x8*)(cur + b_rd + 4096 + xo);
;       bfr[kk][3] = *(const LAS bf16x8*)(cur + b_rd + 6144 + xo);
;     }
.LBB0_234:
	v_mov_b32_e32 v189, v188
	s_lshl_b32 s12, s23, 7
	v_readfirstlane_b32 s42, v189
	s_ashr_i32 s44, s42, 6
	s_lshl_b32 s28, s44, 2
	s_ashr_i32 s29, s28, 31
	s_lshl_b32 s23, s44, 12
	s_lshl_b64 s[40:41], s[28:29], 10
	s_add_i32 s28, s23, 16
	s_ashr_i32 s23, s42, 1
	v_and_b32_e32 v0, 31, v189
	s_andn2_b32 s23, s23, 63
	v_lshlrev_b32_e32 v2, 4, v189
	s_lshl_b32 s10, s44, 1
	v_or_b32_e32 v197, s23, v0
	s_lshl_b32 s23, s44, 7
	v_bitop3_b32 v2, v2, 48, v189 bitop3:0x48
	v_lshlrev_b32_e32 v3, 9, v189
	s_ashr_i32 s13, s12, 31
	s_ashr_i32 s11, s10, 31
	s_and_b32 s23, s23, 0x80
	s_movk_i32 s42, 0x7800
	s_lshl_b64 s[10:11], s[10:11], 10
	s_add_i32 s29, s28, 0x2000
	v_or_b32_e32 v4, s23, v0
	v_and_or_b32 v0, v3, s42, v2
	v_lshlrev_b32_e32 v10, 4, v189
	v_and_b32_e32 v10, 0x3c0, v10
	v_or_b32_e32 v10, v10, v2
	v_mov_b32_e32 v11, 0
	s_lshl_b64 s[42:43], s[12:13], 6
	s_add_u32 s13, s18, s42
	s_addc_u32 s42, s19, s43
	s_add_u32 s10, s13, s10
	s_addc_u32 s11, s42, s11
	s_lshl_b64 s[42:43], s[14:15], 6
	s_add_u32 s13, s20, s42
	s_addc_u32 s42, s21, s43
	s_add_u32 s40, s13, s40
	s_addc_u32 s41, s42, s41
	s_lshl_b32 s13, s44, 11
	s_sub_i32 s13, s28, s13
	v_lshl_add_u64 v[192:193], s[10:11], 0, v[10:11]
	s_mov_b32 m0, s13
	s_nop 0
	global_load_lds_dwordx4 v[192:193], off
	global_load_lds_dwordx4 v[192:193], off offset:1024
	v_lshl_add_u64 v[194:195], s[40:41], 0, v[10:11]
	s_mov_b32 m0, s29
	s_nop 0
	global_load_lds_dwordx4 v[194:195], off
	global_load_lds_dwordx4 v[194:195], off offset:1024
	global_load_lds_dwordx4 v[194:195], off offset:2048
	global_load_lds_dwordx4 v[194:195], off offset:3072
	s_mov_b64 s[10:11], 0x10000
	s_mov_b64 s[10:11], 0x18000
	s_mov_b64 s[10:11], 0x8040
	s_add_i32 m0, s13, 0x6000
	s_mov_b32 vcc_lo, 0x480000
	s_mov_b32 vcc_hi, 0
	v_lshl_add_u64 v[2:3], v[192:193], 0, vcc
	global_load_lds_dwordx4 v[2:3], off
	global_load_lds_dwordx4 v[2:3], off offset:1024
	v_bfe_u32 v196, v189, 5, 1
	s_add_i32 m0, s28, 0x8000
	s_mov_b32 s100, 0x24000
	v_lshl_add_u64 v[2:3], v[194:195], 0, s[100:101]
	global_load_lds_dwordx4 v[2:3], off
	global_load_lds_dwordx4 v[2:3], off offset:1024
	global_load_lds_dwordx4 v[2:3], off offset:2048
	global_load_lds_dwordx4 v[2:3], off offset:3072
	s_mov_b64 s[10:11], 0x10040
	s_mov_b64 s[10:11], 0x18040
	v_lshlrev_b32_e32 v218, 6, v4
	v_bfe_u32 v4, v189, 2, 2
	v_lshrrev_b32_e32 v5, 5, v189
	s_lshl_b32 s100, s100, 1
	v_lshl_add_u64 v[194:195], v[194:195], 0, s[100:101]
	s_lshl_b32 vcc_lo, vcc_lo, 1
	v_lshl_add_u64 v[192:193], v[192:193], 0, vcc
	s_waitcnt vmcnt(6)
	s_barrier
	v_bitop3_b32 v2, v196, v4, 2 bitop3:0x36
	v_bitop3_b32 v0, v5, v4, 1 bitop3:0x6c
	v_lshlrev_b32_e32 v220, 4, v2
	v_mov_b32_e32 v2, 0
	v_lshlrev_b32_e32 v219, 6, v197
	v_lshlrev_b32_e32 v0, 4, v0
	s_mov_b32 s40, 0xc000
	s_mov_b32 s29, 0
	s_mov_b32 s41, 0
	v_mov_b32_e32 v3, v2
	v_mov_b32_e32 v4, v2
	v_mov_b32_e32 v5, v2
	v_mov_b32_e32 v6, v2
	v_mov_b32_e32 v7, v2
	v_mov_b32_e32 v8, v2
	v_mov_b32_e32 v9, v2
	v_mov_b32_e32 v10, v2
	v_mov_b32_e32 v11, v2
	v_mov_b32_e32 v12, v2
	v_mov_b32_e32 v13, v2
	v_mov_b32_e32 v14, v2
	v_mov_b32_e32 v15, v2
	v_mov_b32_e32 v16, v2
	v_mov_b32_e32 v17, v2
	v_mov_b32_e32 v18, v2
	v_mov_b32_e32 v19, v2
	v_mov_b32_e32 v20, v2
	v_mov_b32_e32 v21, v2
	v_mov_b32_e32 v22, v2
	v_mov_b32_e32 v23, v2
	v_mov_b32_e32 v24, v2
	v_mov_b32_e32 v25, v2
	v_mov_b32_e32 v26, v2
	v_mov_b32_e32 v27, v2
	v_mov_b32_e32 v28, v2
	v_mov_b32_e32 v29, v2
	v_mov_b32_e32 v30, v2
	v_mov_b32_e32 v31, v2
	v_mov_b32_e32 v32, v2
	v_mov_b32_e32 v33, v2
	v_mov_b32_e32 v50, v2
	v_mov_b32_e32 v51, v2
	v_mov_b32_e32 v52, v2
	v_mov_b32_e32 v53, v2
	v_mov_b32_e32 v54, v2
	v_mov_b32_e32 v55, v2
	v_mov_b32_e32 v56, v2
	v_mov_b32_e32 v57, v2
	v_mov_b32_e32 v58, v2
	v_mov_b32_e32 v59, v2
	v_mov_b32_e32 v60, v2
	v_mov_b32_e32 v61, v2
	v_mov_b32_e32 v62, v2
	v_mov_b32_e32 v63, v2
	v_mov_b32_e32 v64, v2
	v_mov_b32_e32 v65, v2
	v_mov_b32_e32 v82, v2
	v_mov_b32_e32 v83, v2
	v_mov_b32_e32 v84, v2
	v_mov_b32_e32 v85, v2
	v_mov_b32_e32 v86, v2
	v_mov_b32_e32 v87, v2
	v_mov_b32_e32 v88, v2
	v_mov_b32_e32 v89, v2
	v_mov_b32_e32 v90, v2
	v_mov_b32_e32 v91, v2
	v_mov_b32_e32 v92, v2
	v_mov_b32_e32 v93, v2
	v_mov_b32_e32 v94, v2
	v_mov_b32_e32 v95, v2
	v_mov_b32_e32 v96, v2
	v_mov_b32_e32 v97, v2
	v_mov_b32_e32 v34, v2
	v_mov_b32_e32 v35, v2
	v_mov_b32_e32 v36, v2
	v_mov_b32_e32 v37, v2
	v_mov_b32_e32 v38, v2
	v_mov_b32_e32 v39, v2
	v_mov_b32_e32 v40, v2
	v_mov_b32_e32 v41, v2
	v_mov_b32_e32 v42, v2
	v_mov_b32_e32 v43, v2
	v_mov_b32_e32 v44, v2
	v_mov_b32_e32 v45, v2
	v_mov_b32_e32 v46, v2
	v_mov_b32_e32 v47, v2
	v_mov_b32_e32 v48, v2
	v_mov_b32_e32 v49, v2
	v_mov_b32_e32 v66, v2
	v_mov_b32_e32 v67, v2
	v_mov_b32_e32 v68, v2
	v_mov_b32_e32 v69, v2
	v_mov_b32_e32 v70, v2
	v_mov_b32_e32 v71, v2
	v_mov_b32_e32 v72, v2
	v_mov_b32_e32 v73, v2
	v_mov_b32_e32 v74, v2
	v_mov_b32_e32 v75, v2
	v_mov_b32_e32 v76, v2
	v_mov_b32_e32 v77, v2
	v_mov_b32_e32 v78, v2
	v_mov_b32_e32 v79, v2
	v_mov_b32_e32 v80, v2
	v_mov_b32_e32 v81, v2
	v_mov_b32_e32 v98, v2
	v_mov_b32_e32 v99, v2
	v_mov_b32_e32 v100, v2
	v_mov_b32_e32 v101, v2
	v_mov_b32_e32 v102, v2
	v_mov_b32_e32 v103, v2
	v_mov_b32_e32 v104, v2
	v_mov_b32_e32 v105, v2
	v_mov_b32_e32 v106, v2
	v_mov_b32_e32 v107, v2
	v_mov_b32_e32 v108, v2
	v_mov_b32_e32 v109, v2
	v_mov_b32_e32 v110, v2
	v_mov_b32_e32 v111, v2
	v_mov_b32_e32 v112, v2
	v_mov_b32_e32 v113, v2
	v_mov_b32_e32 v114, v2
	v_mov_b32_e32 v115, v2
	v_mov_b32_e32 v116, v2
	v_mov_b32_e32 v117, v2
	v_mov_b32_e32 v118, v2
	v_mov_b32_e32 v119, v2
	v_mov_b32_e32 v120, v2
	v_mov_b32_e32 v121, v2
	v_mov_b32_e32 v122, v2
	v_mov_b32_e32 v123, v2
	v_mov_b32_e32 v124, v2
	v_mov_b32_e32 v125, v2
	v_mov_b32_e32 v126, v2
	v_mov_b32_e32 v127, v2
	v_mov_b32_e32 v128, v2
	v_mov_b32_e32 v129, v2
	s_mov_b32 vcc_hi, 0
	v_add_u32_e32 v158, 16, v219
	v_add_u32_e32 v170, 16, v218
	v_add_u32_e32 v158, v158, v0
	v_add_u32_e32 v170, v170, v0
	ds_read_b128 v[154:157], v158
	ds_read_b128 v[182:185], v170 offset:8192
	ds_read_b128 v[178:181], v170 offset:10240
	ds_read_b128 v[158:161], v158 offset:2048
	ds_read_b128 v[174:177], v170 offset:12288
	ds_read_b128 v[170:173], v170 offset:14336
	s_setprio 1
; #define LAS __attribute__((address_space(3)))
; DI f32x16 mfma32(bf16x8 a, bf16x8 b, f32x16 c) { return __builtin_amdgcn_mfma_f32_32x32x16_bf16(a, b, c, 0, 0, 0); }
;     ...
;   for (int kt = 0; kt < nk; ++kt) {
;     const int kn = (kt + 2 < nk) ? (kt + 2) : (nk - 1);
;     const LAS char* cur = lds + s0;
;     bf16x8 af[2][2], bfr[2][4];
; #pragma unroll
;     for (int kk = 0; kk < 2; ++kk) {
;       const int xo = kk ? x1 : x0;
;       af[kk][0] = *(const LAS bf16x8*)(cur + a_rd + xo);
;       bfr[kk][0] = *(const LAS bf16x8*)(cur + b_rd + xo);
;       bfr[kk][1] = *(const LAS bf16x8*)(cur + b_rd + 2048 + xo);
;       af[kk][1] = *(const LAS bf16x8*)(cur + a_rd + 2048 + xo);
;       bfr[kk][2] = *(const LAS bf16x8*)(cur + b_rd + 4096 + xo);
;       bfr[kk][3] = *(const LAS bf16x8*)(cur + b_rd + 6144 + xo);
;     }
;     DMA_STEP_(kn, s2);
; #pragma unroll
;     for (int kk = 0; kk < 2; ++kk) {
;       acc[0][0] = mfma32(bfr[kk][0], af[kk][0], acc[0][0]); acc[0][1] = mfma32(bfr[kk][1], af[kk][0], acc[0][1]);
;       acc[1][0] = mfma32(bfr[kk][0], af[kk][1], acc[1][0]); acc[1][1] = mfma32(bfr[kk][1], af[kk][1], acc[1][1]);
;       acc[0][2] = mfma32(bfr[kk][2], af[kk][0], acc[0][2]); acc[0][3] = mfma32(bfr[kk][3], af[kk][0], acc[0][3]);
;       acc[1][2] = mfma32(bfr[kk][2], af[kk][1], acc[1][2]); acc[1][3] = mfma32(bfr[kk][3], af[kk][1], acc[1][3]);
;     }
;     __builtin_amdgcn_sched_group_barrier(0x100, 12, 0);
;     __builtin_amdgcn_sched_group_barrier(0x010, 6, 0);
;     __builtin_amdgcn_sched_group_barrier(0x008, 16, 0);
;     asm volatile("s_waitcnt vmcnt(6) lgkmcnt(0)" ::: "memory");
;     __builtin_amdgcn_s_barrier();
;     asm volatile("" ::: "memory");
;     s0 = (s0 == 2 * STG) ? 0 : s0 + STG;
;     s2 = (s2 == 2 * STG) ? 0 : s2 + STG;
;   }
.LBB0_235:
	s_add_i32 s11, s41, 16
	s_mov_b32 s10, s29
	v_add_u32_e32 v142, s11, v219
	v_add_u32_e32 v150, s11, v218
	s_min_u32 s10, s10, 29
	v_add_u32_e32 v142, v142, v220
	v_add_u32_e32 v150, v150, v220
	s_lshl_b32 s70, s10, 6
	ds_read_b128 v[138:141], v142
	ds_read_b128 v[162:165], v150 offset:8192
	ds_read_b128 v[166:169], v150 offset:10240
	ds_read_b128 v[142:145], v142 offset:2048
	ds_read_b128 v[146:149], v150 offset:12288
	ds_read_b128 v[150:153], v150 offset:14336
	s_mul_i32 vcc_lo, s70, 0x12000
	s_add_i32 s10, s13, s40
	v_lshl_add_u64 v[222:223], v[192:193], 0, vcc
	s_mov_b32 m0, s10
	s_mul_i32 s100, s70, 0x900
	v_lshl_add_u64 v[224:225], v[194:195], 0, s[100:101]
	s_add_i32 s10, s28, s40
	s_waitcnt lgkmcnt(6)
	v_mfma_f32_32x32x16_bf16 v[114:129], v[182:185], v[154:157], v[114:129]
	global_load_lds_dwordx4 v[222:223], off
	v_mfma_f32_32x32x16_bf16 v[98:113], v[178:181], v[154:157], v[98:113]
	global_load_lds_dwordx4 v[222:223], off offset:1024
	s_add_i32 m0, s10, 0x2000
	v_mfma_f32_32x32x16_bf16 v[66:81], v[182:185], v[158:161], v[66:81]
	global_load_lds_dwordx4 v[224:225], off
	v_mfma_f32_32x32x16_bf16 v[34:49], v[178:181], v[158:161], v[34:49]
	global_load_lds_dwordx4 v[224:225], off offset:1024
	v_mfma_f32_32x32x16_bf16 v[82:97], v[174:177], v[154:157], v[82:97]
	global_load_lds_dwordx4 v[224:225], off offset:2048
	v_mfma_f32_32x32x16_bf16 v[50:65], v[170:173], v[154:157], v[50:65]
	global_load_lds_dwordx4 v[224:225], off offset:3072
	v_mfma_f32_32x32x16_bf16 v[18:33], v[174:177], v[158:161], v[18:33]
	s_add_i32 s10, s41, 0x6000
	s_cmpk_lg_u32 s41, 0xc000
	s_cselect_b32 s41, s10, 0
	s_add_i32 s10, s40, 0x6000
	s_cmpk_lg_u32 s40, 0xc000
	s_cselect_b32 s40, s10, 0
	v_mfma_f32_32x32x16_bf16 v[2:17], v[170:173], v[158:161], v[2:17]
	s_add_i32 s11, s41, 16
	s_waitcnt vmcnt(6) lgkmcnt(0)
	s_barrier
	v_add_u32_e32 v158, s11, v219
	v_add_u32_e32 v170, s11, v218
	v_add_u32_e32 v158, v158, v0
	v_add_u32_e32 v170, v170, v0
	ds_read_b128 v[154:157], v158
	ds_read_b128 v[182:185], v170 offset:8192
	ds_read_b128 v[178:181], v170 offset:10240
	ds_read_b128 v[158:161], v158 offset:2048
	ds_read_b128 v[174:177], v170 offset:12288
	ds_read_b128 v[170:173], v170 offset:14336
	v_mfma_f32_32x32x16_bf16 v[114:129], v[162:165], v[138:141], v[114:129]
	v_mfma_f32_32x32x16_bf16 v[98:113], v[166:169], v[138:141], v[98:113]
	v_mfma_f32_32x32x16_bf16 v[66:81], v[162:165], v[142:145], v[66:81]
	v_mfma_f32_32x32x16_bf16 v[34:49], v[166:169], v[142:145], v[34:49]
	v_mfma_f32_32x32x16_bf16 v[82:97], v[146:149], v[138:141], v[82:97]
	v_mfma_f32_32x32x16_bf16 v[50:65], v[150:153], v[138:141], v[50:65]
	v_mfma_f32_32x32x16_bf16 v[18:33], v[146:149], v[142:145], v[18:33]
	v_mfma_f32_32x32x16_bf16 v[2:17], v[150:153], v[142:145], v[2:17]
	s_add_i32 s11, s41, 16
	s_add_i32 s10, s29, 1
	v_add_u32_e32 v142, s11, v219
	v_add_u32_e32 v150, s11, v218
	s_min_u32 s10, s10, 29
	v_add_u32_e32 v142, v142, v220
	v_add_u32_e32 v150, v150, v220
	s_lshl_b32 s70, s10, 6
	ds_read_b128 v[138:141], v142
	ds_read_b128 v[162:165], v150 offset:8192
	ds_read_b128 v[166:169], v150 offset:10240
	ds_read_b128 v[142:145], v142 offset:2048
	ds_read_b128 v[146:149], v150 offset:12288
	ds_read_b128 v[150:153], v150 offset:14336
	s_mul_i32 vcc_lo, s70, 0x12000
	s_add_i32 s10, s13, s40
	v_lshl_add_u64 v[222:223], v[192:193], 0, vcc
	s_mov_b32 m0, s10
	s_mul_i32 s100, s70, 0x900
	v_lshl_add_u64 v[224:225], v[194:195], 0, s[100:101]
	s_add_i32 s10, s28, s40
	s_waitcnt lgkmcnt(6)
	v_mfma_f32_32x32x16_bf16 v[114:129], v[182:185], v[154:157], v[114:129]
	global_load_lds_dwordx4 v[222:223], off
	v_mfma_f32_32x32x16_bf16 v[98:113], v[178:181], v[154:157], v[98:113]
	global_load_lds_dwordx4 v[222:223], off offset:1024
	s_add_i32 m0, s10, 0x2000
	v_mfma_f32_32x32x16_bf16 v[66:81], v[182:185], v[158:161], v[66:81]
	global_load_lds_dwordx4 v[224:225], off
	v_mfma_f32_32x32x16_bf16 v[34:49], v[178:181], v[158:161], v[34:49]
	global_load_lds_dwordx4 v[224:225], off offset:1024
	v_mfma_f32_32x32x16_bf16 v[82:97], v[174:177], v[154:157], v[82:97]
	global_load_lds_dwordx4 v[224:225], off offset:2048
	v_mfma_f32_32x32x16_bf16 v[50:65], v[170:173], v[154:157], v[50:65]
	global_load_lds_dwordx4 v[224:225], off offset:3072
	v_mfma_f32_32x32x16_bf16 v[18:33], v[174:177], v[158:161], v[18:33]
	s_add_i32 s10, s41, 0x6000
	s_cmpk_lg_u32 s41, 0xc000
	s_cselect_b32 s41, s10, 0
	s_add_i32 s10, s40, 0x6000
	s_cmpk_lg_u32 s40, 0xc000
	s_cselect_b32 s40, s10, 0
	v_mfma_f32_32x32x16_bf16 v[2:17], v[170:173], v[158:161], v[2:17]
	s_add_i32 s11, s41, 16
	s_waitcnt vmcnt(6) lgkmcnt(0)
	s_barrier
	v_add_u32_e32 v158, s11, v219
	v_add_u32_e32 v170, s11, v218
	v_add_u32_e32 v158, v158, v0
	v_add_u32_e32 v170, v170, v0
	ds_read_b128 v[154:157], v158
	ds_read_b128 v[182:185], v170 offset:8192
	ds_read_b128 v[178:181], v170 offset:10240
	ds_read_b128 v[158:161], v158 offset:2048
	ds_read_b128 v[174:177], v170 offset:12288
	ds_read_b128 v[170:173], v170 offset:14336
	v_mfma_f32_32x32x16_bf16 v[114:129], v[162:165], v[138:141], v[114:129]
	v_mfma_f32_32x32x16_bf16 v[98:113], v[166:169], v[138:141], v[98:113]
	v_mfma_f32_32x32x16_bf16 v[66:81], v[162:165], v[142:145], v[66:81]
	v_mfma_f32_32x32x16_bf16 v[34:49], v[166:169], v[142:145], v[34:49]
	v_mfma_f32_32x32x16_bf16 v[82:97], v[146:149], v[138:141], v[82:97]
	v_mfma_f32_32x32x16_bf16 v[50:65], v[150:153], v[138:141], v[50:65]
	v_mfma_f32_32x32x16_bf16 v[18:33], v[146:149], v[142:145], v[18:33]
	v_mfma_f32_32x32x16_bf16 v[2:17], v[150:153], v[142:145], v[2:17]
	s_add_i32 s29, s29, 2
	s_cmp_lg_u32 s29, 32
	s_cbranch_scc1 .LBB0_235
; DI unsigned pk2(float a, float b) { f32x2 v = {a, b}; bf2_t r = __builtin_convertvector(v, bf2_t); return __builtin_bit_cast(unsigned, r); }
;     ...
;   asm volatile("s_waitcnt vmcnt(0)" ::: "memory");
;   __builtin_amdgcn_s_barrier();
;   asm volatile("" ::: "memory");
;     ...
;   {
;     const int h = lane >> 5, cl = lane & 31;
; #pragma unroll
;     for (int i = 0; i < 2; ++i)
; #pragma unroll
;       for (int j = 0; j < 4; ++j)
; #pragma unroll
;         for (int g = 0; g < 4; ++g) {
;           u32x2 w; w.x = pk2(acc[i][j][4 * g], acc[i][j][4 * g + 1]); w.y = pk2(acc[i][j][4 * g + 2], acc[i][j][4 * g + 3]);
;           *(u32x2*)(smem + (wr * 64 + i * 32 + cl) * 528 + (wc * 128 + j * 32 + 8 * g + 4 * h) * 2) = w;
;         }
;   }
;   __syncthreads();
	s_waitcnt lgkmcnt(0)
	s_setprio 0
	v_mul_lo_u32 v0, v197, s55
	v_add_u32_e32 v0, 16, v0
	s_nop 1
	v_cvt_pk_bf16_f32 v114, v114, v115
	v_cvt_pk_bf16_f32 v115, v116, v117
	v_lshlrev_b32_e32 v116, 3, v196
	s_lshl_b32 s10, s23, 1
	v_add3_u32 v0, v0, v116, s10
	v_cvt_pk_bf16_f32 v116, v118, v119
	v_cvt_pk_bf16_f32 v117, v120, v121
	v_cvt_pk_bf16_f32 v98, v98, v99
	v_cvt_pk_bf16_f32 v99, v100, v101
	v_cvt_pk_bf16_f32 v100, v102, v103
	v_cvt_pk_bf16_f32 v101, v104, v105
	v_cvt_pk_bf16_f32 v82, v82, v83
	v_cvt_pk_bf16_f32 v83, v84, v85
	v_cvt_pk_bf16_f32 v84, v86, v87
	v_cvt_pk_bf16_f32 v85, v88, v89
	v_cvt_pk_bf16_f32 v50, v50, v51
	v_cvt_pk_bf16_f32 v51, v52, v53
	v_cvt_pk_bf16_f32 v52, v54, v55
	v_cvt_pk_bf16_f32 v53, v56, v57
	s_waitcnt vmcnt(0)
	s_barrier
	ds_write2_b64 v0, v[114:115], v[116:117] offset1:2
	v_cvt_pk_bf16_f32 v114, v122, v123
	v_cvt_pk_bf16_f32 v115, v124, v125
	v_cvt_pk_bf16_f32 v116, v126, v127
	v_cvt_pk_bf16_f32 v117, v128, v129
	ds_write2_b64 v0, v[98:99], v[100:101] offset0:8 offset1:10
	v_cvt_pk_bf16_f32 v98, v106, v107
	v_cvt_pk_bf16_f32 v99, v108, v109
	v_cvt_pk_bf16_f32 v100, v110, v111
	v_cvt_pk_bf16_f32 v101, v112, v113
	ds_write2_b64 v0, v[82:83], v[84:85] offset0:16 offset1:18
	v_cvt_pk_bf16_f32 v82, v90, v91
	v_cvt_pk_bf16_f32 v83, v92, v93
	v_cvt_pk_bf16_f32 v84, v94, v95
	v_cvt_pk_bf16_f32 v85, v96, v97
	ds_write2_b64 v0, v[50:51], v[52:53] offset0:24 offset1:26
	v_cvt_pk_bf16_f32 v50, v58, v59
	v_cvt_pk_bf16_f32 v51, v60, v61
	v_cvt_pk_bf16_f32 v52, v62, v63
	v_cvt_pk_bf16_f32 v53, v64, v65
	ds_write2_b64 v0, v[114:115], v[116:117] offset0:4 offset1:6
	ds_write2_b64 v0, v[98:99], v[100:101] offset0:12 offset1:14
	ds_write2_b64 v0, v[82:83], v[84:85] offset0:20 offset1:22
	ds_write2_b64 v0, v[50:51], v[52:53] offset0:28 offset1:30
	v_cvt_pk_bf16_f32 v50, v66, v67
	v_cvt_pk_bf16_f32 v51, v68, v69
	v_cvt_pk_bf16_f32 v52, v70, v71
	v_cvt_pk_bf16_f32 v53, v72, v73
	v_add_u32_e32 v0, 0x4000, v0
	v_cvt_pk_bf16_f32 v34, v34, v35
	v_cvt_pk_bf16_f32 v35, v36, v37
	v_cvt_pk_bf16_f32 v36, v38, v39
	v_cvt_pk_bf16_f32 v37, v40, v41
	v_cvt_pk_bf16_f32 v18, v18, v19
	v_cvt_pk_bf16_f32 v19, v20, v21
	v_cvt_pk_bf16_f32 v20, v22, v23
	v_cvt_pk_bf16_f32 v21, v24, v25
	v_cvt_pk_bf16_f32 v2, v2, v3
	v_cvt_pk_bf16_f32 v3, v4, v5
	v_cvt_pk_bf16_f32 v4, v6, v7
	v_cvt_pk_bf16_f32 v5, v8, v9
	ds_write2_b64 v0, v[50:51], v[52:53] offset0:64 offset1:66
	v_cvt_pk_bf16_f32 v50, v74, v75
	v_cvt_pk_bf16_f32 v51, v76, v77
	v_cvt_pk_bf16_f32 v52, v78, v79
	v_cvt_pk_bf16_f32 v53, v80, v81
	ds_write2_b64 v0, v[34:35], v[36:37] offset0:72 offset1:74
	v_cvt_pk_bf16_f32 v34, v42, v43
	v_cvt_pk_bf16_f32 v35, v44, v45
	v_cvt_pk_bf16_f32 v36, v46, v47
	v_cvt_pk_bf16_f32 v37, v48, v49
	ds_write2_b64 v0, v[18:19], v[20:21] offset0:80 offset1:82
	v_cvt_pk_bf16_f32 v18, v26, v27
	v_cvt_pk_bf16_f32 v19, v28, v29
	v_cvt_pk_bf16_f32 v20, v30, v31
	v_cvt_pk_bf16_f32 v21, v32, v33
	ds_write2_b64 v0, v[2:3], v[4:5] offset0:88 offset1:90
	v_cvt_pk_bf16_f32 v2, v10, v11
	v_cvt_pk_bf16_f32 v3, v12, v13
	v_cvt_pk_bf16_f32 v4, v14, v15
	v_cvt_pk_bf16_f32 v5, v16, v17
	s_lshl_b64 s[10:11], s[14:15], 1
	ds_write2_b64 v0, v[50:51], v[52:53] offset0:68 offset1:70
	ds_write2_b64 v0, v[34:35], v[36:37] offset0:76 offset1:78
	ds_write2_b64 v0, v[18:19], v[20:21] offset0:84 offset1:86
	ds_write2_b64 v0, v[2:3], v[4:5] offset0:92 offset1:94
	s_waitcnt vmcnt(0) lgkmcnt(0)
	s_barrier
; #define GAS __attribute__((address_space(1)))
;     ...
;   int tid2 = tid; asm volatile("" : "+v"(tid2));
;   if (EPI == 0) {
; #pragma unroll
;     for (int i = 0; i < 16; ++i) {
;       const int id = tid2 + 256 * i, r = id >> 5, c8 = (id & 31) * 8;
;       const u32x4 v = *(const u32x4*)(smem + r * 528 + c8 * 2);
;       *(GAS u32x4*)(ea.out + (size_t)(m0 + r) * ea.ldo + n0 + c8) = v;
;     }
	s_add_u32 s10, s16, s10
	v_lshlrev_b32_e32 v0, 4, v189
	v_and_b32_e32 v0, 0x1f0, v0
	s_addc_u32 s11, s17, s11
	v_add_u32_e32 v10, 16, v0
	v_lshl_add_u64 v[12:13], s[10:11], 0, v[0:1]
	v_ashrrev_i32_e32 v0, 5, v189
	v_mad_u64_u32 v[2:3], s[10:11], v0, s55, v[10:11]
	v_add_u32_e32 v0, s12, v0
	v_mad_i64_i32 v[14:15], s[10:11], v0, s35, v[12:13]
	v_add_u32_e32 v0, 0x100, v189
	ds_read_b128 v[2:5], v2
	v_ashrrev_i32_e32 v0, 5, v0
	v_mad_u64_u32 v[6:7], s[10:11], v0, s55, v[10:11]
	ds_read_b128 v[6:9], v6
	v_add_u32_e32 v0, s12, v0
	s_waitcnt lgkmcnt(1)
	global_store_dwordx4 v[14:15], v[2:5], off
	s_nop 1
	v_mad_i64_i32 v[2:3], s[10:11], v0, s35, v[12:13]
	v_add_u32_e32 v0, 0x200, v189
	v_ashrrev_i32_e32 v0, 5, v0
	s_waitcnt lgkmcnt(0)
	global_store_dwordx4 v[2:3], v[6:9], off
	v_mad_u64_u32 v[2:3], s[10:11], v0, s55, v[10:11]
	v_add_u32_e32 v0, s12, v0
	v_mad_i64_i32 v[14:15], s[10:11], v0, s35, v[12:13]
	v_add_u32_e32 v0, 0x300, v189
	ds_read_b128 v[2:5], v2
	v_ashrrev_i32_e32 v0, 5, v0
	v_mad_u64_u32 v[6:7], s[10:11], v0, s55, v[10:11]
	ds_read_b128 v[6:9], v6
	v_add_u32_e32 v0, s12, v0
	s_waitcnt lgkmcnt(1)
	global_store_dwordx4 v[14:15], v[2:5], off
	s_nop 1
	v_mad_i64_i32 v[2:3], s[10:11], v0, s35, v[12:13]
	v_add_u32_e32 v0, 0x400, v189
	v_ashrrev_i32_e32 v0, 5, v0
	s_waitcnt lgkmcnt(0)
	global_store_dwordx4 v[2:3], v[6:9], off
	v_mad_u64_u32 v[2:3], s[10:11], v0, s55, v[10:11]
	v_add_u32_e32 v0, s12, v0
	v_mad_i64_i32 v[14:15], s[10:11], v0, s35, v[12:13]
	v_add_u32_e32 v0, 0x500, v189
	ds_read_b128 v[2:5], v2
	v_ashrrev_i32_e32 v0, 5, v0
	v_mad_u64_u32 v[6:7], s[10:11], v0, s55, v[10:11]
	ds_read_b128 v[6:9], v6
	v_add_u32_e32 v0, s12, v0
	s_waitcnt lgkmcnt(1)
	global_store_dwordx4 v[14:15], v[2:5], off
	s_nop 1
	v_mad_i64_i32 v[2:3], s[10:11], v0, s35, v[12:13]
	v_add_u32_e32 v0, 0x600, v189
	v_ashrrev_i32_e32 v0, 5, v0
	s_waitcnt lgkmcnt(0)
	global_store_dwordx4 v[2:3], v[6:9], off
	v_mad_u64_u32 v[2:3], s[10:11], v0, s55, v[10:11]
	v_add_u32_e32 v0, s12, v0
	v_mad_i64_i32 v[14:15], s[10:11], v0, s35, v[12:13]
	v_add_u32_e32 v0, 0x700, v189
	ds_read_b128 v[2:5], v2
	v_ashrrev_i32_e32 v0, 5, v0
	v_mad_u64_u32 v[6:7], s[10:11], v0, s55, v[10:11]
	ds_read_b128 v[6:9], v6
	v_add_u32_e32 v0, s12, v0
	s_waitcnt lgkmcnt(1)
	global_store_dwordx4 v[14:15], v[2:5], off
	s_nop 1
	v_mad_i64_i32 v[2:3], s[10:11], v0, s35, v[12:13]
	v_add_u32_e32 v0, 0x800, v189
	v_ashrrev_i32_e32 v0, 5, v0
	s_waitcnt lgkmcnt(0)
	global_store_dwordx4 v[2:3], v[6:9], off
	v_mad_u64_u32 v[2:3], s[10:11], v0, s55, v[10:11]
	v_add_u32_e32 v0, s12, v0
	v_mad_i64_i32 v[14:15], s[10:11], v0, s35, v[12:13]
	v_add_u32_e32 v0, 0x900, v189
	ds_read_b128 v[2:5], v2
	v_ashrrev_i32_e32 v0, 5, v0
	v_mad_u64_u32 v[6:7], s[10:11], v0, s55, v[10:11]
	ds_read_b128 v[6:9], v6
	v_add_u32_e32 v0, s12, v0
	s_waitcnt lgkmcnt(1)
	global_store_dwordx4 v[14:15], v[2:5], off
	s_nop 1
	v_mad_i64_i32 v[2:3], s[10:11], v0, s35, v[12:13]
	v_add_u32_e32 v0, 0xa00, v189
	v_ashrrev_i32_e32 v0, 5, v0
	s_waitcnt lgkmcnt(0)
	global_store_dwordx4 v[2:3], v[6:9], off
	v_mad_u64_u32 v[2:3], s[10:11], v0, s55, v[10:11]
	v_add_u32_e32 v0, s12, v0
	v_mad_i64_i32 v[14:15], s[10:11], v0, s35, v[12:13]
	v_add_u32_e32 v0, 0xb00, v189
	ds_read_b128 v[2:5], v2
	v_ashrrev_i32_e32 v0, 5, v0
	v_mad_u64_u32 v[6:7], s[10:11], v0, s55, v[10:11]
	ds_read_b128 v[6:9], v6
	v_add_u32_e32 v0, s12, v0
	s_waitcnt lgkmcnt(1)
	global_store_dwordx4 v[14:15], v[2:5], off
	s_nop 1
	v_mad_i64_i32 v[2:3], s[10:11], v0, s35, v[12:13]
	v_add_u32_e32 v0, 0xc00, v189
	v_ashrrev_i32_e32 v0, 5, v0
	s_waitcnt lgkmcnt(0)
	global_store_dwordx4 v[2:3], v[6:9], off
	v_mad_u64_u32 v[2:3], s[10:11], v0, s55, v[10:11]
	v_add_u32_e32 v0, s12, v0
	v_mad_i64_i32 v[14:15], s[10:11], v0, s35, v[12:13]
	v_add_u32_e32 v0, 0xd00, v189
	ds_read_b128 v[2:5], v2
	v_ashrrev_i32_e32 v0, 5, v0
	v_mad_u64_u32 v[6:7], s[10:11], v0, s55, v[10:11]
	ds_read_b128 v[6:9], v6
	v_add_u32_e32 v0, s12, v0
	s_waitcnt lgkmcnt(1)
	global_store_dwordx4 v[14:15], v[2:5], off
	s_nop 1
	v_mad_i64_i32 v[2:3], s[10:11], v0, s35, v[12:13]
	v_add_u32_e32 v0, 0xe00, v189
	v_ashrrev_i32_e32 v0, 5, v0
	s_waitcnt lgkmcnt(0)
	global_store_dwordx4 v[2:3], v[6:9], off
	v_mad_u64_u32 v[2:3], s[10:11], v0, s55, v[10:11]
	ds_read_b128 v[2:5], v2
	v_add_u32_e32 v0, s12, v0
	v_mad_i64_i32 v[14:15], s[10:11], v0, s35, v[12:13]
	v_add_u32_e32 v0, 0xf00, v189
	v_ashrrev_i32_e32 v0, 5, v0
	v_mad_u64_u32 v[6:7], s[10:11], v0, s55, v[10:11]
	ds_read_b128 v[6:9], v6
	v_add_u32_e32 v0, s12, v0
	s_waitcnt lgkmcnt(1)
	global_store_dwordx4 v[14:15], v[2:5], off
	s_nop 1
	v_mad_i64_i32 v[2:3], s[10:11], v0, s35, v[12:13]
	v_readlane_b32 s10, v252, 12
	s_add_i32 s22, s22, s10
	v_readlane_b32 s10, v252, 38
	s_cmp_ge_i32 s22, s10
	s_waitcnt lgkmcnt(0)
	global_store_dwordx4 v[2:3], v[6:9], off
	s_barrier
	s_cbranch_scc0 .LBB0_230

; #define LAS __attribute__((address_space(3)))
;   int tid = tid_in; asm volatile("" : "+v"(tid));
;   const int lane = tid & 63, wid = __builtin_amdgcn_readfirstlane(tid >> 6), wr = wid >> 1, wc = wid & 1;
;   const int m0 = mt * 128, n0 = nt * 256;
;   const int r = lane & 31, h = lane >> 5, key = (r >> 2) & 3;
;   constexpr int STG = 24576;
;   const int rowl = lane >> 2, cch = (lane & 3) ^ ((lane >> 4) & 3);
;   const unsigned voffA = (unsigned)(rowl * lda * 2 + cch * 16), voffB = (unsigned)(rowl * K * 2 + cch * 16);
;   const char* Abase = (const char*)(A + (size_t)m0 * lda) + (size_t)(wid * 2) * 32 * lda;
;   const char* Bbase = (const char*)(Bt + (size_t)n0 * K) + (size_t)(wid * 4) * 32 * K;
;   const size_t ablk = (size_t)32 * lda, bblk = (size_t)32 * K;
;   LAS char* lds = (LAS char*)smem;
;   LAS char* ldsA = lds + (wid * 2) * 1024;
;   LAS char* ldsB = lds + 8192 + (wid * 4) * 1024;
;     ...
;   const int x0 = ((0 + h) ^ key) * 16, x1 = ((2 + h) ^ key) * 16;
;   const int a_rd = (wr * 64 + r) * 64, b_rd = 8192 + (wc * 128 + r) * 64;
;   f32x16 acc[2][4];
; #pragma unroll
;   for (int i = 0; i < 2; ++i)
; #pragma unroll
;     for (int j = 0; j < 4; ++j)
; #pragma unroll
;       for (int e = 0; e < 16; ++e) acc[i][j][e] = 0.f;
;   const int nk = K >> 5;
;   DMA_STEP_(0, 0);
;   DMA_STEP_(1, STG);
;   asm volatile("s_waitcnt vmcnt(6)" ::: "memory");
;   __builtin_amdgcn_s_barrier();
;   asm volatile("" ::: "memory");
;   int s0 = 0, s2 = 2 * STG;
;   for (int kt = 0; kt < nk; ++kt) {
;     const int kn = (kt + 2 < nk) ? (kt + 2) : (nk - 1);
;     const LAS char* cur = lds + s0;
;     bf16x8 af[2][2], bfr[2][4];
; #pragma unroll
;     for (int kk = 0; kk < 2; ++kk) {
;       const int xo = kk ? x1 : x0;
;       af[kk][0] = *(const LAS bf16x8*)(cur + a_rd + xo);
;       bfr[kk][0] = *(const LAS bf16x8*)(cur + b_rd + xo);
;       bfr[kk][1] = *(const LAS bf16x8*)(cur + b_rd + 2048 + xo);
;       af[kk][1] = *(const LAS bf16x8*)(cur + a_rd + 2048 + xo);
;       bfr[kk][2] = *(const LAS bf16x8*)(cur + b_rd + 4096 + xo);
;       bfr[kk][3] = *(const LAS bf16x8*)(cur + b_rd + 6144 + xo);
;     }
.LBB0_243:
	s_ashr_i32 s10, s29, 31
	s_lshr_b32 s10, s10, 27
	s_add_i32 s10, s29, s10
	s_ashr_i32 s10, s10, 5
	v_readlane_b32 s11, v252, 18
	s_lshl_b32 s11, s10, s11
	v_readlane_b32 s16, v252, 41
	s_add_i32 s11, s11, s16
	s_lshl_b32 s16, s29, 7
	v_mov_b32_e32 v189, v188
	s_lshl_b32 s11, s11, 10
	s_and_b32 s16, s16, 0x380
	s_or_b32 s40, s11, s16
	v_readfirstlane_b32 s42, v189
	s_lshl_b32 s10, s10, 10
	s_lshl_b32 s11, s29, 5
	s_ashr_i32 s44, s42, 6
	s_sub_i32 s10, s11, s10
	s_and_b32 s16, s10, 0xffffff00
	s_lshl_b32 s10, s44, 1
	s_mul_hi_i32 s45, s10, 0x16000
	s_lshl_b32 s10, s44, 2
	s_mov_b32 s47, 0
	s_lshl_b32 s10, s44, 12
	s_add_i32 s43, s10, 16
	s_ashr_i32 s10, s42, 1
	v_and_b32_e32 v0, 31, v189
	s_andn2_b32 s10, s10, 63
	v_or_b32_e32 v197, s10, v0
	s_lshl_b32 s10, s44, 7
	s_ashr_i32 s17, s16, 31
	s_add_i32 s56, s43, 0x2000
	s_and_b32 s42, s10, 0x80
	s_mul_i32 s57, s40, 0x1600
	s_mul_hi_i32 s10, s40, 0x1600
	s_add_u32 s57, s23, s57
	s_mul_i32 s11, s44, 0x2c000
	s_addc_u32 s58, s28, s10
	s_add_u32 s10, s57, s11
	s_addc_u32 s11, s58, s45
	s_mul_i32 s57, s16, 64
	s_mov_b32 s45, 0
	s_add_u32 s57, s19, s57
	s_mul_i32 s46, s44, 0x1000
	s_addc_u32 s45, s20, s45
	s_add_u32 s46, s57, s46
	v_bfe_u32 v2, v189, 2, 4
	v_lshlrev_b32_e32 v3, 4, v189
	s_addc_u32 s47, s45, s47
	s_lshl_b32 s44, s44, 11
	v_xor_b32_e32 v3, v3, v189
	v_mul_u32_u24_e32 v2, 0x1600, v2
	s_sub_i32 s44, s43, s44
	v_or_b32_e32 v5, s42, v0
	v_and_or_b32 v0, v3, 48, v2
	v_bfe_u32 v10, v189, 2, 4
	v_lshlrev_b32_e32 v10, 6, v10
	v_and_or_b32 v10, v3, 48, v10
	v_mov_b32_e32 v11, 0
	s_mov_b32 m0, s44
	v_lshl_add_u64 v[192:193], s[10:11], 0, v[0:1]
	global_load_lds_dwordx4 v0, s[10:11]
	s_mov_b64 s[10:11], 0x16000
	v_lshl_add_u64 v[2:3], v[192:193], 0, s[10:11]
	s_add_i32 m0, s44, 0x400
	v_lshl_add_u64 v[194:195], s[46:47], 0, v[10:11]
	global_load_lds_dwordx4 v[2:3], off
	s_mov_b32 m0, s56
	s_nop 0
	global_load_lds_dwordx4 v[194:195], off
	global_load_lds_dwordx4 v[194:195], off offset:1024
	global_load_lds_dwordx4 v[194:195], off offset:2048
	global_load_lds_dwordx4 v[194:195], off offset:3072
	s_mov_b64 s[10:11], 0x2c000
	s_mov_b64 s[10:11], 0x42000
	s_mov_b64 s[10:11], 0x16040
	s_add_i32 m0, s44, 0x6000
	v_lshl_add_u64 v[2:3], v[192:193], 0, 64
	global_load_lds_dwordx4 v[2:3], off
	v_lshl_add_u64 v[2:3], v[192:193], 0, s[10:11]
	s_add_i32 m0, s44, 0x6400
	v_bfe_u32 v196, v189, 5, 1
	global_load_lds_dwordx4 v[2:3], off
	s_add_i32 m0, s43, 0x8000
	s_mov_b32 s100, 0x10000
	v_lshl_add_u64 v[2:3], v[194:195], 0, s[100:101]
	global_load_lds_dwordx4 v[2:3], off
	global_load_lds_dwordx4 v[2:3], off offset:1024
	global_load_lds_dwordx4 v[2:3], off offset:2048
	global_load_lds_dwordx4 v[2:3], off offset:3072
	s_mov_b64 s[10:11], 0x2c040
	s_mov_b64 s[10:11], 0x42040
	v_lshlrev_b32_e32 v218, 6, v5
	v_bfe_u32 v5, v189, 2, 2
	v_lshrrev_b32_e32 v4, 2, v189
	s_lshl_b32 s100, s100, 1
	v_lshl_add_u64 v[194:195], v[194:195], 0, s[100:101]
	s_waitcnt vmcnt(6)
	s_barrier
	v_bitop3_b32 v2, v196, v5, 2 bitop3:0x36
	v_bitop3_b32 v0, v196, v4, 3 bitop3:0x78
	v_lshlrev_b32_e32 v220, 4, v2
	v_mov_b32_e32 v2, 0
	s_mov_b32 s41, 1
	v_lshlrev_b32_e32 v219, 6, v197
	v_lshlrev_b32_e32 v0, 4, v0
	s_mov_b32 s46, 0
	s_mov_b32 s45, 0xc000
	v_mov_b32_e32 v3, v2
	v_mov_b32_e32 v4, v2
	v_mov_b32_e32 v5, v2
	v_mov_b32_e32 v6, v2
	v_mov_b32_e32 v7, v2
	v_mov_b32_e32 v8, v2
	v_mov_b32_e32 v9, v2
	v_mov_b32_e32 v10, v2
	v_mov_b32_e32 v11, v2
	v_mov_b32_e32 v12, v2
	v_mov_b32_e32 v13, v2
	v_mov_b32_e32 v14, v2
	v_mov_b32_e32 v15, v2
	v_mov_b32_e32 v16, v2
	v_mov_b32_e32 v17, v2
	v_mov_b32_e32 v18, v2
	v_mov_b32_e32 v19, v2
	v_mov_b32_e32 v20, v2
	v_mov_b32_e32 v21, v2
	v_mov_b32_e32 v22, v2
	v_mov_b32_e32 v23, v2
	v_mov_b32_e32 v24, v2
	v_mov_b32_e32 v25, v2
	v_mov_b32_e32 v26, v2
	v_mov_b32_e32 v27, v2
	v_mov_b32_e32 v28, v2
	v_mov_b32_e32 v29, v2
	v_mov_b32_e32 v30, v2
	v_mov_b32_e32 v31, v2
	v_mov_b32_e32 v32, v2
	v_mov_b32_e32 v33, v2
	v_mov_b32_e32 v50, v2
	v_mov_b32_e32 v51, v2
	v_mov_b32_e32 v52, v2
	v_mov_b32_e32 v53, v2
	v_mov_b32_e32 v54, v2
	v_mov_b32_e32 v55, v2
	v_mov_b32_e32 v56, v2
	v_mov_b32_e32 v57, v2
	v_mov_b32_e32 v58, v2
	v_mov_b32_e32 v59, v2
	v_mov_b32_e32 v60, v2
	v_mov_b32_e32 v61, v2
	v_mov_b32_e32 v62, v2
	v_mov_b32_e32 v63, v2
	v_mov_b32_e32 v64, v2
	v_mov_b32_e32 v65, v2
	v_mov_b32_e32 v82, v2
	v_mov_b32_e32 v83, v2
	v_mov_b32_e32 v84, v2
	v_mov_b32_e32 v85, v2
	v_mov_b32_e32 v86, v2
	v_mov_b32_e32 v87, v2
	v_mov_b32_e32 v88, v2
	v_mov_b32_e32 v89, v2
	v_mov_b32_e32 v90, v2
	v_mov_b32_e32 v91, v2
	v_mov_b32_e32 v92, v2
	v_mov_b32_e32 v93, v2
	v_mov_b32_e32 v94, v2
	v_mov_b32_e32 v95, v2
	v_mov_b32_e32 v96, v2
	v_mov_b32_e32 v97, v2
	v_mov_b32_e32 v34, v2
	v_mov_b32_e32 v35, v2
	v_mov_b32_e32 v36, v2
	v_mov_b32_e32 v37, v2
	v_mov_b32_e32 v38, v2
	v_mov_b32_e32 v39, v2
	v_mov_b32_e32 v40, v2
	v_mov_b32_e32 v41, v2
	v_mov_b32_e32 v42, v2
	v_mov_b32_e32 v43, v2
	v_mov_b32_e32 v44, v2
	v_mov_b32_e32 v45, v2
	v_mov_b32_e32 v46, v2
	v_mov_b32_e32 v47, v2
	v_mov_b32_e32 v48, v2
	v_mov_b32_e32 v49, v2
	v_mov_b32_e32 v66, v2
	v_mov_b32_e32 v67, v2
	v_mov_b32_e32 v68, v2
	v_mov_b32_e32 v69, v2
	v_mov_b32_e32 v70, v2
	v_mov_b32_e32 v71, v2
	v_mov_b32_e32 v72, v2
	v_mov_b32_e32 v73, v2
	v_mov_b32_e32 v74, v2
	v_mov_b32_e32 v75, v2
	v_mov_b32_e32 v76, v2
	v_mov_b32_e32 v77, v2
	v_mov_b32_e32 v78, v2
	v_mov_b32_e32 v79, v2
	v_mov_b32_e32 v80, v2
	v_mov_b32_e32 v81, v2
	v_mov_b32_e32 v98, v2
	v_mov_b32_e32 v99, v2
	v_mov_b32_e32 v100, v2
	v_mov_b32_e32 v101, v2
	v_mov_b32_e32 v102, v2
	v_mov_b32_e32 v103, v2
	v_mov_b32_e32 v104, v2
	v_mov_b32_e32 v105, v2
	v_mov_b32_e32 v106, v2
	v_mov_b32_e32 v107, v2
	v_mov_b32_e32 v108, v2
	v_mov_b32_e32 v109, v2
	v_mov_b32_e32 v110, v2
	v_mov_b32_e32 v111, v2
	v_mov_b32_e32 v112, v2
	v_mov_b32_e32 v113, v2
	v_mov_b32_e32 v114, v2
	v_mov_b32_e32 v115, v2
	v_mov_b32_e32 v116, v2
	v_mov_b32_e32 v117, v2
	v_mov_b32_e32 v118, v2
	v_mov_b32_e32 v119, v2
	v_mov_b32_e32 v120, v2
	v_mov_b32_e32 v121, v2
	v_mov_b32_e32 v122, v2
	v_mov_b32_e32 v123, v2
	v_mov_b32_e32 v124, v2
	v_mov_b32_e32 v125, v2
	v_mov_b32_e32 v126, v2
	v_mov_b32_e32 v127, v2
	v_mov_b32_e32 v128, v2
	v_mov_b32_e32 v129, v2
	v_add_u32_e32 v162, 16, v219
	v_add_u32_e32 v170, 16, v218
	v_add_u32_e32 v162, v162, v0
	v_add_u32_e32 v170, v170, v0
	ds_read_b128 v[158:161], v162
	ds_read_b128 v[182:185], v170 offset:8192
	ds_read_b128 v[178:181], v170 offset:10240
	ds_read_b128 v[162:165], v162 offset:2048
	ds_read_b128 v[174:177], v170 offset:12288
	ds_read_b128 v[170:173], v170 offset:14336
	s_setprio 1
; #define LAS __attribute__((address_space(3)))
; DI f32x16 mfma32(bf16x8 a, bf16x8 b, f32x16 c) { return __builtin_amdgcn_mfma_f32_32x32x16_bf16(a, b, c, 0, 0, 0); }
;     ...
;   for (int kt = 0; kt < nk; ++kt) {
;     const int kn = (kt + 2 < nk) ? (kt + 2) : (nk - 1);
;     const LAS char* cur = lds + s0;
;     bf16x8 af[2][2], bfr[2][4];
; #pragma unroll
;     for (int kk = 0; kk < 2; ++kk) {
;       const int xo = kk ? x1 : x0;
;       af[kk][0] = *(const LAS bf16x8*)(cur + a_rd + xo);
;       bfr[kk][0] = *(const LAS bf16x8*)(cur + b_rd + xo);
;       bfr[kk][1] = *(const LAS bf16x8*)(cur + b_rd + 2048 + xo);
;       af[kk][1] = *(const LAS bf16x8*)(cur + a_rd + 2048 + xo);
;       bfr[kk][2] = *(const LAS bf16x8*)(cur + b_rd + 4096 + xo);
;       bfr[kk][3] = *(const LAS bf16x8*)(cur + b_rd + 6144 + xo);
;     }
;     DMA_STEP_(kn, s2);
; #pragma unroll
;     for (int kk = 0; kk < 2; ++kk) {
;       acc[0][0] = mfma32(bfr[kk][0], af[kk][0], acc[0][0]); acc[0][1] = mfma32(bfr[kk][1], af[kk][0], acc[0][1]);
;       acc[1][0] = mfma32(bfr[kk][0], af[kk][1], acc[1][0]); acc[1][1] = mfma32(bfr[kk][1], af[kk][1], acc[1][1]);
;       acc[0][2] = mfma32(bfr[kk][2], af[kk][0], acc[0][2]); acc[0][3] = mfma32(bfr[kk][3], af[kk][0], acc[0][3]);
;       acc[1][2] = mfma32(bfr[kk][2], af[kk][1], acc[1][2]); acc[1][3] = mfma32(bfr[kk][3], af[kk][1], acc[1][3]);
;     }
;     __builtin_amdgcn_sched_group_barrier(0x100, 12, 0);
;     __builtin_amdgcn_sched_group_barrier(0x010, 6, 0);
;     __builtin_amdgcn_sched_group_barrier(0x008, 16, 0);
;     asm volatile("s_waitcnt vmcnt(6) lgkmcnt(0)" ::: "memory");
;     __builtin_amdgcn_s_barrier();
;     asm volatile("" ::: "memory");
;     s0 = (s0 == 2 * STG) ? 0 : s0 + STG;
;     s2 = (s2 == 2 * STG) ? 0 : s2 + STG;
;   }
.LBB0_244:
	s_add_i32 s11, s46, 16
	s_add_i32 s10, s41, -1
	v_add_u32_e32 v142, s11, v219
	v_add_u32_e32 v150, s11, v218
	s_min_u32 s10, s10, 0x55
	v_add_u32_e32 v142, v142, v220
	v_add_u32_e32 v150, v150, v220
	s_lshl_b32 s70, s10, 6
	ds_read_b128 v[138:141], v142
	ds_read_b128 v[166:169], v150 offset:8192
	ds_read_b128 v[154:157], v150 offset:10240
	ds_read_b128 v[142:145], v142 offset:2048
	ds_read_b128 v[146:149], v150 offset:12288
	ds_read_b128 v[150:153], v150 offset:14336
	v_lshl_add_u64 v[222:223], v[192:193], 0, s[70:71]
	s_add_i32 s10, s44, s45
	v_lshl_add_u64 v[224:225], v[222:223], 0, s[24:25]
	s_mov_b32 m0, s10
	v_lshl_add_u64 v[222:223], v[222:223], 0, s[98:99]
	s_mul_i32 s100, s70, 0x400
	s_waitcnt lgkmcnt(6)
	v_mfma_f32_32x32x16_bf16 v[114:129], v[182:185], v[158:161], v[114:129]
	global_load_lds_dwordx4 v[224:225], off
	s_add_i32 m0, s10, 0x400
	v_mfma_f32_32x32x16_bf16 v[98:113], v[178:181], v[158:161], v[98:113]
	global_load_lds_dwordx4 v[222:223], off
	v_lshl_add_u64 v[224:225], v[194:195], 0, s[100:101]
	s_add_i32 s10, s43, s45
	s_add_i32 m0, s10, 0x2000
	v_mfma_f32_32x32x16_bf16 v[66:81], v[182:185], v[162:165], v[66:81]
	global_load_lds_dwordx4 v[224:225], off
	v_mfma_f32_32x32x16_bf16 v[34:49], v[178:181], v[162:165], v[34:49]
	global_load_lds_dwordx4 v[224:225], off offset:1024
	v_mfma_f32_32x32x16_bf16 v[82:97], v[174:177], v[158:161], v[82:97]
	global_load_lds_dwordx4 v[224:225], off offset:2048
	v_mfma_f32_32x32x16_bf16 v[50:65], v[170:173], v[158:161], v[50:65]
	global_load_lds_dwordx4 v[224:225], off offset:3072
	v_mfma_f32_32x32x16_bf16 v[18:33], v[174:177], v[162:165], v[18:33]
	s_add_i32 s10, s46, 0x6000
	s_cmpk_lg_u32 s46, 0xc000
	s_cselect_b32 s46, s10, 0
	s_add_i32 s10, s45, 0x6000
	s_cmpk_lg_u32 s45, 0xc000
	s_cselect_b32 s45, s10, 0
	v_mfma_f32_32x32x16_bf16 v[2:17], v[170:173], v[162:165], v[2:17]
	s_add_i32 s11, s46, 16
	s_waitcnt vmcnt(6) lgkmcnt(0)
	s_barrier
	v_add_u32_e32 v162, s11, v219
	v_add_u32_e32 v170, s11, v218
	v_add_u32_e32 v162, v162, v0
	v_add_u32_e32 v170, v170, v0
	ds_read_b128 v[158:161], v162
	ds_read_b128 v[182:185], v170 offset:8192
	ds_read_b128 v[178:181], v170 offset:10240
	ds_read_b128 v[162:165], v162 offset:2048
	ds_read_b128 v[174:177], v170 offset:12288
	ds_read_b128 v[170:173], v170 offset:14336
	v_mfma_f32_32x32x16_bf16 v[114:129], v[166:169], v[138:141], v[114:129]
	v_mfma_f32_32x32x16_bf16 v[98:113], v[154:157], v[138:141], v[98:113]
	v_mfma_f32_32x32x16_bf16 v[66:81], v[166:169], v[142:145], v[66:81]
	v_mfma_f32_32x32x16_bf16 v[34:49], v[154:157], v[142:145], v[34:49]
	v_mfma_f32_32x32x16_bf16 v[82:97], v[146:149], v[138:141], v[82:97]
	v_mfma_f32_32x32x16_bf16 v[50:65], v[150:153], v[138:141], v[50:65]
	v_mfma_f32_32x32x16_bf16 v[18:33], v[146:149], v[142:145], v[18:33]
	v_mfma_f32_32x32x16_bf16 v[2:17], v[150:153], v[142:145], v[2:17]
	s_add_i32 s11, s46, 16
	s_mov_b32 s10, s41
	v_add_u32_e32 v142, s11, v219
	v_add_u32_e32 v150, s11, v218
	s_min_u32 s10, s10, 0x55
	v_add_u32_e32 v142, v142, v220
	v_add_u32_e32 v150, v150, v220
	s_lshl_b32 s70, s10, 6
	ds_read_b128 v[138:141], v142
	ds_read_b128 v[166:169], v150 offset:8192
	ds_read_b128 v[154:157], v150 offset:10240
	ds_read_b128 v[142:145], v142 offset:2048
	ds_read_b128 v[146:149], v150 offset:12288
	ds_read_b128 v[150:153], v150 offset:14336
	v_lshl_add_u64 v[222:223], v[192:193], 0, s[70:71]
	s_add_i32 s10, s44, s45
	v_lshl_add_u64 v[224:225], v[222:223], 0, s[24:25]
	s_mov_b32 m0, s10
	v_lshl_add_u64 v[222:223], v[222:223], 0, s[98:99]
	s_mul_i32 s100, s70, 0x400
	s_waitcnt lgkmcnt(6)
	v_mfma_f32_32x32x16_bf16 v[114:129], v[182:185], v[158:161], v[114:129]
	global_load_lds_dwordx4 v[224:225], off
	s_add_i32 m0, s10, 0x400
	v_mfma_f32_32x32x16_bf16 v[98:113], v[178:181], v[158:161], v[98:113]
	global_load_lds_dwordx4 v[222:223], off
	v_lshl_add_u64 v[224:225], v[194:195], 0, s[100:101]
	s_add_i32 s10, s43, s45
	s_add_i32 m0, s10, 0x2000
	v_mfma_f32_32x32x16_bf16 v[66:81], v[182:185], v[162:165], v[66:81]
	global_load_lds_dwordx4 v[224:225], off
	v_mfma_f32_32x32x16_bf16 v[34:49], v[178:181], v[162:165], v[34:49]
	global_load_lds_dwordx4 v[224:225], off offset:1024
	v_mfma_f32_32x32x16_bf16 v[82:97], v[174:177], v[158:161], v[82:97]
	global_load_lds_dwordx4 v[224:225], off offset:2048
	v_mfma_f32_32x32x16_bf16 v[50:65], v[170:173], v[158:161], v[50:65]
	global_load_lds_dwordx4 v[224:225], off offset:3072
	v_mfma_f32_32x32x16_bf16 v[18:33], v[174:177], v[162:165], v[18:33]
	s_add_i32 s10, s46, 0x6000
	s_cmpk_lg_u32 s46, 0xc000
	s_cselect_b32 s46, s10, 0
	s_add_i32 s10, s45, 0x6000
	s_cmpk_lg_u32 s45, 0xc000
	s_cselect_b32 s45, s10, 0
	v_mfma_f32_32x32x16_bf16 v[2:17], v[170:173], v[162:165], v[2:17]
	s_add_i32 s11, s46, 16
	s_waitcnt vmcnt(6) lgkmcnt(0)
	s_barrier
	v_add_u32_e32 v162, s11, v219
	v_add_u32_e32 v170, s11, v218
	v_add_u32_e32 v162, v162, v0
	v_add_u32_e32 v170, v170, v0
	ds_read_b128 v[158:161], v162
	ds_read_b128 v[182:185], v170 offset:8192
	ds_read_b128 v[178:181], v170 offset:10240
	ds_read_b128 v[162:165], v162 offset:2048
	ds_read_b128 v[174:177], v170 offset:12288
	ds_read_b128 v[170:173], v170 offset:14336
	v_mfma_f32_32x32x16_bf16 v[114:129], v[166:169], v[138:141], v[114:129]
	v_mfma_f32_32x32x16_bf16 v[98:113], v[154:157], v[138:141], v[98:113]
	v_mfma_f32_32x32x16_bf16 v[66:81], v[166:169], v[142:145], v[66:81]
	v_mfma_f32_32x32x16_bf16 v[34:49], v[154:157], v[142:145], v[34:49]
	v_mfma_f32_32x32x16_bf16 v[82:97], v[146:149], v[138:141], v[82:97]
	v_mfma_f32_32x32x16_bf16 v[50:65], v[150:153], v[138:141], v[50:65]
	v_mfma_f32_32x32x16_bf16 v[18:33], v[146:149], v[142:145], v[18:33]
	v_mfma_f32_32x32x16_bf16 v[2:17], v[150:153], v[142:145], v[2:17]
	s_add_i32 s41, s41, 2
	s_cmpk_lg_i32 s41, 0x59
	s_cbranch_scc1 .LBB0_244
; DI unsigned pk2(float a, float b) { f32x2 v = {a, b}; bf2_t r = __builtin_convertvector(v, bf2_t); return __builtin_bit_cast(unsigned, r); }
;     ...
;   asm volatile("s_waitcnt vmcnt(0)" ::: "memory");
;   __builtin_amdgcn_s_barrier();
;   asm volatile("" ::: "memory");
;     ...
;   {
;     const int h = lane >> 5, cl = lane & 31;
; #pragma unroll
;     for (int i = 0; i < 2; ++i)
; #pragma unroll
;       for (int j = 0; j < 4; ++j)
; #pragma unroll
;         for (int g = 0; g < 4; ++g) {
;           u32x2 w; w.x = pk2(acc[i][j][4 * g], acc[i][j][4 * g + 1]); w.y = pk2(acc[i][j][4 * g + 2], acc[i][j][4 * g + 3]);
;           *(u32x2*)(smem + (wr * 64 + i * 32 + cl) * 528 + (wc * 128 + j * 32 + 8 * g + 4 * h) * 2) = w;
;         }
;   }
;   __syncthreads();
	s_waitcnt lgkmcnt(0)
	s_setprio 0
	v_mul_lo_u32 v0, v197, s55
	v_add_u32_e32 v0, 16, v0
	s_nop 1
	v_cvt_pk_bf16_f32 v114, v114, v115
	v_cvt_pk_bf16_f32 v115, v116, v117
	v_lshlrev_b32_e32 v116, 3, v196
	s_lshl_b32 s10, s42, 1
	v_add3_u32 v0, v0, v116, s10
	v_cvt_pk_bf16_f32 v116, v118, v119
	v_cvt_pk_bf16_f32 v117, v120, v121
	v_cvt_pk_bf16_f32 v98, v98, v99
	v_cvt_pk_bf16_f32 v99, v100, v101
	v_cvt_pk_bf16_f32 v100, v102, v103
	v_cvt_pk_bf16_f32 v101, v104, v105
	v_cvt_pk_bf16_f32 v82, v82, v83
	v_cvt_pk_bf16_f32 v83, v84, v85
	v_cvt_pk_bf16_f32 v84, v86, v87
	v_cvt_pk_bf16_f32 v85, v88, v89
	v_cvt_pk_bf16_f32 v50, v50, v51
	v_cvt_pk_bf16_f32 v51, v52, v53
	v_cvt_pk_bf16_f32 v52, v54, v55
	v_cvt_pk_bf16_f32 v53, v56, v57
	s_waitcnt vmcnt(0)
	s_barrier
	ds_write2_b64 v0, v[114:115], v[116:117] offset1:2
	v_cvt_pk_bf16_f32 v114, v122, v123
	v_cvt_pk_bf16_f32 v115, v124, v125
	v_cvt_pk_bf16_f32 v116, v126, v127
	v_cvt_pk_bf16_f32 v117, v128, v129
	ds_write2_b64 v0, v[98:99], v[100:101] offset0:8 offset1:10
	v_cvt_pk_bf16_f32 v98, v106, v107
	v_cvt_pk_bf16_f32 v99, v108, v109
	v_cvt_pk_bf16_f32 v100, v110, v111
	v_cvt_pk_bf16_f32 v101, v112, v113
	ds_write2_b64 v0, v[82:83], v[84:85] offset0:16 offset1:18
	v_cvt_pk_bf16_f32 v82, v90, v91
	v_cvt_pk_bf16_f32 v83, v92, v93
	v_cvt_pk_bf16_f32 v84, v94, v95
	v_cvt_pk_bf16_f32 v85, v96, v97
	ds_write2_b64 v0, v[50:51], v[52:53] offset0:24 offset1:26
	v_cvt_pk_bf16_f32 v50, v58, v59
	v_cvt_pk_bf16_f32 v51, v60, v61
	v_cvt_pk_bf16_f32 v52, v62, v63
	v_cvt_pk_bf16_f32 v53, v64, v65
	ds_write2_b64 v0, v[114:115], v[116:117] offset0:4 offset1:6
	ds_write2_b64 v0, v[98:99], v[100:101] offset0:12 offset1:14
	ds_write2_b64 v0, v[82:83], v[84:85] offset0:20 offset1:22
	ds_write2_b64 v0, v[50:51], v[52:53] offset0:28 offset1:30
	v_cvt_pk_bf16_f32 v50, v66, v67
	v_cvt_pk_bf16_f32 v51, v68, v69
	v_cvt_pk_bf16_f32 v52, v70, v71
	v_cvt_pk_bf16_f32 v53, v72, v73
	v_add_u32_e32 v0, 0x4000, v0
	v_cvt_pk_bf16_f32 v34, v34, v35
	v_cvt_pk_bf16_f32 v35, v36, v37
	v_cvt_pk_bf16_f32 v36, v38, v39
	v_cvt_pk_bf16_f32 v37, v40, v41
	v_cvt_pk_bf16_f32 v18, v18, v19
	v_cvt_pk_bf16_f32 v19, v20, v21
	v_cvt_pk_bf16_f32 v20, v22, v23
	v_cvt_pk_bf16_f32 v21, v24, v25
	v_cvt_pk_bf16_f32 v2, v2, v3
	v_cvt_pk_bf16_f32 v3, v4, v5
	v_cvt_pk_bf16_f32 v4, v6, v7
	v_cvt_pk_bf16_f32 v5, v8, v9
	ds_write2_b64 v0, v[50:51], v[52:53] offset0:64 offset1:66
	v_cvt_pk_bf16_f32 v50, v74, v75
	v_cvt_pk_bf16_f32 v51, v76, v77
	v_cvt_pk_bf16_f32 v52, v78, v79
	v_cvt_pk_bf16_f32 v53, v80, v81
	ds_write2_b64 v0, v[34:35], v[36:37] offset0:72 offset1:74
	v_cvt_pk_bf16_f32 v34, v42, v43
	v_cvt_pk_bf16_f32 v35, v44, v45
	v_cvt_pk_bf16_f32 v36, v46, v47
	v_cvt_pk_bf16_f32 v37, v48, v49
	ds_write2_b64 v0, v[18:19], v[20:21] offset0:80 offset1:82
	v_cvt_pk_bf16_f32 v18, v26, v27
	v_cvt_pk_bf16_f32 v19, v28, v29
	v_cvt_pk_bf16_f32 v20, v30, v31
	v_cvt_pk_bf16_f32 v21, v32, v33
	ds_write2_b64 v0, v[2:3], v[4:5] offset0:88 offset1:90
	v_cvt_pk_bf16_f32 v2, v10, v11
	v_cvt_pk_bf16_f32 v3, v12, v13
	v_cvt_pk_bf16_f32 v4, v14, v15
	v_cvt_pk_bf16_f32 v5, v16, v17
	s_lshl_b64 s[10:11], s[16:17], 1
	ds_write2_b64 v0, v[50:51], v[52:53] offset0:68 offset1:70
	ds_write2_b64 v0, v[34:35], v[36:37] offset0:76 offset1:78
	ds_write2_b64 v0, v[18:19], v[20:21] offset0:84 offset1:86
	ds_write2_b64 v0, v[2:3], v[4:5] offset0:92 offset1:94
	s_waitcnt vmcnt(0) lgkmcnt(0)
	s_barrier
; #define GAS __attribute__((address_space(1)))
;     ...
;   int tid2 = tid; asm volatile("" : "+v"(tid2));
;   if (EPI == 0) {
; #pragma unroll
;     for (int i = 0; i < 16; ++i) {
;       const int id = tid2 + 256 * i, r = id >> 5, c8 = (id & 31) * 8;
;       const u32x4 v = *(const u32x4*)(smem + r * 528 + c8 * 2);
;       *(GAS u32x4*)(ea.out + (size_t)(m0 + r) * ea.ldo + n0 + c8) = v;
;     }
	s_add_u32 s10, s21, s10
	v_lshlrev_b32_e32 v0, 4, v189
	v_and_b32_e32 v0, 0x1f0, v0
	s_addc_u32 s11, s22, s11
	v_add_u32_e32 v10, 16, v0
	v_lshl_add_u64 v[12:13], s[10:11], 0, v[0:1]
	v_ashrrev_i32_e32 v0, 5, v189
	v_mad_u64_u32 v[2:3], s[10:11], v0, s55, v[10:11]
	ds_read_b128 v[2:5], v2
	v_add_u32_e32 v6, s40, v0
	v_ashrrev_i32_e32 v7, 31, v6
	v_add_u32_e32 v0, 0x100, v189
	v_lshlrev_b64 v[6:7], 11, v[6:7]
	v_ashrrev_i32_e32 v0, 5, v0
	v_lshl_add_u64 v[14:15], v[12:13], 0, v[6:7]
	v_mad_u64_u32 v[6:7], s[10:11], v0, s55, v[10:11]
	ds_read_b128 v[6:9], v6
	s_waitcnt lgkmcnt(1)
	global_store_dwordx4 v[14:15], v[2:5], off
	s_nop 1
	v_add_u32_e32 v2, s40, v0
	v_ashrrev_i32_e32 v3, 31, v2
	v_lshlrev_b64 v[2:3], 11, v[2:3]
	v_add_u32_e32 v0, 0x200, v189
	v_lshl_add_u64 v[2:3], v[12:13], 0, v[2:3]
	v_ashrrev_i32_e32 v0, 5, v0
	s_waitcnt lgkmcnt(0)
	global_store_dwordx4 v[2:3], v[6:9], off
	v_mad_u64_u32 v[2:3], s[10:11], v0, s55, v[10:11]
	ds_read_b128 v[2:5], v2
	v_add_u32_e32 v6, s40, v0
	v_ashrrev_i32_e32 v7, 31, v6
	v_add_u32_e32 v0, 0x300, v189
	v_lshlrev_b64 v[6:7], 11, v[6:7]
	v_ashrrev_i32_e32 v0, 5, v0
	v_lshl_add_u64 v[14:15], v[12:13], 0, v[6:7]
	v_mad_u64_u32 v[6:7], s[10:11], v0, s55, v[10:11]
	ds_read_b128 v[6:9], v6
	s_waitcnt lgkmcnt(1)
	global_store_dwordx4 v[14:15], v[2:5], off
	s_nop 1
	v_add_u32_e32 v2, s40, v0
	v_ashrrev_i32_e32 v3, 31, v2
	v_lshlrev_b64 v[2:3], 11, v[2:3]
	v_add_u32_e32 v0, 0x400, v189
	v_lshl_add_u64 v[2:3], v[12:13], 0, v[2:3]
	v_ashrrev_i32_e32 v0, 5, v0
	s_waitcnt lgkmcnt(0)
	global_store_dwordx4 v[2:3], v[6:9], off
	v_mad_u64_u32 v[2:3], s[10:11], v0, s55, v[10:11]
	ds_read_b128 v[2:5], v2
	v_add_u32_e32 v6, s40, v0
	v_ashrrev_i32_e32 v7, 31, v6
	v_add_u32_e32 v0, 0x500, v189
	v_lshlrev_b64 v[6:7], 11, v[6:7]
	v_ashrrev_i32_e32 v0, 5, v0
	v_lshl_add_u64 v[14:15], v[12:13], 0, v[6:7]
	v_mad_u64_u32 v[6:7], s[10:11], v0, s55, v[10:11]
	ds_read_b128 v[6:9], v6
	s_waitcnt lgkmcnt(1)
	global_store_dwordx4 v[14:15], v[2:5], off
	s_nop 1
	v_add_u32_e32 v2, s40, v0
	v_ashrrev_i32_e32 v3, 31, v2
	v_lshlrev_b64 v[2:3], 11, v[2:3]
	v_add_u32_e32 v0, 0x600, v189
	v_lshl_add_u64 v[2:3], v[12:13], 0, v[2:3]
	v_ashrrev_i32_e32 v0, 5, v0
	s_waitcnt lgkmcnt(0)
	global_store_dwordx4 v[2:3], v[6:9], off
	v_mad_u64_u32 v[2:3], s[10:11], v0, s55, v[10:11]
	ds_read_b128 v[2:5], v2
	v_add_u32_e32 v6, s40, v0
	v_ashrrev_i32_e32 v7, 31, v6
	v_add_u32_e32 v0, 0x700, v189
	v_lshlrev_b64 v[6:7], 11, v[6:7]
	v_ashrrev_i32_e32 v0, 5, v0
	v_lshl_add_u64 v[14:15], v[12:13], 0, v[6:7]
	v_mad_u64_u32 v[6:7], s[10:11], v0, s55, v[10:11]
	ds_read_b128 v[6:9], v6
	s_waitcnt lgkmcnt(1)
	global_store_dwordx4 v[14:15], v[2:5], off
	s_nop 1
	v_add_u32_e32 v2, s40, v0
	v_ashrrev_i32_e32 v3, 31, v2
	v_lshlrev_b64 v[2:3], 11, v[2:3]
	v_add_u32_e32 v0, 0x800, v189
	v_lshl_add_u64 v[2:3], v[12:13], 0, v[2:3]
	v_ashrrev_i32_e32 v0, 5, v0
	s_waitcnt lgkmcnt(0)
	global_store_dwordx4 v[2:3], v[6:9], off
	v_mad_u64_u32 v[2:3], s[10:11], v0, s55, v[10:11]
	ds_read_b128 v[2:5], v2
	v_add_u32_e32 v6, s40, v0
	v_ashrrev_i32_e32 v7, 31, v6
	v_add_u32_e32 v0, 0x900, v189
	v_lshlrev_b64 v[6:7], 11, v[6:7]
	v_ashrrev_i32_e32 v0, 5, v0
	v_lshl_add_u64 v[14:15], v[12:13], 0, v[6:7]
	v_mad_u64_u32 v[6:7], s[10:11], v0, s55, v[10:11]
	ds_read_b128 v[6:9], v6
	s_waitcnt lgkmcnt(1)
	global_store_dwordx4 v[14:15], v[2:5], off
	s_nop 1
	v_add_u32_e32 v2, s40, v0
	v_ashrrev_i32_e32 v3, 31, v2
	v_lshlrev_b64 v[2:3], 11, v[2:3]
	v_add_u32_e32 v0, 0xa00, v189
	v_lshl_add_u64 v[2:3], v[12:13], 0, v[2:3]
	v_ashrrev_i32_e32 v0, 5, v0
	s_waitcnt lgkmcnt(0)
	global_store_dwordx4 v[2:3], v[6:9], off
	v_mad_u64_u32 v[2:3], s[10:11], v0, s55, v[10:11]
	ds_read_b128 v[2:5], v2
	v_add_u32_e32 v6, s40, v0
	v_ashrrev_i32_e32 v7, 31, v6
	v_add_u32_e32 v0, 0xb00, v189
	v_lshlrev_b64 v[6:7], 11, v[6:7]
	v_ashrrev_i32_e32 v0, 5, v0
	v_lshl_add_u64 v[14:15], v[12:13], 0, v[6:7]
	v_mad_u64_u32 v[6:7], s[10:11], v0, s55, v[10:11]
	ds_read_b128 v[6:9], v6
	s_waitcnt lgkmcnt(1)
	global_store_dwordx4 v[14:15], v[2:5], off
	s_nop 1
	v_add_u32_e32 v2, s40, v0
	v_ashrrev_i32_e32 v3, 31, v2
	v_lshlrev_b64 v[2:3], 11, v[2:3]
	v_add_u32_e32 v0, 0xc00, v189
	v_lshl_add_u64 v[2:3], v[12:13], 0, v[2:3]
	v_ashrrev_i32_e32 v0, 5, v0
	s_waitcnt lgkmcnt(0)
	global_store_dwordx4 v[2:3], v[6:9], off
	v_mad_u64_u32 v[2:3], s[10:11], v0, s55, v[10:11]
	ds_read_b128 v[2:5], v2
	v_add_u32_e32 v6, s40, v0
	v_ashrrev_i32_e32 v7, 31, v6
	v_add_u32_e32 v0, 0xd00, v189
	v_lshlrev_b64 v[6:7], 11, v[6:7]
	v_ashrrev_i32_e32 v0, 5, v0
	v_lshl_add_u64 v[14:15], v[12:13], 0, v[6:7]
	v_mad_u64_u32 v[6:7], s[10:11], v0, s55, v[10:11]
	ds_read_b128 v[6:9], v6
	s_waitcnt lgkmcnt(1)
	global_store_dwordx4 v[14:15], v[2:5], off
	s_nop 1
	v_add_u32_e32 v2, s40, v0
	v_ashrrev_i32_e32 v3, 31, v2
	v_lshlrev_b64 v[2:3], 11, v[2:3]
	v_add_u32_e32 v0, 0xe00, v189
	v_lshl_add_u64 v[2:3], v[12:13], 0, v[2:3]
	v_ashrrev_i32_e32 v0, 5, v0
	s_waitcnt lgkmcnt(0)
	global_store_dwordx4 v[2:3], v[6:9], off
	v_mad_u64_u32 v[2:3], s[10:11], v0, s55, v[10:11]
	ds_read_b128 v[2:5], v2
	v_add_u32_e32 v6, s40, v0
	v_ashrrev_i32_e32 v7, 31, v6
	v_add_u32_e32 v0, 0xf00, v189
	v_lshlrev_b64 v[6:7], 11, v[6:7]
	v_ashrrev_i32_e32 v0, 5, v0
	v_lshl_add_u64 v[14:15], v[12:13], 0, v[6:7]
	v_mad_u64_u32 v[6:7], s[10:11], v0, s55, v[10:11]
	ds_read_b128 v[6:9], v6
	s_waitcnt lgkmcnt(1)
	global_store_dwordx4 v[14:15], v[2:5], off
	v_readlane_b32 s10, v252, 12
	s_add_i32 s29, s29, s10
	v_add_u32_e32 v2, s40, v0
	v_ashrrev_i32_e32 v3, 31, v2
	v_lshlrev_b64 v[2:3], 11, v[2:3]
	v_lshl_add_u64 v[2:3], v[12:13], 0, v[2:3]
	s_cmp_ge_i32 s29, s18
	s_waitcnt lgkmcnt(0)
	global_store_dwordx4 v[2:3], v[6:9], off
	s_barrier
	s_cbranch_scc0 .LBB0_243

; #define LAS __attribute__((address_space(3)))
;   int tid = tid_in; asm volatile("" : "+v"(tid));
;   const int lane = tid & 63, wid = __builtin_amdgcn_readfirstlane(tid >> 6), wr = wid >> 1, wc = wid & 1;
;   const int m0 = mt * 128, n0 = nt * 256;
;   const int r = lane & 31, h = lane >> 5, key = (r >> 2) & 3;
;   constexpr int STG = 24576;
;   const int rowl = lane >> 2, cch = (lane & 3) ^ ((lane >> 4) & 3);
;   const unsigned voffA = (unsigned)(rowl * lda * 2 + cch * 16), voffB = (unsigned)(rowl * K * 2 + cch * 16);
;   const char* Abase = (const char*)(A + (size_t)m0 * lda) + (size_t)(wid * 2) * 32 * lda;
;   const char* Bbase = (const char*)(Bt + (size_t)n0 * K) + (size_t)(wid * 4) * 32 * K;
;   const size_t ablk = (size_t)32 * lda, bblk = (size_t)32 * K;
;   LAS char* lds = (LAS char*)smem;
;   LAS char* ldsA = lds + (wid * 2) * 1024;
;   LAS char* ldsB = lds + 8192 + (wid * 4) * 1024;
;     ...
;   const int x0 = ((0 + h) ^ key) * 16, x1 = ((2 + h) ^ key) * 16;
;   const int a_rd = (wr * 64 + r) * 64, b_rd = 8192 + (wc * 128 + r) * 64;
;   f32x16 acc[2][4];
; #pragma unroll
;   for (int i = 0; i < 2; ++i)
; #pragma unroll
;     for (int j = 0; j < 4; ++j)
; #pragma unroll
;       for (int e = 0; e < 16; ++e) acc[i][j][e] = 0.f;
;   const int nk = K >> 5;
;   DMA_STEP_(0, 0);
;   DMA_STEP_(1, STG);
;   asm volatile("s_waitcnt vmcnt(6)" ::: "memory");
;   __builtin_amdgcn_s_barrier();
;   asm volatile("" ::: "memory");
;   int s0 = 0, s2 = 2 * STG;
;   for (int kt = 0; kt < nk; ++kt) {
;     const int kn = (kt + 2 < nk) ? (kt + 2) : (nk - 1);
;     const LAS char* cur = lds + s0;
;     bf16x8 af[2][2], bfr[2][4];
; #pragma unroll
;     for (int kk = 0; kk < 2; ++kk) {
;       const int xo = kk ? x1 : x0;
;       af[kk][0] = *(const LAS bf16x8*)(cur + a_rd + xo);
;       bfr[kk][0] = *(const LAS bf16x8*)(cur + b_rd + xo);
;       bfr[kk][1] = *(const LAS bf16x8*)(cur + b_rd + 2048 + xo);
;       af[kk][1] = *(const LAS bf16x8*)(cur + a_rd + 2048 + xo);
;       bfr[kk][2] = *(const LAS bf16x8*)(cur + b_rd + 4096 + xo);
;       bfr[kk][3] = *(const LAS bf16x8*)(cur + b_rd + 6144 + xo);
;     }
.LBB0_271:
	s_mul_hi_i32 s10, s14, 0x2e8ba2e9
	s_lshr_b32 s11, s10, 31
	s_ashr_i32 s10, s10, 4
	s_add_i32 s10, s10, s11
	v_readlane_b32 s15, v252, 18
	s_mul_i32 s11, s10, 0xffffffa8
	s_lshl_b32 s10, s10, s15
	v_readlane_b32 s15, v252, 41
	s_add_i32 s10, s10, s15
	s_lshr_b32 s15, s10, 31
	s_add_i32 s15, s10, s15
	s_and_b32 s18, s15, -2
	s_add_i32 s11, s11, s14
	s_sub_i32 s10, s10, s18
	s_mul_i32 s22, s10, 11
	s_ashr_i32 s10, s11, 3
	v_mov_b32_e32 v189, v188
	s_lshl_b32 s15, s15, 2
	s_add_i32 s22, s22, s10
	s_and_b32 s15, s15, -8
	v_readfirstlane_b32 s10, v189
	s_and_b32 s18, s14, 7
	s_ashr_i32 s11, s10, 6
	s_or_b32 s15, s15, s18
	s_lshl_b32 s18, s11, 1
	s_ashr_i32 s19, s18, 31
	s_lshl_b64 s[28:29], s[18:19], 10
	s_lshl_b32 s18, s11, 2
	s_ashr_i32 s19, s18, 31
	s_ashr_i32 s10, s10, 1
	s_lshl_b32 s46, s15, 7
	s_lshl_b32 s66, s22, 8
	v_and_b32_e32 v0, 31, v189
	s_lshl_b64 s[74:75], s[18:19], 10
	s_lshl_b32 s18, s11, 12
	s_andn2_b32 s10, s10, 63
	v_lshlrev_b32_e32 v3, 4, v189
	s_ashr_i32 s47, s46, 31
	s_ashr_i32 s67, s66, 31
	s_add_i32 s19, s18, 16
	v_or_b32_e32 v197, s10, v0
	s_lshl_b32 s10, s11, 7
	v_lshlrev_b32_e32 v2, 9, v189
	v_bitop3_b32 v3, v3, 48, v189 bitop3:0x48
	s_lshl_b64 s[20:21], s[46:47], 6
	s_lshl_b64 s[40:41], s[66:67], 6
	s_add_i32 s23, s19, 0x2000
	s_and_b32 s18, s10, 0x80
	s_movk_i32 s10, 0x7800
	v_or_b32_e32 v4, s18, v0
	v_and_or_b32 v0, v2, s10, v3
	v_lshlrev_b32_e32 v10, 4, v189
	v_and_b32_e32 v10, 0x3c0, v10
	v_or_b32_e32 v10, v10, v3
	v_mov_b32_e32 v11, 0
	s_add_u32 s10, s42, s20
	s_addc_u32 s20, s43, s21
	s_add_u32 s28, s10, s28
	s_addc_u32 s29, s20, s29
	s_add_u32 s10, s87, s40
	s_addc_u32 s21, s76, s41
	s_lshl_b32 s11, s11, 11
	s_sub_i32 s20, s19, s11
	s_mov_b32 m0, s20
	v_lshl_add_u64 v[192:193], s[28:29], 0, v[10:11]
	global_load_lds_dwordx4 v[192:193], off
	global_load_lds_dwordx4 v[192:193], off offset:1024
	s_add_u32 s28, s10, s74
	s_addc_u32 s29, s21, s75
	v_lshl_add_u64 v[194:195], s[28:29], 0, v[10:11]
	s_mov_b32 m0, s23
	s_nop 0
	global_load_lds_dwordx4 v[194:195], off
	global_load_lds_dwordx4 v[194:195], off offset:1024
	global_load_lds_dwordx4 v[194:195], off offset:2048
	global_load_lds_dwordx4 v[194:195], off offset:3072
	s_mov_b64 s[10:11], 0x10000
	s_mov_b64 s[10:11], 0x18000
	s_mov_b64 s[10:11], 0x8040
	s_add_i32 m0, s20, 0x6000
	s_mov_b32 vcc_lo, 0x480000
	s_mov_b32 vcc_hi, 0
	v_lshl_add_u64 v[2:3], v[192:193], 0, vcc
	global_load_lds_dwordx4 v[2:3], off
	global_load_lds_dwordx4 v[2:3], off offset:1024
	v_lshrrev_b32_e32 v5, 5, v189
	s_add_i32 m0, s19, 0x8000
	s_mov_b32 s100, 0x58000
	v_lshl_add_u64 v[2:3], v[194:195], 0, s[100:101]
	global_load_lds_dwordx4 v[2:3], off
	global_load_lds_dwordx4 v[2:3], off offset:1024
	global_load_lds_dwordx4 v[2:3], off offset:2048
	global_load_lds_dwordx4 v[2:3], off offset:3072
	s_mov_b64 s[10:11], 0x10040
	s_mov_b64 s[10:11], 0x18040
	v_bfe_u32 v6, v189, 2, 2
	v_bfe_u32 v196, v189, 5, 1
	s_lshl_b32 s100, s100, 1
	v_lshl_add_u64 v[194:195], v[194:195], 0, s[100:101]
	s_lshl_b32 vcc_lo, vcc_lo, 1
	v_lshl_add_u64 v[192:193], v[192:193], 0, vcc
	s_waitcnt vmcnt(6)
	s_barrier
	v_bitop3_b32 v2, v5, v6, 1 bitop3:0x6c
	v_lshlrev_b32_e32 v219, 4, v2
	v_bitop3_b32 v2, v196, v6, 2 bitop3:0x36
	v_mov_b32_e32 v66, 0
	v_lshlrev_b32_e32 v218, 6, v197
	v_lshlrev_b32_e32 v0, 6, v4
	v_lshlrev_b32_e32 v220, 4, v2
	s_mov_b32 s23, 0xc000
	s_mov_b32 s28, 0
	s_mov_b32 s21, 0
	v_mov_b32_e32 v67, v66
	v_mov_b32_e32 v68, v66
	v_mov_b32_e32 v69, v66
	v_mov_b32_e32 v70, v66
	v_mov_b32_e32 v71, v66
	v_mov_b32_e32 v72, v66
	v_mov_b32_e32 v73, v66
	v_mov_b32_e32 v74, v66
	v_mov_b32_e32 v75, v66
	v_mov_b32_e32 v76, v66
	v_mov_b32_e32 v77, v66
	v_mov_b32_e32 v78, v66
	v_mov_b32_e32 v79, v66
	v_mov_b32_e32 v80, v66
	v_mov_b32_e32 v81, v66
	v_mov_b32_e32 v82, v66
	v_mov_b32_e32 v83, v66
	v_mov_b32_e32 v84, v66
	v_mov_b32_e32 v85, v66
	v_mov_b32_e32 v86, v66
	v_mov_b32_e32 v87, v66
	v_mov_b32_e32 v88, v66
	v_mov_b32_e32 v89, v66
	s_waitcnt vmcnt(0)
	v_mov_b32_e32 v90, v66
	v_mov_b32_e32 v91, v66
	v_mov_b32_e32 v92, v66
	v_mov_b32_e32 v93, v66
	v_mov_b32_e32 v94, v66
	v_mov_b32_e32 v95, v66
	v_mov_b32_e32 v96, v66
	v_mov_b32_e32 v97, v66
	v_mov_b32_e32 v18, v66
	v_mov_b32_e32 v19, v66
	v_mov_b32_e32 v20, v66
	v_mov_b32_e32 v21, v66
	v_mov_b32_e32 v22, v66
	v_mov_b32_e32 v23, v66
	v_mov_b32_e32 v24, v66
	v_mov_b32_e32 v25, v66
	v_mov_b32_e32 v26, v66
	v_mov_b32_e32 v27, v66
	v_mov_b32_e32 v28, v66
	v_mov_b32_e32 v29, v66
	v_mov_b32_e32 v30, v66
	v_mov_b32_e32 v31, v66
	v_mov_b32_e32 v32, v66
	v_mov_b32_e32 v33, v66
	v_mov_b32_e32 v2, v66
	v_mov_b32_e32 v3, v66
	v_mov_b32_e32 v4, v66
	v_mov_b32_e32 v5, v66
	v_mov_b32_e32 v6, v66
	v_mov_b32_e32 v7, v66
	v_mov_b32_e32 v8, v66
	v_mov_b32_e32 v9, v66
	v_mov_b32_e32 v10, v66
	v_mov_b32_e32 v11, v66
	v_mov_b32_e32 v12, v66
	v_mov_b32_e32 v13, v66
	v_mov_b32_e32 v14, v66
	v_mov_b32_e32 v15, v66
	v_mov_b32_e32 v16, v66
	v_mov_b32_e32 v17, v66
	v_mov_b32_e32 v114, v66
	v_mov_b32_e32 v115, v66
	v_mov_b32_e32 v116, v66
	v_mov_b32_e32 v117, v66
	v_mov_b32_e32 v118, v66
	v_mov_b32_e32 v119, v66
	v_mov_b32_e32 v120, v66
	v_mov_b32_e32 v121, v66
	v_mov_b32_e32 v122, v66
	v_mov_b32_e32 v123, v66
	v_mov_b32_e32 v124, v66
	v_mov_b32_e32 v125, v66
	v_mov_b32_e32 v126, v66
	v_mov_b32_e32 v127, v66
	v_mov_b32_e32 v128, v66
	v_mov_b32_e32 v129, v66
	v_mov_b32_e32 v98, v66
	v_mov_b32_e32 v99, v66
	v_mov_b32_e32 v100, v66
	v_mov_b32_e32 v101, v66
	v_mov_b32_e32 v102, v66
	v_mov_b32_e32 v103, v66
	v_mov_b32_e32 v104, v66
	v_mov_b32_e32 v105, v66
	v_mov_b32_e32 v106, v66
	v_mov_b32_e32 v107, v66
	v_mov_b32_e32 v108, v66
	v_mov_b32_e32 v109, v66
	v_mov_b32_e32 v110, v66
	v_mov_b32_e32 v111, v66
	v_mov_b32_e32 v112, v66
	v_mov_b32_e32 v113, v66
	v_mov_b32_e32 v50, v66
	v_mov_b32_e32 v51, v66
	v_mov_b32_e32 v52, v66
	v_mov_b32_e32 v53, v66
	v_mov_b32_e32 v54, v66
	v_mov_b32_e32 v55, v66
	v_mov_b32_e32 v56, v66
	v_mov_b32_e32 v57, v66
	v_mov_b32_e32 v58, v66
	v_mov_b32_e32 v59, v66
	v_mov_b32_e32 v60, v66
	v_mov_b32_e32 v61, v66
	v_mov_b32_e32 v62, v66
	v_mov_b32_e32 v63, v66
	v_mov_b32_e32 v64, v66
	v_mov_b32_e32 v65, v66
	v_mov_b32_e32 v34, v66
	v_mov_b32_e32 v35, v66
	v_mov_b32_e32 v36, v66
	v_mov_b32_e32 v37, v66
	v_mov_b32_e32 v38, v66
	v_mov_b32_e32 v39, v66
	v_mov_b32_e32 v40, v66
	v_mov_b32_e32 v41, v66
	v_mov_b32_e32 v42, v66
	v_mov_b32_e32 v43, v66
	v_mov_b32_e32 v44, v66
	v_mov_b32_e32 v45, v66
	v_mov_b32_e32 v46, v66
	v_mov_b32_e32 v47, v66
	v_mov_b32_e32 v48, v66
	v_mov_b32_e32 v49, v66
	s_mov_b32 vcc_hi, 0
	v_add_u32_e32 v158, 16, v218
	v_add_u32_e32 v170, 16, v0
	v_add_u32_e32 v158, v158, v219
	v_add_u32_e32 v170, v170, v219
	ds_read_b128 v[154:157], v158
	ds_read_b128 v[182:185], v170 offset:8192
	ds_read_b128 v[178:181], v170 offset:10240
	ds_read_b128 v[158:161], v158 offset:2048
	ds_read_b128 v[174:177], v170 offset:12288
	ds_read_b128 v[170:173], v170 offset:14336
	s_setprio 1
; #define LAS __attribute__((address_space(3)))
; DI f32x16 mfma32(bf16x8 a, bf16x8 b, f32x16 c) { return __builtin_amdgcn_mfma_f32_32x32x16_bf16(a, b, c, 0, 0, 0); }
;     ...
;   for (int kt = 0; kt < nk; ++kt) {
;     const int kn = (kt + 2 < nk) ? (kt + 2) : (nk - 1);
;     const LAS char* cur = lds + s0;
;     bf16x8 af[2][2], bfr[2][4];
; #pragma unroll
;     for (int kk = 0; kk < 2; ++kk) {
;       const int xo = kk ? x1 : x0;
;       af[kk][0] = *(const LAS bf16x8*)(cur + a_rd + xo);
;       bfr[kk][0] = *(const LAS bf16x8*)(cur + b_rd + xo);
;       bfr[kk][1] = *(const LAS bf16x8*)(cur + b_rd + 2048 + xo);
;       af[kk][1] = *(const LAS bf16x8*)(cur + a_rd + 2048 + xo);
;       bfr[kk][2] = *(const LAS bf16x8*)(cur + b_rd + 4096 + xo);
;       bfr[kk][3] = *(const LAS bf16x8*)(cur + b_rd + 6144 + xo);
;     }
;     DMA_STEP_(kn, s2);
; #pragma unroll
;     for (int kk = 0; kk < 2; ++kk) {
;       acc[0][0] = mfma32(bfr[kk][0], af[kk][0], acc[0][0]); acc[0][1] = mfma32(bfr[kk][1], af[kk][0], acc[0][1]);
;       acc[1][0] = mfma32(bfr[kk][0], af[kk][1], acc[1][0]); acc[1][1] = mfma32(bfr[kk][1], af[kk][1], acc[1][1]);
;       acc[0][2] = mfma32(bfr[kk][2], af[kk][0], acc[0][2]); acc[0][3] = mfma32(bfr[kk][3], af[kk][0], acc[0][3]);
;       acc[1][2] = mfma32(bfr[kk][2], af[kk][1], acc[1][2]); acc[1][3] = mfma32(bfr[kk][3], af[kk][1], acc[1][3]);
;     }
;     __builtin_amdgcn_sched_group_barrier(0x100, 12, 0);
;     __builtin_amdgcn_sched_group_barrier(0x010, 6, 0);
;     __builtin_amdgcn_sched_group_barrier(0x008, 16, 0);
;     asm volatile("s_waitcnt vmcnt(6) lgkmcnt(0)" ::: "memory");
;     __builtin_amdgcn_s_barrier();
;     asm volatile("" ::: "memory");
;     s0 = (s0 == 2 * STG) ? 0 : s0 + STG;
;     s2 = (s2 == 2 * STG) ? 0 : s2 + STG;
;   }
.LBB0_272:
	s_add_i32 s11, s28, 16
	s_mov_b32 s10, s21
	v_add_u32_e32 v142, s11, v218
	v_add_u32_e32 v150, s11, v0
	s_min_u32 s10, s10, 29
	v_add_u32_e32 v142, v142, v220
	v_add_u32_e32 v150, v150, v220
	s_lshl_b32 s70, s10, 6
	ds_read_b128 v[138:141], v142
	ds_read_b128 v[162:165], v150 offset:8192
	ds_read_b128 v[166:169], v150 offset:10240
	ds_read_b128 v[142:145], v142 offset:2048
	ds_read_b128 v[146:149], v150 offset:12288
	ds_read_b128 v[150:153], v150 offset:14336
	s_mul_i32 vcc_lo, s70, 0x12000
	s_add_i32 s10, s20, s23
	v_lshl_add_u64 v[222:223], v[192:193], 0, vcc
	s_mov_b32 m0, s10
	s_mul_i32 s100, s70, 0x1600
	v_lshl_add_u64 v[224:225], v[194:195], 0, s[100:101]
	s_add_i32 s10, s19, s23
	s_waitcnt lgkmcnt(6)
	v_mfma_f32_32x32x16_bf16 v[66:81], v[182:185], v[154:157], v[66:81]
	global_load_lds_dwordx4 v[222:223], off
	v_mfma_f32_32x32x16_bf16 v[82:97], v[178:181], v[154:157], v[82:97]
	global_load_lds_dwordx4 v[222:223], off offset:1024
	s_add_i32 m0, s10, 0x2000
	v_mfma_f32_32x32x16_bf16 v[18:33], v[182:185], v[158:161], v[18:33]
	global_load_lds_dwordx4 v[224:225], off
	v_mfma_f32_32x32x16_bf16 v[2:17], v[178:181], v[158:161], v[2:17]
	global_load_lds_dwordx4 v[224:225], off offset:1024
	v_mfma_f32_32x32x16_bf16 v[114:129], v[174:177], v[154:157], v[114:129]
	global_load_lds_dwordx4 v[224:225], off offset:2048
	v_mfma_f32_32x32x16_bf16 v[98:113], v[170:173], v[154:157], v[98:113]
	global_load_lds_dwordx4 v[224:225], off offset:3072
	v_mfma_f32_32x32x16_bf16 v[50:65], v[174:177], v[158:161], v[50:65]
	s_add_i32 s10, s28, 0x6000
	s_cmpk_lg_u32 s28, 0xc000
	s_cselect_b32 s28, s10, 0
	s_add_i32 s10, s23, 0x6000
	s_cmpk_lg_u32 s23, 0xc000
	s_cselect_b32 s23, s10, 0
	v_mfma_f32_32x32x16_bf16 v[34:49], v[170:173], v[158:161], v[34:49]
	s_add_i32 s11, s28, 16
	s_waitcnt vmcnt(6) lgkmcnt(0)
	s_barrier
	v_add_u32_e32 v158, s11, v218
	v_add_u32_e32 v170, s11, v0
	v_add_u32_e32 v158, v158, v219
	v_add_u32_e32 v170, v170, v219
	ds_read_b128 v[154:157], v158
	ds_read_b128 v[182:185], v170 offset:8192
	ds_read_b128 v[178:181], v170 offset:10240
	ds_read_b128 v[158:161], v158 offset:2048
	ds_read_b128 v[174:177], v170 offset:12288
	ds_read_b128 v[170:173], v170 offset:14336
	v_mfma_f32_32x32x16_bf16 v[66:81], v[162:165], v[138:141], v[66:81]
	v_mfma_f32_32x32x16_bf16 v[82:97], v[166:169], v[138:141], v[82:97]
	v_mfma_f32_32x32x16_bf16 v[18:33], v[162:165], v[142:145], v[18:33]
	v_mfma_f32_32x32x16_bf16 v[2:17], v[166:169], v[142:145], v[2:17]
	v_mfma_f32_32x32x16_bf16 v[114:129], v[146:149], v[138:141], v[114:129]
	v_mfma_f32_32x32x16_bf16 v[98:113], v[150:153], v[138:141], v[98:113]
	v_mfma_f32_32x32x16_bf16 v[50:65], v[146:149], v[142:145], v[50:65]
	v_mfma_f32_32x32x16_bf16 v[34:49], v[150:153], v[142:145], v[34:49]
	s_add_i32 s11, s28, 16
	s_add_i32 s10, s21, 1
	v_add_u32_e32 v142, s11, v218
	v_add_u32_e32 v150, s11, v0
	s_min_u32 s10, s10, 29
	v_add_u32_e32 v142, v142, v220
	v_add_u32_e32 v150, v150, v220
	s_lshl_b32 s70, s10, 6
	ds_read_b128 v[138:141], v142
	ds_read_b128 v[162:165], v150 offset:8192
	ds_read_b128 v[166:169], v150 offset:10240
	ds_read_b128 v[142:145], v142 offset:2048
	ds_read_b128 v[146:149], v150 offset:12288
	ds_read_b128 v[150:153], v150 offset:14336
	s_mul_i32 vcc_lo, s70, 0x12000
	s_add_i32 s10, s20, s23
	v_lshl_add_u64 v[222:223], v[192:193], 0, vcc
	s_mov_b32 m0, s10
	s_mul_i32 s100, s70, 0x1600
	v_lshl_add_u64 v[224:225], v[194:195], 0, s[100:101]
	s_add_i32 s10, s19, s23
	s_waitcnt lgkmcnt(6)
	v_mfma_f32_32x32x16_bf16 v[66:81], v[182:185], v[154:157], v[66:81]
	global_load_lds_dwordx4 v[222:223], off
	v_mfma_f32_32x32x16_bf16 v[82:97], v[178:181], v[154:157], v[82:97]
	global_load_lds_dwordx4 v[222:223], off offset:1024
	s_add_i32 m0, s10, 0x2000
	v_mfma_f32_32x32x16_bf16 v[18:33], v[182:185], v[158:161], v[18:33]
	global_load_lds_dwordx4 v[224:225], off
	v_mfma_f32_32x32x16_bf16 v[2:17], v[178:181], v[158:161], v[2:17]
	global_load_lds_dwordx4 v[224:225], off offset:1024
	v_mfma_f32_32x32x16_bf16 v[114:129], v[174:177], v[154:157], v[114:129]
	global_load_lds_dwordx4 v[224:225], off offset:2048
	v_mfma_f32_32x32x16_bf16 v[98:113], v[170:173], v[154:157], v[98:113]
	global_load_lds_dwordx4 v[224:225], off offset:3072
	v_mfma_f32_32x32x16_bf16 v[50:65], v[174:177], v[158:161], v[50:65]
	s_add_i32 s10, s28, 0x6000
	s_cmpk_lg_u32 s28, 0xc000
	s_cselect_b32 s28, s10, 0
	s_add_i32 s10, s23, 0x6000
	s_cmpk_lg_u32 s23, 0xc000
	s_cselect_b32 s23, s10, 0
	v_mfma_f32_32x32x16_bf16 v[34:49], v[170:173], v[158:161], v[34:49]
	s_add_i32 s11, s28, 16
	s_waitcnt vmcnt(6) lgkmcnt(0)
	s_barrier
; #define GAS __attribute__((address_space(1)))
; DI unsigned pk2(float a, float b) { f32x2 v = {a, b}; bf2_t r = __builtin_convertvector(v, bf2_t); return __builtin_bit_cast(unsigned, r); }
;     ...
;   asm volatile("s_waitcnt vmcnt(0)" ::: "memory");
;   __builtin_amdgcn_s_barrier();
;   asm volatile("" ::: "memory");
;     ...
;   {
;     const int h = lane >> 5, cl = lane & 31;
; #pragma unroll
;     for (int i = 0; i < 2; ++i)
; #pragma unroll
;       for (int j = 0; j < 4; ++j)
; #pragma unroll
;         for (int g = 0; g < 4; ++g) {
;           u32x2 w; w.x = pk2(acc[i][j][4 * g], acc[i][j][4 * g + 1]); w.y = pk2(acc[i][j][4 * g + 2], acc[i][j][4 * g + 3]);
;           *(u32x2*)(smem + (wr * 64 + i * 32 + cl) * 528 + (wc * 128 + j * 32 + 8 * g + 4 * h) * 2) = w;
;         }
;   }
;   __syncthreads();
;     ...
;     const int L = (mt < 512) ? 2048 : 256;
;     const bool first = (m0 % L) == 0, last = ((m0 + 128) % L) == 0;
;     const float* cw = ea.cw; const float* cb = ea.cb;
; #pragma unroll 1
;     for (int p = 0; p < 2; ++p) {
;       const int j8 = (tid2 & 7) * 8;
;       const int ja0 = (nt * 2 + p) * 64, ja = ja0 + j8;
;       f32x4 wa[4][2], wg[4][2];
; #pragma unroll
;       for (int hh = 0; hh < 2; ++hh) {
;         wa[0][hh] = *(const GAS f32x4*)(cw + ja + 4 * hh); wa[1][hh] = *(const GAS f32x4*)(cw + 5632 + ja + 4 * hh); wa[2][hh] = *(const GAS f32x4*)(cw + 11264 + ja + 4 * hh); wa[3][hh] = *(const GAS f32x4*)(cb + ja + 4 * hh);
;         wg[0][hh] = *(const GAS f32x4*)(cw + 2816 + ja + 4 * hh); wg[1][hh] = *(const GAS f32x4*)(cw + 5632 + 2816 + ja + 4 * hh); wg[2][hh] = *(const GAS f32x4*)(cw + 11264 + 2816 + ja + 4 * hh); wg[3][hh] = *(const GAS f32x4*)(cb + 2816 + ja + 4 * hh);
;       }
; #pragma unroll 1
;       for (int i = 0; i < 4; ++i) {
;         const int r = (tid2 + 256 * i) >> 3;
;         const bool top = (r == 0), bot = (r == 127);
;         if ((top && !first) || (bot && !last)) continue;
;         const char* base = smem + r * 528 + (p * 128 + j8) * 2;
	v_add_u32_e32 v158, s11, v218
	v_add_u32_e32 v170, s11, v0
	v_add_u32_e32 v158, v158, v219
	v_add_u32_e32 v170, v170, v219
	ds_read_b128 v[154:157], v158
	ds_read_b128 v[182:185], v170 offset:8192
	ds_read_b128 v[178:181], v170 offset:10240
	ds_read_b128 v[158:161], v158 offset:2048
	ds_read_b128 v[174:177], v170 offset:12288
	ds_read_b128 v[170:173], v170 offset:14336
	v_mfma_f32_32x32x16_bf16 v[66:81], v[162:165], v[138:141], v[66:81]
	v_mfma_f32_32x32x16_bf16 v[82:97], v[166:169], v[138:141], v[82:97]
	v_mfma_f32_32x32x16_bf16 v[18:33], v[162:165], v[142:145], v[18:33]
	v_mfma_f32_32x32x16_bf16 v[2:17], v[166:169], v[142:145], v[2:17]
	v_mfma_f32_32x32x16_bf16 v[114:129], v[146:149], v[138:141], v[114:129]
	v_mfma_f32_32x32x16_bf16 v[98:113], v[150:153], v[138:141], v[98:113]
	v_mfma_f32_32x32x16_bf16 v[50:65], v[146:149], v[142:145], v[50:65]
	v_mfma_f32_32x32x16_bf16 v[34:49], v[150:153], v[142:145], v[34:49]
	s_add_i32 s21, s21, 2
	s_cmp_eq_u32 s21, 32
	s_cbranch_scc0 .LBB0_272
	s_waitcnt lgkmcnt(0)
	s_setprio 0
	v_mul_lo_u32 v0, v197, s55
	v_add_u32_e32 v0, 16, v0
	s_nop 1
	v_cvt_pk_bf16_f32 v66, v66, v67
	v_cvt_pk_bf16_f32 v67, v68, v69
	v_lshlrev_b32_e32 v68, 3, v196
	s_lshl_b32 s10, s18, 1
	v_add3_u32 v0, v0, v68, s10
	v_cvt_pk_bf16_f32 v68, v70, v71
	v_cvt_pk_bf16_f32 v69, v72, v73
	s_waitcnt vmcnt(0)
	s_barrier
	ds_write2_b64 v0, v[66:67], v[68:69] offset1:2
	v_cvt_pk_bf16_f32 v66, v74, v75
	v_cvt_pk_bf16_f32 v67, v76, v77
	v_cvt_pk_bf16_f32 v68, v78, v79
	v_cvt_pk_bf16_f32 v69, v80, v81
	ds_write2_b64 v0, v[66:67], v[68:69] offset0:4 offset1:6
	v_cvt_pk_bf16_f32 v66, v82, v83
	v_cvt_pk_bf16_f32 v67, v84, v85
	v_cvt_pk_bf16_f32 v68, v86, v87
	v_cvt_pk_bf16_f32 v69, v88, v89
	ds_write2_b64 v0, v[66:67], v[68:69] offset0:8 offset1:10
	v_cvt_pk_bf16_f32 v66, v90, v91
	v_cvt_pk_bf16_f32 v67, v92, v93
	v_cvt_pk_bf16_f32 v68, v94, v95
	v_cvt_pk_bf16_f32 v69, v96, v97
	ds_write2_b64 v0, v[66:67], v[68:69] offset0:12 offset1:14
	v_cvt_pk_bf16_f32 v66, v114, v115
	v_cvt_pk_bf16_f32 v67, v116, v117
	v_cvt_pk_bf16_f32 v68, v118, v119
	v_cvt_pk_bf16_f32 v69, v120, v121
	ds_write2_b64 v0, v[66:67], v[68:69] offset0:16 offset1:18
	v_cvt_pk_bf16_f32 v66, v122, v123
	v_cvt_pk_bf16_f32 v67, v124, v125
	v_cvt_pk_bf16_f32 v68, v126, v127
	v_cvt_pk_bf16_f32 v69, v128, v129
	ds_write2_b64 v0, v[66:67], v[68:69] offset0:20 offset1:22
	v_cvt_pk_bf16_f32 v66, v98, v99
	v_cvt_pk_bf16_f32 v67, v100, v101
	v_cvt_pk_bf16_f32 v68, v102, v103
	v_cvt_pk_bf16_f32 v69, v104, v105
	ds_write2_b64 v0, v[66:67], v[68:69] offset0:24 offset1:26
	v_cvt_pk_bf16_f32 v66, v106, v107
	v_cvt_pk_bf16_f32 v67, v108, v109
	v_cvt_pk_bf16_f32 v68, v110, v111
	v_cvt_pk_bf16_f32 v69, v112, v113
	ds_write2_b64 v0, v[66:67], v[68:69] offset0:28 offset1:30
	v_add_u32_e32 v0, 0x4000, v0
	v_cvt_pk_bf16_f32 v2, v2, v3
	v_cvt_pk_bf16_f32 v3, v4, v5
	v_cvt_pk_bf16_f32 v4, v6, v7
	v_cvt_pk_bf16_f32 v5, v8, v9
	ds_write2_b64 v0, v[2:3], v[4:5] offset0:72 offset1:74
	v_cvt_pk_bf16_f32 v2, v10, v11
	v_cvt_pk_bf16_f32 v3, v12, v13
	v_cvt_pk_bf16_f32 v4, v14, v15
	v_cvt_pk_bf16_f32 v5, v16, v17
	ds_write2_b64 v0, v[2:3], v[4:5] offset0:76 offset1:78
	v_cvt_pk_bf16_f32 v2, v50, v51
	v_cvt_pk_bf16_f32 v3, v52, v53
	v_cvt_pk_bf16_f32 v4, v54, v55
	v_cvt_pk_bf16_f32 v5, v56, v57
	s_cmpk_lt_i32 s15, 0x200
	ds_write2_b64 v0, v[2:3], v[4:5] offset0:80 offset1:82
	v_cvt_pk_bf16_f32 v2, v58, v59
	v_cvt_pk_bf16_f32 v3, v60, v61
	v_cvt_pk_bf16_f32 v4, v62, v63
	v_cvt_pk_bf16_f32 v5, v64, v65
	s_cselect_b32 s10, 0x7ff, s78
	v_cvt_pk_bf16_f32 v18, v18, v19
	v_cvt_pk_bf16_f32 v19, v20, v21
	v_cvt_pk_bf16_f32 v20, v22, v23
	v_cvt_pk_bf16_f32 v21, v24, v25
	ds_write2_b64 v0, v[2:3], v[4:5] offset0:84 offset1:86
	v_cvt_pk_bf16_f32 v2, v34, v35
	v_cvt_pk_bf16_f32 v3, v36, v37
	v_cvt_pk_bf16_f32 v4, v38, v39
	v_cvt_pk_bf16_f32 v5, v40, v41
	s_and_b32 s11, s10, s46
	ds_write2_b64 v0, v[18:19], v[20:21] offset0:64 offset1:66
	v_cvt_pk_bf16_f32 v18, v26, v27
	v_cvt_pk_bf16_f32 v19, v28, v29
	v_cvt_pk_bf16_f32 v20, v30, v31
	v_cvt_pk_bf16_f32 v21, v32, v33
	ds_write2_b64 v0, v[2:3], v[4:5] offset0:88 offset1:90
	v_cvt_pk_bf16_f32 v2, v42, v43
	v_cvt_pk_bf16_f32 v3, v44, v45
	v_cvt_pk_bf16_f32 v4, v46, v47
	v_cvt_pk_bf16_f32 v5, v48, v49
	s_cmp_eq_u32 s11, 0
	ds_write2_b64 v0, v[18:19], v[20:21] offset0:68 offset1:70
	ds_write2_b64 v0, v[2:3], v[4:5] offset0:92 offset1:94
	s_waitcnt vmcnt(0) lgkmcnt(0)
	s_barrier
	s_cselect_b64 s[18:19], -1, 0
	s_add_i32 s11, s46, 0x80
	v_lshlrev_b32_e32 v0, 3, v189
	s_and_b32 s10, s11, s10
	v_and_b32_e32 v96, 56, v0
	s_cmp_eq_u32 s10, 0
	v_lshlrev_b32_e32 v0, 1, v96
	s_mov_b32 s40, 0
	s_cselect_b64 s[20:21], -1, 0
	s_lshl_b32 s47, s22, 7
	v_add_u32_e32 v97, 16, v0
	v_lshl_add_u64 v[90:91], s[44:45], 0, v[0:1]
	s_mov_b64 s[28:29], -1
	s_branch .LBB0_275
